# v11 + the 48 back-to-back 's_setprio 0 / s_setprio 1' pairs between the two MFMA blocks of each super-phase removed (priority stays 1 across both blocks)
# baseline (speedup 1.0000x reference)
; #define PG8_STAGE(bufoff, gbase, voff) do { _Pragma("unroll") for (int _i = 0; _i < 2; ++_i) \
;         __builtin_amdgcn_global_load_lds((const unsigned*)((const char*)(gbase) + (voff)[_i]), (PG8_LAS unsigned*)(lds + (bufoff) + ldsw + _i * 8192), 16, 0, 0); } while (0)
; #define PG8_WAIT_V(n) asm volatile("s_waitcnt vmcnt(" #n ")" ::: "memory")
; #define PG8_WAIT_L(n) asm volatile("s_waitcnt lgkmcnt(" #n ")" ::: "memory")
; #define PG8_BAR __builtin_amdgcn_s_barrier()
; #define PG8_SCHED __builtin_amdgcn_sched_barrier(0)
; template <class Epi, class Sched, bool ALIGN_EPI = true, bool SP2 = true>
; __device__ __forceinline__ void gemm_phase(PG8_LAS unsigned char* lds, const int K  , const Sched& S, const Epi& E) {
;     ...
;             PG8_LDB(B0, 0, 0); PG8_LDB(B1, 0, 1); PG8_SCHED; PG8_LDA(At, 0, 0); PG8_STAGE(PG8_SA(1, 1), a1 + hstep, voffA);
;             PG8_WAIT_V(8); PG8_WAIT_L(0); PG8_BAR; PG8_MMA(0, 0, At, B0); PG8_MMA(0, 1, At, B1); PG8_BAR; PG8_SCHED;
;             PG8_LDA(At, 0, 1); PG8_STAGE(PG8_SB(0, 0), b2, voffB); PG8_STAGE(PG8_SB(0, 1), b2 + hstep, voffB); PG8_STAGE(PG8_SA(0, 0), a2, voffA);
;             PG8_WAIT_V(8); PG8_WAIT_L(0); PG8_BAR; PG8_MMA(1, 0, At, B0); PG8_MMA(1, 1, At, B1); PG8_BAR; PG8_SCHED;
.LBB0_219:
	ds_read_b128 v[148:151], v154
	ds_read_b128 v[160:163], v154 offset:1024
	ds_read_b128 v[164:167], v154 offset:2048
	ds_read_b128 v[168:171], v154 offset:3072
	ds_read_b128 v[172:175], v155
	ds_read_b128 v[176:179], v155 offset:1024
	ds_read_b128 v[180:183], v155 offset:2048
	ds_read_b128 v[184:187], v155 offset:3072
	s_add_u32 s22, s20, 0xfff80080
	s_addc_u32 s23, s21, -1
	s_cmp_eq_u32 s48, 28
	s_cselect_b32 s25, s13, s23
	s_cselect_b32 s24, s44, s22
	s_cselect_b32 s23, s11, s47
	s_cselect_b32 s22, s45, s46
	v_lshl_add_u64 v[220:221], s[20:21], 0, v[140:141]
	s_add_i32 m0, s19, 0xc000
	ds_read_b128 v[188:191], v156
	ds_read_b128 v[192:195], v156 offset:1024
	ds_read_b128 v[196:199], v156 offset:2048
	ds_read_b128 v[200:203], v156 offset:3072
	ds_read_b128 v[204:207], v156 offset:4096
	ds_read_b128 v[208:211], v156 offset:5120
	ds_read_b128 v[212:215], v156 offset:6144
	ds_read_b128 v[216:219], v156 offset:7168
	global_load_lds_dwordx4 v[220:221], off
	v_lshl_add_u64 v[220:221], s[20:21], 0, v[142:143]
	s_add_i32 m0, s19, 0xe000
	s_nop 0
	global_load_lds_dwordx4 v[220:221], off
	s_waitcnt vmcnt(8)
	s_waitcnt lgkmcnt(0)
	s_barrier
	s_setprio 1
	s_waitcnt lgkmcnt(0)
	v_mfma_f32_16x16x32_bf16 v[126:129], v[148:151], v[188:191], v[126:129]
	v_mfma_f32_16x16x32_bf16 v[118:121], v[164:167], v[188:191], v[118:121]
	v_mfma_f32_16x16x32_bf16 v[110:113], v[148:151], v[196:199], v[110:113]
	v_mfma_f32_16x16x32_bf16 v[102:105], v[164:167], v[196:199], v[102:105]
	v_mfma_f32_16x16x32_bf16 v[94:97], v[148:151], v[204:207], v[94:97]
	v_mfma_f32_16x16x32_bf16 v[86:89], v[164:167], v[204:207], v[86:89]
	v_mfma_f32_16x16x32_bf16 v[78:81], v[148:151], v[212:215], v[78:81]
	v_mfma_f32_16x16x32_bf16 v[70:73], v[164:167], v[212:215], v[70:73]
	v_mfma_f32_16x16x32_bf16 v[126:129], v[160:163], v[192:195], v[126:129]
	v_mfma_f32_16x16x32_bf16 v[118:121], v[168:171], v[192:195], v[118:121]
	v_mfma_f32_16x16x32_bf16 v[110:113], v[160:163], v[200:203], v[110:113]
	v_mfma_f32_16x16x32_bf16 v[102:105], v[168:171], v[200:203], v[102:105]
	v_mfma_f32_16x16x32_bf16 v[94:97], v[160:163], v[208:211], v[94:97]
	v_mfma_f32_16x16x32_bf16 v[86:89], v[168:171], v[208:211], v[86:89]
	v_mfma_f32_16x16x32_bf16 v[78:81], v[160:163], v[216:219], v[78:81]
	v_mfma_f32_16x16x32_bf16 v[70:73], v[168:171], v[216:219], v[70:73]
	v_mfma_f32_16x16x32_bf16 v[122:125], v[172:175], v[188:191], v[122:125]
	v_mfma_f32_16x16x32_bf16 v[114:117], v[180:183], v[188:191], v[114:117]
	v_mfma_f32_16x16x32_bf16 v[106:109], v[172:175], v[196:199], v[106:109]
	v_mfma_f32_16x16x32_bf16 v[98:101], v[180:183], v[196:199], v[98:101]
	v_mfma_f32_16x16x32_bf16 v[90:93], v[172:175], v[204:207], v[90:93]
	v_mfma_f32_16x16x32_bf16 v[82:85], v[180:183], v[204:207], v[82:85]
	v_mfma_f32_16x16x32_bf16 v[74:77], v[172:175], v[212:215], v[74:77]
	v_mfma_f32_16x16x32_bf16 v[66:69], v[180:183], v[212:215], v[66:69]
	v_mfma_f32_16x16x32_bf16 v[122:125], v[176:179], v[192:195], v[122:125]
	v_mfma_f32_16x16x32_bf16 v[114:117], v[184:187], v[192:195], v[114:117]
	v_mfma_f32_16x16x32_bf16 v[106:109], v[176:179], v[200:203], v[106:109]
	v_mfma_f32_16x16x32_bf16 v[98:101], v[184:187], v[200:203], v[98:101]
	v_mfma_f32_16x16x32_bf16 v[90:93], v[176:179], v[208:211], v[90:93]
	v_mfma_f32_16x16x32_bf16 v[82:85], v[184:187], v[208:211], v[82:85]
	v_mfma_f32_16x16x32_bf16 v[74:77], v[176:179], v[216:219], v[74:77]
	v_mfma_f32_16x16x32_bf16 v[66:69], v[184:187], v[216:219], v[66:69]
	s_setprio 0
	s_barrier
	s_add_i32 s49, s39, s29
	v_lshl_add_u64 v[220:221], s[22:23], 0, v[136:137]
	s_mov_b32 m0, s49
	ds_read_b128 v[188:191], v156 offset:16384
	ds_read_b128 v[192:195], v156 offset:17408
	ds_read_b128 v[196:199], v156 offset:18432
	ds_read_b128 v[200:203], v156 offset:19456
	ds_read_b128 v[204:207], v156 offset:20480
	ds_read_b128 v[208:211], v156 offset:21504
	ds_read_b128 v[212:215], v156 offset:22528
	ds_read_b128 v[216:219], v156 offset:23552
	global_load_lds_dwordx4 v[220:221], off
	s_add_i32 m0, s49, 0x2000
	s_add_u32 s50, s22, 0x80000
	v_lshl_add_u64 v[222:223], s[22:23], 0, v[132:133]
	s_addc_u32 s51, s23, 0
	s_add_i32 s49, s40, s29
	global_load_lds_dwordx4 v[222:223], off
	v_lshl_add_u64 v[224:225], s[50:51], 0, v[136:137]
	s_mov_b32 m0, s49
	v_lshl_add_u64 v[226:227], s[24:25], 0, v[134:135]
	global_load_lds_dwordx4 v[224:225], off
	v_lshl_add_u64 v[224:225], s[50:51], 0, v[132:133]
	s_add_i32 m0, s49, 0x2000
	s_nop 0
	global_load_lds_dwordx4 v[224:225], off
	v_lshl_add_u64 v[224:225], s[24:25], 0, v[138:139]
	s_mov_b32 m0, s19
	s_nop 0
	global_load_lds_dwordx4 v[224:225], off
	s_mov_b32 m0, s31
	s_nop 0
	global_load_lds_dwordx4 v[226:227], off
	s_waitcnt vmcnt(8)
	s_waitcnt lgkmcnt(0)
	s_barrier
; #define PG8_STAGE(bufoff, gbase, voff) do { _Pragma("unroll") for (int _i = 0; _i < 2; ++_i) \
;         __builtin_amdgcn_global_load_lds((const unsigned*)((const char*)(gbase) + (voff)[_i]), (PG8_LAS unsigned*)(lds + (bufoff) + ldsw + _i * 8192), 16, 0, 0); } while (0)
; #define PG8_WAIT_V(n) asm volatile("s_waitcnt vmcnt(" #n ")" ::: "memory")
; #define PG8_WAIT_L(n) asm volatile("s_waitcnt lgkmcnt(" #n ")" ::: "memory")
; #define PG8_BAR __builtin_amdgcn_s_barrier()
; #define PG8_SCHED __builtin_amdgcn_sched_barrier(0)
; template <class Epi, class Sched, bool ALIGN_EPI = true, bool SP2 = true>
; __device__ __forceinline__ void gemm_phase(PG8_LAS unsigned char* lds, const int K  , const Sched& S, const Epi& E) {
;     ...
;             PG8_WAIT_V(8); PG8_WAIT_L(0); PG8_BAR; PG8_MMA(1, 0, At, B0); PG8_MMA(1, 1, At, B1); PG8_BAR; PG8_SCHED;
;             PG8_LDB(B0, 1, 0); PG8_LDB(B1, 1, 1); PG8_SCHED; PG8_LDA(At, 1, 0); PG8_STAGE(PG8_SA(0, 1), a2 + hstep, voffA);
;             PG8_WAIT_V(8); PG8_WAIT_L(0); PG8_BAR; PG8_MMA(0, 0, At, B0); PG8_MMA(0, 1, At, B1); PG8_BAR; PG8_SCHED;
	s_setprio 1
	s_waitcnt lgkmcnt(0)
	v_mfma_f32_16x16x32_bf16 v[62:65], v[148:151], v[188:191], v[62:65]
	v_mfma_f32_16x16x32_bf16 v[54:57], v[164:167], v[188:191], v[54:57]
	v_mfma_f32_16x16x32_bf16 v[46:49], v[148:151], v[196:199], v[46:49]
	v_mfma_f32_16x16x32_bf16 v[38:41], v[164:167], v[196:199], v[38:41]
	v_mfma_f32_16x16x32_bf16 v[30:33], v[148:151], v[204:207], v[30:33]
	v_mfma_f32_16x16x32_bf16 v[22:25], v[164:167], v[204:207], v[22:25]
	v_mfma_f32_16x16x32_bf16 v[14:17], v[148:151], v[212:215], v[14:17]
	v_mfma_f32_16x16x32_bf16 v[6:9], v[164:167], v[212:215], v[6:9]
	v_mfma_f32_16x16x32_bf16 v[62:65], v[160:163], v[192:195], v[62:65]
	v_mfma_f32_16x16x32_bf16 v[54:57], v[168:171], v[192:195], v[54:57]
	v_mfma_f32_16x16x32_bf16 v[46:49], v[160:163], v[200:203], v[46:49]
	v_mfma_f32_16x16x32_bf16 v[38:41], v[168:171], v[200:203], v[38:41]
	v_mfma_f32_16x16x32_bf16 v[30:33], v[160:163], v[208:211], v[30:33]
	v_mfma_f32_16x16x32_bf16 v[22:25], v[168:171], v[208:211], v[22:25]
	v_mfma_f32_16x16x32_bf16 v[14:17], v[160:163], v[216:219], v[14:17]
	v_mfma_f32_16x16x32_bf16 v[6:9], v[168:171], v[216:219], v[6:9]
	v_mfma_f32_16x16x32_bf16 v[58:61], v[172:175], v[188:191], v[58:61]
	v_mfma_f32_16x16x32_bf16 v[50:53], v[180:183], v[188:191], v[50:53]
	v_mfma_f32_16x16x32_bf16 v[42:45], v[172:175], v[196:199], v[42:45]
	v_mfma_f32_16x16x32_bf16 v[34:37], v[180:183], v[196:199], v[34:37]
	v_mfma_f32_16x16x32_bf16 v[26:29], v[172:175], v[204:207], v[26:29]
	v_mfma_f32_16x16x32_bf16 v[18:21], v[180:183], v[204:207], v[18:21]
	v_mfma_f32_16x16x32_bf16 v[10:13], v[172:175], v[212:215], v[10:13]
	v_mfma_f32_16x16x32_bf16 v[2:5], v[180:183], v[212:215], v[2:5]
	v_mfma_f32_16x16x32_bf16 v[58:61], v[176:179], v[192:195], v[58:61]
	v_mfma_f32_16x16x32_bf16 v[50:53], v[184:187], v[192:195], v[50:53]
	v_mfma_f32_16x16x32_bf16 v[42:45], v[176:179], v[200:203], v[42:45]
	v_mfma_f32_16x16x32_bf16 v[34:37], v[184:187], v[200:203], v[34:37]
	v_mfma_f32_16x16x32_bf16 v[26:29], v[176:179], v[208:211], v[26:29]
	v_mfma_f32_16x16x32_bf16 v[18:21], v[184:187], v[208:211], v[18:21]
	v_mfma_f32_16x16x32_bf16 v[10:13], v[176:179], v[216:219], v[10:13]
	v_mfma_f32_16x16x32_bf16 v[2:5], v[184:187], v[216:219], v[2:5]
	s_setprio 0
	s_barrier
	s_add_i32 s49, 0, 0x18000
	v_add_u32_e32 v159, s49, v152
	s_add_i32 s50, 0, 0x1c000
	ds_read_b128 v[148:151], v159
	ds_read_b128 v[160:163], v159 offset:1024
	ds_read_b128 v[164:167], v159 offset:2048
	ds_read_b128 v[168:171], v159 offset:3072
	v_add_u32_e32 v159, s50, v152
	ds_read_b128 v[172:175], v159
	ds_read_b128 v[176:179], v159 offset:1024
	ds_read_b128 v[180:183], v159 offset:2048
	ds_read_b128 v[184:187], v159 offset:3072
	s_add_u32 s24, s24, 0x80000
	s_addc_u32 s25, s25, 0
	s_mov_b32 m0, s33
	v_lshl_add_u64 v[230:231], s[24:25], 0, v[138:139]
	ds_read_b128 v[188:191], v156 offset:32768
	ds_read_b128 v[192:195], v156 offset:33792
	ds_read_b128 v[196:199], v156 offset:34816
	ds_read_b128 v[200:203], v156 offset:35840
	ds_read_b128 v[204:207], v156 offset:36864
	ds_read_b128 v[208:211], v156 offset:37888
	ds_read_b128 v[212:215], v156 offset:38912
	ds_read_b128 v[216:219], v156 offset:39936
	global_load_lds_dwordx4 v[230:231], off
	v_lshl_add_u64 v[230:231], s[24:25], 0, v[134:135]
	s_mov_b32 m0, s34
	s_nop 0
	global_load_lds_dwordx4 v[230:231], off
	s_waitcnt vmcnt(8)
	s_waitcnt lgkmcnt(0)
	s_barrier
	s_setprio 1
	s_waitcnt lgkmcnt(0)
	v_mfma_f32_16x16x32_bf16 v[126:129], v[148:151], v[188:191], v[126:129]
	v_mfma_f32_16x16x32_bf16 v[118:121], v[164:167], v[188:191], v[118:121]
	v_mfma_f32_16x16x32_bf16 v[110:113], v[148:151], v[196:199], v[110:113]
	v_mfma_f32_16x16x32_bf16 v[102:105], v[164:167], v[196:199], v[102:105]
	v_mfma_f32_16x16x32_bf16 v[94:97], v[148:151], v[204:207], v[94:97]
	v_mfma_f32_16x16x32_bf16 v[86:89], v[164:167], v[204:207], v[86:89]
	v_mfma_f32_16x16x32_bf16 v[78:81], v[148:151], v[212:215], v[78:81]
	v_mfma_f32_16x16x32_bf16 v[70:73], v[164:167], v[212:215], v[70:73]
	v_mfma_f32_16x16x32_bf16 v[126:129], v[160:163], v[192:195], v[126:129]
	v_mfma_f32_16x16x32_bf16 v[118:121], v[168:171], v[192:195], v[118:121]
	v_mfma_f32_16x16x32_bf16 v[110:113], v[160:163], v[200:203], v[110:113]
	v_mfma_f32_16x16x32_bf16 v[102:105], v[168:171], v[200:203], v[102:105]
	v_mfma_f32_16x16x32_bf16 v[94:97], v[160:163], v[208:211], v[94:97]
	v_mfma_f32_16x16x32_bf16 v[86:89], v[168:171], v[208:211], v[86:89]
	v_mfma_f32_16x16x32_bf16 v[78:81], v[160:163], v[216:219], v[78:81]
	v_mfma_f32_16x16x32_bf16 v[70:73], v[168:171], v[216:219], v[70:73]
	v_mfma_f32_16x16x32_bf16 v[122:125], v[172:175], v[188:191], v[122:125]
	v_mfma_f32_16x16x32_bf16 v[114:117], v[180:183], v[188:191], v[114:117]
	v_mfma_f32_16x16x32_bf16 v[106:109], v[172:175], v[196:199], v[106:109]
	v_mfma_f32_16x16x32_bf16 v[98:101], v[180:183], v[196:199], v[98:101]
	v_mfma_f32_16x16x32_bf16 v[90:93], v[172:175], v[204:207], v[90:93]
	v_mfma_f32_16x16x32_bf16 v[82:85], v[180:183], v[204:207], v[82:85]
	v_mfma_f32_16x16x32_bf16 v[74:77], v[172:175], v[212:215], v[74:77]
	v_mfma_f32_16x16x32_bf16 v[66:69], v[180:183], v[212:215], v[66:69]
	v_mfma_f32_16x16x32_bf16 v[122:125], v[176:179], v[192:195], v[122:125]
	v_mfma_f32_16x16x32_bf16 v[114:117], v[184:187], v[192:195], v[114:117]
	v_mfma_f32_16x16x32_bf16 v[106:109], v[176:179], v[200:203], v[106:109]
	v_mfma_f32_16x16x32_bf16 v[98:101], v[184:187], v[200:203], v[98:101]
	v_mfma_f32_16x16x32_bf16 v[90:93], v[176:179], v[208:211], v[90:93]
	v_mfma_f32_16x16x32_bf16 v[82:85], v[184:187], v[208:211], v[82:85]
	v_mfma_f32_16x16x32_bf16 v[74:77], v[176:179], v[216:219], v[74:77]
	v_mfma_f32_16x16x32_bf16 v[66:69], v[184:187], v[216:219], v[66:69]
	s_setprio 0
	s_barrier
; #define PG8_STAGE(bufoff, gbase, voff) do { _Pragma("unroll") for (int _i = 0; _i < 2; ++_i) \
;         __builtin_amdgcn_global_load_lds((const unsigned*)((const char*)(gbase) + (voff)[_i]), (PG8_LAS unsigned*)(lds + (bufoff) + ldsw + _i * 8192), 16, 0, 0); } while (0)
; #define PG8_WAIT_V(n) asm volatile("s_waitcnt vmcnt(" #n ")" ::: "memory")
; #define PG8_WAIT_L(n) asm volatile("s_waitcnt lgkmcnt(" #n ")" ::: "memory")
; #define PG8_BAR __builtin_amdgcn_s_barrier()
; #define PG8_SCHED __builtin_amdgcn_sched_barrier(0)
; template <class Epi, class Sched, bool ALIGN_EPI = true, bool SP2 = true>
; __device__ __forceinline__ void gemm_phase(PG8_LAS unsigned char* lds, const int K  , const Sched& S, const Epi& E) {
;     ...
;             PG8_WAIT_V(8); PG8_WAIT_L(0); PG8_BAR; PG8_MMA(0, 0, At, B0); PG8_MMA(0, 1, At, B1); PG8_BAR; PG8_SCHED;
;             PG8_LDA(At, 1, 1); PG8_STAGE(PG8_SB(1, 0), b3, voffB); PG8_STAGE(PG8_SB(1, 1), b3 + hstep, voffB); PG8_STAGE(PG8_SA(1, 0), a3, voffA);
;             PG8_WAIT_V(8); PG8_WAIT_L(0); PG8_BAR; PG8_MMA(1, 0, At, B0); PG8_MMA(1, 1, At, B1); PG8_BAR; PG8_SCHED;
	s_add_i32 s24, s49, s29
	v_lshl_add_u64 v[220:221], v[220:221], 0, s[6:7]
	s_mov_b32 m0, s24
	ds_read_b128 v[188:191], v156 offset:49152
	ds_read_b128 v[192:195], v156 offset:50176
	ds_read_b128 v[196:199], v156 offset:51200
	ds_read_b128 v[200:203], v156 offset:52224
	ds_read_b128 v[204:207], v156 offset:53248
	ds_read_b128 v[208:211], v156 offset:54272
	ds_read_b128 v[212:215], v156 offset:55296
	ds_read_b128 v[216:219], v156 offset:56320
	global_load_lds_dwordx4 v[220:221], off
	s_add_i32 m0, s24, 0x2000
	s_add_u32 s22, s22, 0x80080
	v_lshl_add_u64 v[220:221], v[222:223], 0, s[6:7]
	s_addc_u32 s23, s23, 0
	s_add_i32 s24, s50, s29
	global_load_lds_dwordx4 v[220:221], off
	v_lshl_add_u64 v[220:221], s[22:23], 0, v[136:137]
	s_mov_b32 m0, s24
	s_nop 0
	global_load_lds_dwordx4 v[220:221], off
	v_lshl_add_u64 v[220:221], s[22:23], 0, v[132:133]
	s_add_i32 m0, s24, 0x2000
	s_nop 0
	global_load_lds_dwordx4 v[220:221], off
	v_lshl_add_u64 v[220:221], v[224:225], 0, s[6:7]
	s_mov_b32 m0, s36
	s_nop 0
	global_load_lds_dwordx4 v[220:221], off
	v_lshl_add_u64 v[220:221], v[226:227], 0, s[6:7]
	s_mov_b32 m0, s37
	s_nop 0
	global_load_lds_dwordx4 v[220:221], off
	s_waitcnt vmcnt(8)
	s_waitcnt lgkmcnt(0)
	s_barrier
	s_setprio 1
	s_waitcnt lgkmcnt(0)
	v_mfma_f32_16x16x32_bf16 v[62:65], v[148:151], v[188:191], v[62:65]
	v_mfma_f32_16x16x32_bf16 v[54:57], v[164:167], v[188:191], v[54:57]
	v_mfma_f32_16x16x32_bf16 v[46:49], v[148:151], v[196:199], v[46:49]
	v_mfma_f32_16x16x32_bf16 v[38:41], v[164:167], v[196:199], v[38:41]
	v_mfma_f32_16x16x32_bf16 v[30:33], v[148:151], v[204:207], v[30:33]
	v_mfma_f32_16x16x32_bf16 v[22:25], v[164:167], v[204:207], v[22:25]
	v_mfma_f32_16x16x32_bf16 v[14:17], v[148:151], v[212:215], v[14:17]
	v_mfma_f32_16x16x32_bf16 v[6:9], v[164:167], v[212:215], v[6:9]
	v_mfma_f32_16x16x32_bf16 v[62:65], v[160:163], v[192:195], v[62:65]
	v_mfma_f32_16x16x32_bf16 v[54:57], v[168:171], v[192:195], v[54:57]
	v_mfma_f32_16x16x32_bf16 v[46:49], v[160:163], v[200:203], v[46:49]
	v_mfma_f32_16x16x32_bf16 v[38:41], v[168:171], v[200:203], v[38:41]
	v_mfma_f32_16x16x32_bf16 v[30:33], v[160:163], v[208:211], v[30:33]
	v_mfma_f32_16x16x32_bf16 v[22:25], v[168:171], v[208:211], v[22:25]
	v_mfma_f32_16x16x32_bf16 v[14:17], v[160:163], v[216:219], v[14:17]
	v_mfma_f32_16x16x32_bf16 v[6:9], v[168:171], v[216:219], v[6:9]
	v_mfma_f32_16x16x32_bf16 v[58:61], v[172:175], v[188:191], v[58:61]
	v_mfma_f32_16x16x32_bf16 v[50:53], v[180:183], v[188:191], v[50:53]
	v_mfma_f32_16x16x32_bf16 v[42:45], v[172:175], v[196:199], v[42:45]
	v_mfma_f32_16x16x32_bf16 v[34:37], v[180:183], v[196:199], v[34:37]
	v_mfma_f32_16x16x32_bf16 v[26:29], v[172:175], v[204:207], v[26:29]
	v_mfma_f32_16x16x32_bf16 v[18:21], v[180:183], v[204:207], v[18:21]
	v_mfma_f32_16x16x32_bf16 v[10:13], v[172:175], v[212:215], v[10:13]
	v_mfma_f32_16x16x32_bf16 v[2:5], v[180:183], v[212:215], v[2:5]
	v_mfma_f32_16x16x32_bf16 v[58:61], v[176:179], v[192:195], v[58:61]
	v_mfma_f32_16x16x32_bf16 v[50:53], v[184:187], v[192:195], v[50:53]
	v_mfma_f32_16x16x32_bf16 v[42:45], v[176:179], v[200:203], v[42:45]
	v_mfma_f32_16x16x32_bf16 v[34:37], v[184:187], v[200:203], v[34:37]
	v_mfma_f32_16x16x32_bf16 v[26:29], v[176:179], v[208:211], v[26:29]
	v_mfma_f32_16x16x32_bf16 v[18:21], v[184:187], v[208:211], v[18:21]
	v_mfma_f32_16x16x32_bf16 v[10:13], v[176:179], v[216:219], v[10:13]
	v_mfma_f32_16x16x32_bf16 v[2:5], v[184:187], v[216:219], v[2:5]
	s_setprio 0
	s_barrier
	s_add_i32 s48, s48, 2
	s_add_u32 s20, s20, 0x100
	s_addc_u32 s21, s21, 0
	s_add_u32 s46, s46, 0x100
	s_addc_u32 s47, s47, 0
	s_cmp_gt_u32 s48, 29
	s_cbranch_scc0 .LBB0_219
	s_and_b64 vcc, exec, s[8:9]
	s_cbranch_vccz .LBB0_222
	s_barrier

; #define PG8_STAGE(bufoff, gbase, voff) do { _Pragma("unroll") for (int _i = 0; _i < 2; ++_i) \
;         __builtin_amdgcn_global_load_lds((const unsigned*)((const char*)(gbase) + (voff)[_i]), (PG8_LAS unsigned*)(lds + (bufoff) + ldsw + _i * 8192), 16, 0, 0); } while (0)
; #define PG8_WAIT_V(n) asm volatile("s_waitcnt vmcnt(" #n ")" ::: "memory")
; #define PG8_WAIT_L(n) asm volatile("s_waitcnt lgkmcnt(" #n ")" ::: "memory")
; #define PG8_BAR __builtin_amdgcn_s_barrier()
; #define PG8_SCHED __builtin_amdgcn_sched_barrier(0)
; template <class Epi, class Sched, bool ALIGN_EPI = true, bool SP2 = true>
; __device__ __forceinline__ void gemm_phase(PG8_LAS unsigned char* lds, const int K  , const Sched& S, const Epi& E) {
;     ...
;             PG8_LDB(B0, 0, 0); PG8_LDB(B1, 0, 1); PG8_SCHED; PG8_LDA(At, 0, 0); PG8_STAGE(PG8_SA(1, 1), a1 + hstep, voffA);
;             PG8_WAIT_V(8); PG8_WAIT_L(0); PG8_BAR; PG8_MMA(0, 0, At, B0); PG8_MMA(0, 1, At, B1); PG8_BAR; PG8_SCHED;
;             PG8_LDA(At, 0, 1); PG8_STAGE(PG8_SB(0, 0), b2, voffB); PG8_STAGE(PG8_SB(0, 1), b2 + hstep, voffB); PG8_STAGE(PG8_SA(0, 0), a2, voffA);
;             PG8_WAIT_V(8); PG8_WAIT_L(0); PG8_BAR; PG8_MMA(1, 0, At, B0); PG8_MMA(1, 1, At, B1); PG8_BAR; PG8_SCHED;
.LBB0_393:
	ds_read_b128 v[18:21], v190
	ds_read_b128 v[22:25], v190 offset:1024
	ds_read_b128 v[26:29], v190 offset:2048
	ds_read_b128 v[30:33], v190 offset:3072
	ds_read_b128 v[2:5], v191
	ds_read_b128 v[6:9], v191 offset:1024
	ds_read_b128 v[10:13], v191 offset:2048
	ds_read_b128 v[14:17], v191 offset:3072
	s_add_i32 s50, s22, 2
	s_add_u32 s20, s18, 0xfff50080
	s_addc_u32 s21, s19, -1
	s_cmp_eq_u32 s47, s22
	s_cselect_b32 s22, s14, s20
	s_cselect_b32 s23, s15, s21
	s_cselect_b32 s21, s17, s49
	s_cselect_b32 s20, s16, s48
	v_lshl_add_u64 v[218:219], s[18:19], 0, v[170:171]
	s_add_i32 m0, s26, 0xc000
	ds_read_b128 v[178:181], v192
	ds_read_b128 v[182:185], v192 offset:1024
	ds_read_b128 v[194:197], v192 offset:2048
	ds_read_b128 v[198:201], v192 offset:3072
	ds_read_b128 v[202:205], v192 offset:4096
	ds_read_b128 v[206:209], v192 offset:5120
	ds_read_b128 v[210:213], v192 offset:6144
	ds_read_b128 v[214:217], v192 offset:7168
	global_load_lds_dwordx4 v[218:219], off
	v_lshl_add_u64 v[218:219], s[18:19], 0, v[172:173]
	s_add_i32 m0, s26, 0xe000
	s_nop 0
	global_load_lds_dwordx4 v[218:219], off
	s_waitcnt vmcnt(8)
	s_waitcnt lgkmcnt(0)
	s_barrier
	s_setprio 1
	s_waitcnt lgkmcnt(0)
	v_mfma_scale_f32_16x16x128_f8f6f4 v[158:161], v[18:25], v[178:185], v[158:161], v186, v186 op_sel_hi:[0,0,0]
	v_mfma_scale_f32_16x16x128_f8f6f4 v[154:157], v[26:33], v[178:185], v[154:157], v186, v186 op_sel_hi:[0,0,0]
	v_mfma_scale_f32_16x16x128_f8f6f4 v[150:153], v[18:25], v[194:201], v[150:153], v186, v186 op_sel_hi:[0,0,0]
	v_mfma_scale_f32_16x16x128_f8f6f4 v[142:145], v[26:33], v[194:201], v[142:145], v186, v186 op_sel_hi:[0,0,0]
	v_mfma_scale_f32_16x16x128_f8f6f4 v[134:137], v[18:25], v[202:209], v[134:137], v186, v186 op_sel_hi:[0,0,0]
	v_mfma_scale_f32_16x16x128_f8f6f4 v[126:129], v[26:33], v[202:209], v[126:129], v186, v186 op_sel_hi:[0,0,0]
	v_mfma_scale_f32_16x16x128_f8f6f4 v[118:121], v[18:25], v[210:217], v[118:121], v186, v186 op_sel_hi:[0,0,0]
	v_mfma_scale_f32_16x16x128_f8f6f4 v[110:113], v[26:33], v[210:217], v[110:113], v186, v186 op_sel_hi:[0,0,0]
	v_mfma_scale_f32_16x16x128_f8f6f4 v[146:149], v[2:9], v[178:185], v[146:149], v186, v186 op_sel_hi:[0,0,0]
	v_mfma_scale_f32_16x16x128_f8f6f4 v[138:141], v[10:17], v[178:185], v[138:141], v186, v186 op_sel_hi:[0,0,0]
	v_mfma_scale_f32_16x16x128_f8f6f4 v[130:133], v[2:9], v[194:201], v[130:133], v186, v186 op_sel_hi:[0,0,0]
	v_mfma_scale_f32_16x16x128_f8f6f4 v[122:125], v[10:17], v[194:201], v[122:125], v186, v186 op_sel_hi:[0,0,0]
	v_mfma_scale_f32_16x16x128_f8f6f4 v[114:117], v[2:9], v[202:209], v[114:117], v186, v186 op_sel_hi:[0,0,0]
	v_mfma_scale_f32_16x16x128_f8f6f4 v[106:109], v[10:17], v[202:209], v[106:109], v186, v186 op_sel_hi:[0,0,0]
	v_mfma_scale_f32_16x16x128_f8f6f4 v[102:105], v[2:9], v[210:217], v[102:105], v186, v186 op_sel_hi:[0,0,0]
	v_mfma_scale_f32_16x16x128_f8f6f4 v[98:101], v[10:17], v[210:217], v[98:101], v186, v186 op_sel_hi:[0,0,0]
	s_setprio 0
	s_barrier
	s_add_i32 s51, s37, s25
	v_lshl_add_u64 v[178:179], s[20:21], 0, v[164:165]
	s_mov_b32 m0, s51
	ds_read_b128 v[194:197], v192 offset:16384
	ds_read_b128 v[198:201], v192 offset:17408
	ds_read_b128 v[202:205], v192 offset:18432
	ds_read_b128 v[206:209], v192 offset:19456
	ds_read_b128 v[210:213], v192 offset:20480
	ds_read_b128 v[214:217], v192 offset:21504
	ds_read_b128 v[218:221], v192 offset:22528
	ds_read_b128 v[222:225], v192 offset:23552
	global_load_lds_dwordx4 v[178:179], off
	s_add_i32 m0, s51, 0x2000
	s_add_u32 s68, s20, 0xb0000
	v_lshl_add_u64 v[180:181], s[20:21], 0, v[168:169]
	s_addc_u32 s69, s21, 0
	s_add_i32 s51, s38, s25
	global_load_lds_dwordx4 v[180:181], off
	v_lshl_add_u64 v[182:183], s[68:69], 0, v[164:165]
	s_mov_b32 m0, s51
	v_lshl_add_u64 v[184:185], s[22:23], 0, v[166:167]
	global_load_lds_dwordx4 v[182:183], off
	v_lshl_add_u64 v[182:183], s[68:69], 0, v[168:169]
	s_add_i32 m0, s51, 0x2000
	s_nop 0
	global_load_lds_dwordx4 v[182:183], off
	v_lshl_add_u64 v[182:183], s[22:23], 0, v[162:163]
	s_mov_b32 m0, s26
	s_nop 0
	global_load_lds_dwordx4 v[182:183], off
	s_mov_b32 m0, s27
	s_nop 0
	global_load_lds_dwordx4 v[184:185], off
	s_waitcnt vmcnt(8)
	s_waitcnt lgkmcnt(0)
	s_barrier
	s_setprio 1
	s_waitcnt lgkmcnt(0)
	v_mfma_scale_f32_16x16x128_f8f6f4 v[94:97], v[18:25], v[194:201], v[94:97], v186, v186 op_sel_hi:[0,0,0]
	v_mfma_scale_f32_16x16x128_f8f6f4 v[90:93], v[26:33], v[194:201], v[90:93], v186, v186 op_sel_hi:[0,0,0]
	v_mfma_scale_f32_16x16x128_f8f6f4 v[86:89], v[18:25], v[202:209], v[86:89], v186, v186 op_sel_hi:[0,0,0]
	v_mfma_scale_f32_16x16x128_f8f6f4 v[78:81], v[26:33], v[202:209], v[78:81], v186, v186 op_sel_hi:[0,0,0]
	v_mfma_scale_f32_16x16x128_f8f6f4 v[70:73], v[18:25], v[210:217], v[70:73], v186, v186 op_sel_hi:[0,0,0]
	v_mfma_scale_f32_16x16x128_f8f6f4 v[62:65], v[26:33], v[210:217], v[62:65], v186, v186 op_sel_hi:[0,0,0]
	v_mfma_scale_f32_16x16x128_f8f6f4 v[54:57], v[18:25], v[218:225], v[54:57], v186, v186 op_sel_hi:[0,0,0]
	v_mfma_scale_f32_16x16x128_f8f6f4 v[46:49], v[26:33], v[218:225], v[46:49], v186, v186 op_sel_hi:[0,0,0]
	v_mfma_scale_f32_16x16x128_f8f6f4 v[82:85], v[2:9], v[194:201], v[82:85], v186, v186 op_sel_hi:[0,0,0]
	v_mfma_scale_f32_16x16x128_f8f6f4 v[74:77], v[10:17], v[194:201], v[74:77], v186, v186 op_sel_hi:[0,0,0]
	v_mfma_scale_f32_16x16x128_f8f6f4 v[66:69], v[2:9], v[202:209], v[66:69], v186, v186 op_sel_hi:[0,0,0]
	v_mfma_scale_f32_16x16x128_f8f6f4 v[58:61], v[10:17], v[202:209], v[58:61], v186, v186 op_sel_hi:[0,0,0]
	v_mfma_scale_f32_16x16x128_f8f6f4 v[50:53], v[2:9], v[210:217], v[50:53], v186, v186 op_sel_hi:[0,0,0]
	v_mfma_scale_f32_16x16x128_f8f6f4 v[42:45], v[10:17], v[210:217], v[42:45], v186, v186 op_sel_hi:[0,0,0]
	v_mfma_scale_f32_16x16x128_f8f6f4 v[38:41], v[2:9], v[218:225], v[38:41], v186, v186 op_sel_hi:[0,0,0]
	v_mfma_scale_f32_16x16x128_f8f6f4 v[34:37], v[10:17], v[218:225], v[34:37], v186, v186 op_sel_hi:[0,0,0]
	s_setprio 0
	s_barrier
; #define PG8_STAGE(bufoff, gbase, voff) do { _Pragma("unroll") for (int _i = 0; _i < 2; ++_i) \
;         __builtin_amdgcn_global_load_lds((const unsigned*)((const char*)(gbase) + (voff)[_i]), (PG8_LAS unsigned*)(lds + (bufoff) + ldsw + _i * 8192), 16, 0, 0); } while (0)
; #define PG8_WAIT_V(n) asm volatile("s_waitcnt vmcnt(" #n ")" ::: "memory")
; #define PG8_WAIT_L(n) asm volatile("s_waitcnt lgkmcnt(" #n ")" ::: "memory")
; #define PG8_BAR __builtin_amdgcn_s_barrier()
; #define PG8_SCHED __builtin_amdgcn_sched_barrier(0)
; template <class Epi, class Sched, bool ALIGN_EPI = true, bool SP2 = true>
; __device__ __forceinline__ void gemm_phase(PG8_LAS unsigned char* lds, const int K  , const Sched& S, const Epi& E) {
;     ...
;             PG8_LDB(B0, 1, 0); PG8_LDB(B1, 1, 1); PG8_SCHED; PG8_LDA(At, 1, 0); PG8_STAGE(PG8_SA(0, 1), a2 + hstep, voffA);
;             PG8_WAIT_V(8); PG8_WAIT_L(0); PG8_BAR; PG8_MMA(0, 0, At, B0); PG8_MMA(0, 1, At, B1); PG8_BAR; PG8_SCHED;
;             PG8_LDA(At, 1, 1); PG8_STAGE(PG8_SB(1, 0), b3, voffB); PG8_STAGE(PG8_SB(1, 1), b3 + hstep, voffB); PG8_STAGE(PG8_SA(1, 0), a3, voffA);
;             PG8_WAIT_V(8); PG8_WAIT_L(0); PG8_BAR; PG8_MMA(1, 0, At, B0); PG8_MMA(1, 1, At, B1); PG8_BAR; PG8_SCHED;
;     ...
;         if constexpr (Epi::FP8) asm volatile("s_nop 15\n\ts_nop 15\n\ts_nop 15\n\ts_nop 15\n\ts_nop 15" ::: "memory");
	s_add_i32 s51, 0, 0x18000
	s_add_i32 s68, 0, 0x1c000
	v_add_u32_e32 v14, s51, v188
	v_add_u32_e32 v30, s68, v188
	ds_read_b128 v[2:5], v14
	ds_read_b128 v[6:9], v14 offset:1024
	ds_read_b128 v[10:13], v14 offset:2048
	ds_read_b128 v[14:17], v14 offset:3072
	ds_read_b128 v[18:21], v30
	ds_read_b128 v[22:25], v30 offset:1024
	ds_read_b128 v[26:29], v30 offset:2048
	ds_read_b128 v[30:33], v30 offset:3072
	s_add_u32 s22, s22, 0xb0000
	s_addc_u32 s23, s23, 0
	s_mov_b32 m0, s28
	v_lshl_add_u64 v[226:227], s[22:23], 0, v[162:163]
	ds_read_b128 v[194:197], v192 offset:32768
	ds_read_b128 v[198:201], v192 offset:33792
	ds_read_b128 v[202:205], v192 offset:34816
	ds_read_b128 v[206:209], v192 offset:35840
	ds_read_b128 v[210:213], v192 offset:36864
	ds_read_b128 v[214:217], v192 offset:37888
	ds_read_b128 v[218:221], v192 offset:38912
	ds_read_b128 v[222:225], v192 offset:39936
	global_load_lds_dwordx4 v[226:227], off
	v_lshl_add_u64 v[226:227], s[22:23], 0, v[166:167]
	s_mov_b32 m0, s29
	s_nop 0
	global_load_lds_dwordx4 v[226:227], off
	s_waitcnt vmcnt(8)
	s_waitcnt lgkmcnt(0)
	s_barrier
	s_setprio 1
	s_waitcnt lgkmcnt(0)
	v_mfma_scale_f32_16x16x128_f8f6f4 v[158:161], v[2:9], v[194:201], v[158:161], v186, v186 op_sel_hi:[0,0,0]
	v_mfma_scale_f32_16x16x128_f8f6f4 v[154:157], v[10:17], v[194:201], v[154:157], v186, v186 op_sel_hi:[0,0,0]
	v_mfma_scale_f32_16x16x128_f8f6f4 v[150:153], v[2:9], v[202:209], v[150:153], v186, v186 op_sel_hi:[0,0,0]
	v_mfma_scale_f32_16x16x128_f8f6f4 v[142:145], v[10:17], v[202:209], v[142:145], v186, v186 op_sel_hi:[0,0,0]
	v_mfma_scale_f32_16x16x128_f8f6f4 v[134:137], v[2:9], v[210:217], v[134:137], v186, v186 op_sel_hi:[0,0,0]
	v_mfma_scale_f32_16x16x128_f8f6f4 v[126:129], v[10:17], v[210:217], v[126:129], v186, v186 op_sel_hi:[0,0,0]
	v_mfma_scale_f32_16x16x128_f8f6f4 v[118:121], v[2:9], v[218:225], v[118:121], v186, v186 op_sel_hi:[0,0,0]
	v_mfma_scale_f32_16x16x128_f8f6f4 v[110:113], v[10:17], v[218:225], v[110:113], v186, v186 op_sel_hi:[0,0,0]
	v_mfma_scale_f32_16x16x128_f8f6f4 v[146:149], v[18:25], v[194:201], v[146:149], v186, v186 op_sel_hi:[0,0,0]
	v_mfma_scale_f32_16x16x128_f8f6f4 v[138:141], v[26:33], v[194:201], v[138:141], v186, v186 op_sel_hi:[0,0,0]
	v_mfma_scale_f32_16x16x128_f8f6f4 v[130:133], v[18:25], v[202:209], v[130:133], v186, v186 op_sel_hi:[0,0,0]
	v_mfma_scale_f32_16x16x128_f8f6f4 v[122:125], v[26:33], v[202:209], v[122:125], v186, v186 op_sel_hi:[0,0,0]
	v_mfma_scale_f32_16x16x128_f8f6f4 v[114:117], v[18:25], v[210:217], v[114:117], v186, v186 op_sel_hi:[0,0,0]
	v_mfma_scale_f32_16x16x128_f8f6f4 v[106:109], v[26:33], v[210:217], v[106:109], v186, v186 op_sel_hi:[0,0,0]
	v_mfma_scale_f32_16x16x128_f8f6f4 v[102:105], v[18:25], v[218:225], v[102:105], v186, v186 op_sel_hi:[0,0,0]
	v_mfma_scale_f32_16x16x128_f8f6f4 v[98:101], v[26:33], v[218:225], v[98:101], v186, v186 op_sel_hi:[0,0,0]
	s_setprio 0
	s_barrier
	s_add_i32 s22, s51, s25
	v_lshl_add_u64 v[178:179], v[178:179], 0, s[8:9]
	s_mov_b32 m0, s22
	ds_read_b128 v[194:197], v192 offset:49152
	ds_read_b128 v[198:201], v192 offset:50176
	ds_read_b128 v[202:205], v192 offset:51200
	ds_read_b128 v[206:209], v192 offset:52224
	ds_read_b128 v[210:213], v192 offset:53248
	ds_read_b128 v[214:217], v192 offset:54272
	ds_read_b128 v[218:221], v192 offset:55296
	ds_read_b128 v[222:225], v192 offset:56320
	global_load_lds_dwordx4 v[178:179], off
	s_add_i32 m0, s22, 0x2000
	s_add_u32 s20, s20, 0xb0080
	v_lshl_add_u64 v[178:179], v[180:181], 0, s[8:9]
	s_addc_u32 s21, s21, 0
	s_add_i32 s22, s68, s25
	global_load_lds_dwordx4 v[178:179], off
	v_lshl_add_u64 v[178:179], s[20:21], 0, v[164:165]
	s_mov_b32 m0, s22
	s_nop 0
	global_load_lds_dwordx4 v[178:179], off
	v_lshl_add_u64 v[178:179], s[20:21], 0, v[168:169]
	s_add_i32 m0, s22, 0x2000
	s_nop 0
	global_load_lds_dwordx4 v[178:179], off
	v_lshl_add_u64 v[178:179], v[182:183], 0, s[8:9]
	s_mov_b32 m0, s33
	s_nop 0
	global_load_lds_dwordx4 v[178:179], off
	v_lshl_add_u64 v[178:179], v[184:185], 0, s[8:9]
	s_mov_b32 m0, s34
	s_nop 0
	global_load_lds_dwordx4 v[178:179], off
	s_waitcnt vmcnt(8)
	s_waitcnt lgkmcnt(0)
	s_barrier
	s_setprio 1
	s_waitcnt lgkmcnt(0)
	v_mfma_scale_f32_16x16x128_f8f6f4 v[94:97], v[2:9], v[194:201], v[94:97], v186, v186 op_sel_hi:[0,0,0]
	v_mfma_scale_f32_16x16x128_f8f6f4 v[90:93], v[10:17], v[194:201], v[90:93], v186, v186 op_sel_hi:[0,0,0]
	v_mfma_scale_f32_16x16x128_f8f6f4 v[86:89], v[2:9], v[202:209], v[86:89], v186, v186 op_sel_hi:[0,0,0]
	v_mfma_scale_f32_16x16x128_f8f6f4 v[78:81], v[10:17], v[202:209], v[78:81], v186, v186 op_sel_hi:[0,0,0]
	v_mfma_scale_f32_16x16x128_f8f6f4 v[70:73], v[2:9], v[210:217], v[70:73], v186, v186 op_sel_hi:[0,0,0]
	v_mfma_scale_f32_16x16x128_f8f6f4 v[62:65], v[10:17], v[210:217], v[62:65], v186, v186 op_sel_hi:[0,0,0]
	v_mfma_scale_f32_16x16x128_f8f6f4 v[54:57], v[2:9], v[218:225], v[54:57], v186, v186 op_sel_hi:[0,0,0]
	v_mfma_scale_f32_16x16x128_f8f6f4 v[46:49], v[10:17], v[218:225], v[46:49], v186, v186 op_sel_hi:[0,0,0]
	v_mfma_scale_f32_16x16x128_f8f6f4 v[82:85], v[18:25], v[194:201], v[82:85], v186, v186 op_sel_hi:[0,0,0]
	v_mfma_scale_f32_16x16x128_f8f6f4 v[74:77], v[26:33], v[194:201], v[74:77], v186, v186 op_sel_hi:[0,0,0]
	v_mfma_scale_f32_16x16x128_f8f6f4 v[66:69], v[18:25], v[202:209], v[66:69], v186, v186 op_sel_hi:[0,0,0]
	v_mfma_scale_f32_16x16x128_f8f6f4 v[58:61], v[26:33], v[202:209], v[58:61], v186, v186 op_sel_hi:[0,0,0]
	v_mfma_scale_f32_16x16x128_f8f6f4 v[50:53], v[18:25], v[210:217], v[50:53], v186, v186 op_sel_hi:[0,0,0]
	v_mfma_scale_f32_16x16x128_f8f6f4 v[42:45], v[26:33], v[210:217], v[42:45], v186, v186 op_sel_hi:[0,0,0]
	v_mfma_scale_f32_16x16x128_f8f6f4 v[38:41], v[18:25], v[218:225], v[38:41], v186, v186 op_sel_hi:[0,0,0]
	v_mfma_scale_f32_16x16x128_f8f6f4 v[34:37], v[26:33], v[218:225], v[34:37], v186, v186 op_sel_hi:[0,0,0]
	s_setprio 0
	s_barrier
	s_add_u32 s18, s18, 0x100
	s_addc_u32 s19, s19, 0
	s_add_u32 s48, s48, 0x100
	s_addc_u32 s49, s49, 0
	s_cmp_ge_u32 s50, s4
	s_mov_b32 s22, s50
	s_cbranch_scc0 .LBB0_393
	s_nop 15
	s_nop 15
	s_nop 15
	s_nop 15
	s_nop 15
	s_and_b64 vcc, exec, s[10:11]
	s_cbranch_vccz .LBB0_396
	s_barrier

; #define PG8_STAGE(bufoff, gbase, voff) do { _Pragma("unroll") for (int _i = 0; _i < 2; ++_i) \
;         __builtin_amdgcn_global_load_lds((const unsigned*)((const char*)(gbase) + (voff)[_i]), (PG8_LAS unsigned*)(lds + (bufoff) + ldsw + _i * 8192), 16, 0, 0); } while (0)
; #define PG8_WAIT_V(n) asm volatile("s_waitcnt vmcnt(" #n ")" ::: "memory")
; #define PG8_WAIT_L(n) asm volatile("s_waitcnt lgkmcnt(" #n ")" ::: "memory")
; #define PG8_BAR __builtin_amdgcn_s_barrier()
; #define PG8_SCHED __builtin_amdgcn_sched_barrier(0)
; template <class Epi, class Sched, bool ALIGN_EPI = true, bool SP2 = true>
; __device__ __forceinline__ void gemm_phase(PG8_LAS unsigned char* lds, const int K  , const Sched& S, const Epi& E) {
;     ...
;             PG8_LDB(B0, 0, 0); PG8_LDB(B1, 0, 1); PG8_SCHED; PG8_LDA(At, 0, 0); PG8_STAGE(PG8_SA(1, 1), a1 + hstep, voffA);
;             PG8_WAIT_V(8); PG8_WAIT_L(0); PG8_BAR; PG8_MMA(0, 0, At, B0); PG8_MMA(0, 1, At, B1); PG8_BAR; PG8_SCHED;
;             PG8_LDA(At, 0, 1); PG8_STAGE(PG8_SB(0, 0), b2, voffB); PG8_STAGE(PG8_SB(0, 1), b2 + hstep, voffB); PG8_STAGE(PG8_SA(0, 0), a2, voffA);
;             PG8_WAIT_V(8); PG8_WAIT_L(0); PG8_BAR; PG8_MMA(1, 0, At, B0); PG8_MMA(1, 1, At, B1); PG8_BAR; PG8_SCHED;
.LBB0_537:
	ds_read_b128 v[150:153], v156
	ds_read_b128 v[160:163], v156 offset:1024
	ds_read_b128 v[164:167], v156 offset:2048
	ds_read_b128 v[168:171], v156 offset:3072
	ds_read_b128 v[172:175], v157
	ds_read_b128 v[176:179], v157 offset:1024
	ds_read_b128 v[180:183], v157 offset:2048
	ds_read_b128 v[184:187], v157 offset:3072
	s_add_u32 s22, s20, 0xfff80080
	s_addc_u32 s23, s21, -1
	s_cmp_eq_u32 s47, 28
	s_cselect_b32 s25, s13, s23
	s_cselect_b32 s24, s19, s22
	s_cselect_b32 s23, s11, s46
	s_cselect_b32 s22, s44, s45
	v_lshl_add_u64 v[220:221], s[20:21], 0, v[142:143]
	s_add_i32 m0, s31, 0xc000
	ds_read_b128 v[188:191], v158
	ds_read_b128 v[192:195], v158 offset:1024
	ds_read_b128 v[196:199], v158 offset:2048
	ds_read_b128 v[200:203], v158 offset:3072
	ds_read_b128 v[204:207], v158 offset:4096
	ds_read_b128 v[208:211], v158 offset:5120
	ds_read_b128 v[212:215], v158 offset:6144
	ds_read_b128 v[216:219], v158 offset:7168
	global_load_lds_dwordx4 v[220:221], off
	v_lshl_add_u64 v[220:221], s[20:21], 0, v[144:145]
	s_add_i32 m0, s31, 0xe000
	s_nop 0
	global_load_lds_dwordx4 v[220:221], off
	s_waitcnt vmcnt(8)
	s_waitcnt lgkmcnt(0)
	s_barrier
	s_setprio 1
	s_waitcnt lgkmcnt(0)
	v_mfma_f32_16x16x32_bf16 v[126:129], v[150:153], v[188:191], v[126:129]
	v_mfma_f32_16x16x32_bf16 v[122:125], v[164:167], v[188:191], v[122:125]
	v_mfma_f32_16x16x32_bf16 v[118:121], v[150:153], v[196:199], v[118:121]
	v_mfma_f32_16x16x32_bf16 v[110:113], v[164:167], v[196:199], v[110:113]
	v_mfma_f32_16x16x32_bf16 v[102:105], v[150:153], v[204:207], v[102:105]
	v_mfma_f32_16x16x32_bf16 v[94:97], v[164:167], v[204:207], v[94:97]
	v_mfma_f32_16x16x32_bf16 v[86:89], v[150:153], v[212:215], v[86:89]
	v_mfma_f32_16x16x32_bf16 v[78:81], v[164:167], v[212:215], v[78:81]
	v_mfma_f32_16x16x32_bf16 v[126:129], v[160:163], v[192:195], v[126:129]
	v_mfma_f32_16x16x32_bf16 v[122:125], v[168:171], v[192:195], v[122:125]
	v_mfma_f32_16x16x32_bf16 v[118:121], v[160:163], v[200:203], v[118:121]
	v_mfma_f32_16x16x32_bf16 v[110:113], v[168:171], v[200:203], v[110:113]
	v_mfma_f32_16x16x32_bf16 v[102:105], v[160:163], v[208:211], v[102:105]
	v_mfma_f32_16x16x32_bf16 v[94:97], v[168:171], v[208:211], v[94:97]
	v_mfma_f32_16x16x32_bf16 v[86:89], v[160:163], v[216:219], v[86:89]
	v_mfma_f32_16x16x32_bf16 v[78:81], v[168:171], v[216:219], v[78:81]
	v_mfma_f32_16x16x32_bf16 v[114:117], v[172:175], v[188:191], v[114:117]
	v_mfma_f32_16x16x32_bf16 v[106:109], v[180:183], v[188:191], v[106:109]
	v_mfma_f32_16x16x32_bf16 v[98:101], v[172:175], v[196:199], v[98:101]
	v_mfma_f32_16x16x32_bf16 v[90:93], v[180:183], v[196:199], v[90:93]
	v_mfma_f32_16x16x32_bf16 v[82:85], v[172:175], v[204:207], v[82:85]
	v_mfma_f32_16x16x32_bf16 v[74:77], v[180:183], v[204:207], v[74:77]
	v_mfma_f32_16x16x32_bf16 v[70:73], v[172:175], v[212:215], v[70:73]
	v_mfma_f32_16x16x32_bf16 v[66:69], v[180:183], v[212:215], v[66:69]
	v_mfma_f32_16x16x32_bf16 v[114:117], v[176:179], v[192:195], v[114:117]
	v_mfma_f32_16x16x32_bf16 v[106:109], v[184:187], v[192:195], v[106:109]
	v_mfma_f32_16x16x32_bf16 v[98:101], v[176:179], v[200:203], v[98:101]
	v_mfma_f32_16x16x32_bf16 v[90:93], v[184:187], v[200:203], v[90:93]
	v_mfma_f32_16x16x32_bf16 v[82:85], v[176:179], v[208:211], v[82:85]
	v_mfma_f32_16x16x32_bf16 v[74:77], v[184:187], v[208:211], v[74:77]
	v_mfma_f32_16x16x32_bf16 v[70:73], v[176:179], v[216:219], v[70:73]
	v_mfma_f32_16x16x32_bf16 v[66:69], v[184:187], v[216:219], v[66:69]
	s_setprio 0
	s_barrier
	s_add_i32 s48, s40, s29
	v_lshl_add_u64 v[220:221], s[22:23], 0, v[136:137]
	s_mov_b32 m0, s48
	ds_read_b128 v[188:191], v158 offset:16384
	ds_read_b128 v[192:195], v158 offset:17408
	ds_read_b128 v[196:199], v158 offset:18432
	ds_read_b128 v[200:203], v158 offset:19456
	ds_read_b128 v[204:207], v158 offset:20480
	ds_read_b128 v[208:211], v158 offset:21504
	ds_read_b128 v[212:215], v158 offset:22528
	ds_read_b128 v[216:219], v158 offset:23552
	global_load_lds_dwordx4 v[220:221], off
	s_add_i32 m0, s48, 0x2000
	s_add_u32 s48, s22, 0x80000
	v_lshl_add_u64 v[222:223], s[22:23], 0, v[132:133]
	s_addc_u32 s49, s23, 0
	s_add_i32 s50, s41, s29
	global_load_lds_dwordx4 v[222:223], off
	v_lshl_add_u64 v[224:225], s[48:49], 0, v[136:137]
	s_mov_b32 m0, s50
	v_lshl_add_u64 v[226:227], s[24:25], 0, v[134:135]
	global_load_lds_dwordx4 v[224:225], off
	v_lshl_add_u64 v[224:225], s[48:49], 0, v[132:133]
	s_add_i32 m0, s50, 0x2000
	s_nop 0
	global_load_lds_dwordx4 v[224:225], off
	v_lshl_add_u64 v[224:225], s[24:25], 0, v[138:139]
	s_mov_b32 m0, s31
	s_nop 0
	global_load_lds_dwordx4 v[224:225], off
	s_mov_b32 m0, s33
	s_nop 0
	global_load_lds_dwordx4 v[226:227], off
	s_waitcnt vmcnt(8)
	s_waitcnt lgkmcnt(0)
	s_barrier
; #define PG8_STAGE(bufoff, gbase, voff) do { _Pragma("unroll") for (int _i = 0; _i < 2; ++_i) \
;         __builtin_amdgcn_global_load_lds((const unsigned*)((const char*)(gbase) + (voff)[_i]), (PG8_LAS unsigned*)(lds + (bufoff) + ldsw + _i * 8192), 16, 0, 0); } while (0)
; #define PG8_WAIT_V(n) asm volatile("s_waitcnt vmcnt(" #n ")" ::: "memory")
; #define PG8_WAIT_L(n) asm volatile("s_waitcnt lgkmcnt(" #n ")" ::: "memory")
; #define PG8_BAR __builtin_amdgcn_s_barrier()
; #define PG8_SCHED __builtin_amdgcn_sched_barrier(0)
; template <class Epi, class Sched, bool ALIGN_EPI = true, bool SP2 = true>
; __device__ __forceinline__ void gemm_phase(PG8_LAS unsigned char* lds, const int K  , const Sched& S, const Epi& E) {
;     ...
;             PG8_WAIT_V(8); PG8_WAIT_L(0); PG8_BAR; PG8_MMA(1, 0, At, B0); PG8_MMA(1, 1, At, B1); PG8_BAR; PG8_SCHED;
;             PG8_LDB(B0, 1, 0); PG8_LDB(B1, 1, 1); PG8_SCHED; PG8_LDA(At, 1, 0); PG8_STAGE(PG8_SA(0, 1), a2 + hstep, voffA);
;             PG8_WAIT_V(8); PG8_WAIT_L(0); PG8_BAR; PG8_MMA(0, 0, At, B0); PG8_MMA(0, 1, At, B1); PG8_BAR; PG8_SCHED;
	s_setprio 1
	s_waitcnt lgkmcnt(0)
	v_mfma_f32_16x16x32_bf16 v[62:65], v[150:153], v[188:191], v[62:65]
	v_mfma_f32_16x16x32_bf16 v[58:61], v[164:167], v[188:191], v[58:61]
	v_mfma_f32_16x16x32_bf16 v[54:57], v[150:153], v[196:199], v[54:57]
	v_mfma_f32_16x16x32_bf16 v[46:49], v[164:167], v[196:199], v[46:49]
	v_mfma_f32_16x16x32_bf16 v[38:41], v[150:153], v[204:207], v[38:41]
	v_mfma_f32_16x16x32_bf16 v[30:33], v[164:167], v[204:207], v[30:33]
	v_mfma_f32_16x16x32_bf16 v[22:25], v[150:153], v[212:215], v[22:25]
	v_mfma_f32_16x16x32_bf16 v[14:17], v[164:167], v[212:215], v[14:17]
	v_mfma_f32_16x16x32_bf16 v[62:65], v[160:163], v[192:195], v[62:65]
	v_mfma_f32_16x16x32_bf16 v[58:61], v[168:171], v[192:195], v[58:61]
	v_mfma_f32_16x16x32_bf16 v[54:57], v[160:163], v[200:203], v[54:57]
	v_mfma_f32_16x16x32_bf16 v[46:49], v[168:171], v[200:203], v[46:49]
	v_mfma_f32_16x16x32_bf16 v[38:41], v[160:163], v[208:211], v[38:41]
	v_mfma_f32_16x16x32_bf16 v[30:33], v[168:171], v[208:211], v[30:33]
	v_mfma_f32_16x16x32_bf16 v[22:25], v[160:163], v[216:219], v[22:25]
	v_mfma_f32_16x16x32_bf16 v[14:17], v[168:171], v[216:219], v[14:17]
	v_mfma_f32_16x16x32_bf16 v[50:53], v[172:175], v[188:191], v[50:53]
	v_mfma_f32_16x16x32_bf16 v[42:45], v[180:183], v[188:191], v[42:45]
	v_mfma_f32_16x16x32_bf16 v[34:37], v[172:175], v[196:199], v[34:37]
	v_mfma_f32_16x16x32_bf16 v[26:29], v[180:183], v[196:199], v[26:29]
	v_mfma_f32_16x16x32_bf16 v[18:21], v[172:175], v[204:207], v[18:21]
	v_mfma_f32_16x16x32_bf16 v[10:13], v[180:183], v[204:207], v[10:13]
	v_mfma_f32_16x16x32_bf16 v[6:9], v[172:175], v[212:215], v[6:9]
	v_mfma_f32_16x16x32_bf16 v[2:5], v[180:183], v[212:215], v[2:5]
	v_mfma_f32_16x16x32_bf16 v[50:53], v[176:179], v[192:195], v[50:53]
	v_mfma_f32_16x16x32_bf16 v[42:45], v[184:187], v[192:195], v[42:45]
	v_mfma_f32_16x16x32_bf16 v[34:37], v[176:179], v[200:203], v[34:37]
	v_mfma_f32_16x16x32_bf16 v[26:29], v[184:187], v[200:203], v[26:29]
	v_mfma_f32_16x16x32_bf16 v[18:21], v[176:179], v[208:211], v[18:21]
	v_mfma_f32_16x16x32_bf16 v[10:13], v[184:187], v[208:211], v[10:13]
	v_mfma_f32_16x16x32_bf16 v[6:9], v[176:179], v[216:219], v[6:9]
	v_mfma_f32_16x16x32_bf16 v[2:5], v[184:187], v[216:219], v[2:5]
	s_setprio 0
	s_barrier
	s_add_i32 s48, 0, 0x18000
	v_add_u32_e32 v140, s48, v154
	s_add_i32 s49, 0, 0x1c000
	ds_read_b128 v[150:153], v140
	ds_read_b128 v[160:163], v140 offset:1024
	ds_read_b128 v[164:167], v140 offset:2048
	ds_read_b128 v[168:171], v140 offset:3072
	v_add_u32_e32 v140, s49, v154
	ds_read_b128 v[172:175], v140
	ds_read_b128 v[176:179], v140 offset:1024
	ds_read_b128 v[180:183], v140 offset:2048
	ds_read_b128 v[184:187], v140 offset:3072
	s_add_u32 s24, s24, 0x80000
	s_addc_u32 s25, s25, 0
	s_mov_b32 m0, s34
	v_lshl_add_u64 v[230:231], s[24:25], 0, v[138:139]
	ds_read_b128 v[188:191], v158 offset:32768
	ds_read_b128 v[192:195], v158 offset:33792
	ds_read_b128 v[196:199], v158 offset:34816
	ds_read_b128 v[200:203], v158 offset:35840
	ds_read_b128 v[204:207], v158 offset:36864
	ds_read_b128 v[208:211], v158 offset:37888
	ds_read_b128 v[212:215], v158 offset:38912
	ds_read_b128 v[216:219], v158 offset:39936
	global_load_lds_dwordx4 v[230:231], off
	v_lshl_add_u64 v[230:231], s[24:25], 0, v[134:135]
	s_mov_b32 m0, s35
	s_nop 0
	global_load_lds_dwordx4 v[230:231], off
	s_waitcnt vmcnt(8)
	s_waitcnt lgkmcnt(0)
	s_barrier
	s_setprio 1
	s_waitcnt lgkmcnt(0)
	v_mfma_f32_16x16x32_bf16 v[126:129], v[150:153], v[188:191], v[126:129]
	v_mfma_f32_16x16x32_bf16 v[122:125], v[164:167], v[188:191], v[122:125]
	v_mfma_f32_16x16x32_bf16 v[118:121], v[150:153], v[196:199], v[118:121]
	v_mfma_f32_16x16x32_bf16 v[110:113], v[164:167], v[196:199], v[110:113]
	v_mfma_f32_16x16x32_bf16 v[102:105], v[150:153], v[204:207], v[102:105]
	v_mfma_f32_16x16x32_bf16 v[94:97], v[164:167], v[204:207], v[94:97]
	v_mfma_f32_16x16x32_bf16 v[86:89], v[150:153], v[212:215], v[86:89]
	v_mfma_f32_16x16x32_bf16 v[78:81], v[164:167], v[212:215], v[78:81]
	v_mfma_f32_16x16x32_bf16 v[126:129], v[160:163], v[192:195], v[126:129]
	v_mfma_f32_16x16x32_bf16 v[122:125], v[168:171], v[192:195], v[122:125]
	v_mfma_f32_16x16x32_bf16 v[118:121], v[160:163], v[200:203], v[118:121]
	v_mfma_f32_16x16x32_bf16 v[110:113], v[168:171], v[200:203], v[110:113]
	v_mfma_f32_16x16x32_bf16 v[102:105], v[160:163], v[208:211], v[102:105]
	v_mfma_f32_16x16x32_bf16 v[94:97], v[168:171], v[208:211], v[94:97]
	v_mfma_f32_16x16x32_bf16 v[86:89], v[160:163], v[216:219], v[86:89]
	v_mfma_f32_16x16x32_bf16 v[78:81], v[168:171], v[216:219], v[78:81]
	v_mfma_f32_16x16x32_bf16 v[114:117], v[172:175], v[188:191], v[114:117]
	v_mfma_f32_16x16x32_bf16 v[106:109], v[180:183], v[188:191], v[106:109]
	v_mfma_f32_16x16x32_bf16 v[98:101], v[172:175], v[196:199], v[98:101]
	v_mfma_f32_16x16x32_bf16 v[90:93], v[180:183], v[196:199], v[90:93]
	v_mfma_f32_16x16x32_bf16 v[82:85], v[172:175], v[204:207], v[82:85]
	v_mfma_f32_16x16x32_bf16 v[74:77], v[180:183], v[204:207], v[74:77]
	v_mfma_f32_16x16x32_bf16 v[70:73], v[172:175], v[212:215], v[70:73]
	v_mfma_f32_16x16x32_bf16 v[66:69], v[180:183], v[212:215], v[66:69]
	v_mfma_f32_16x16x32_bf16 v[114:117], v[176:179], v[192:195], v[114:117]
	v_mfma_f32_16x16x32_bf16 v[106:109], v[184:187], v[192:195], v[106:109]
	v_mfma_f32_16x16x32_bf16 v[98:101], v[176:179], v[200:203], v[98:101]
	v_mfma_f32_16x16x32_bf16 v[90:93], v[184:187], v[200:203], v[90:93]
	v_mfma_f32_16x16x32_bf16 v[82:85], v[176:179], v[208:211], v[82:85]
	v_mfma_f32_16x16x32_bf16 v[74:77], v[184:187], v[208:211], v[74:77]
	v_mfma_f32_16x16x32_bf16 v[70:73], v[176:179], v[216:219], v[70:73]
	v_mfma_f32_16x16x32_bf16 v[66:69], v[184:187], v[216:219], v[66:69]
	s_setprio 0
	s_barrier
; #define PG8_STAGE(bufoff, gbase, voff) do { _Pragma("unroll") for (int _i = 0; _i < 2; ++_i) \
;         __builtin_amdgcn_global_load_lds((const unsigned*)((const char*)(gbase) + (voff)[_i]), (PG8_LAS unsigned*)(lds + (bufoff) + ldsw + _i * 8192), 16, 0, 0); } while (0)
; #define PG8_WAIT_V(n) asm volatile("s_waitcnt vmcnt(" #n ")" ::: "memory")
; #define PG8_WAIT_L(n) asm volatile("s_waitcnt lgkmcnt(" #n ")" ::: "memory")
; #define PG8_BAR __builtin_amdgcn_s_barrier()
; #define PG8_SCHED __builtin_amdgcn_sched_barrier(0)
; template <class Epi, class Sched, bool ALIGN_EPI = true, bool SP2 = true>
; __device__ __forceinline__ void gemm_phase(PG8_LAS unsigned char* lds, const int K  , const Sched& S, const Epi& E) {
;     ...
;             PG8_WAIT_V(8); PG8_WAIT_L(0); PG8_BAR; PG8_MMA(0, 0, At, B0); PG8_MMA(0, 1, At, B1); PG8_BAR; PG8_SCHED;
;             PG8_LDA(At, 1, 1); PG8_STAGE(PG8_SB(1, 0), b3, voffB); PG8_STAGE(PG8_SB(1, 1), b3 + hstep, voffB); PG8_STAGE(PG8_SA(1, 0), a3, voffA);
;             PG8_WAIT_V(8); PG8_WAIT_L(0); PG8_BAR; PG8_MMA(1, 0, At, B0); PG8_MMA(1, 1, At, B1); PG8_BAR; PG8_SCHED;
	s_add_i32 s24, s48, s29
	v_lshl_add_u64 v[220:221], v[220:221], 0, s[6:7]
	s_mov_b32 m0, s24
	ds_read_b128 v[188:191], v158 offset:49152
	ds_read_b128 v[192:195], v158 offset:50176
	ds_read_b128 v[196:199], v158 offset:51200
	ds_read_b128 v[200:203], v158 offset:52224
	ds_read_b128 v[204:207], v158 offset:53248
	ds_read_b128 v[208:211], v158 offset:54272
	ds_read_b128 v[212:215], v158 offset:55296
	ds_read_b128 v[216:219], v158 offset:56320
	global_load_lds_dwordx4 v[220:221], off
	s_add_i32 m0, s24, 0x2000
	s_add_u32 s22, s22, 0x80080
	v_lshl_add_u64 v[220:221], v[222:223], 0, s[6:7]
	s_addc_u32 s23, s23, 0
	s_add_i32 s24, s49, s29
	global_load_lds_dwordx4 v[220:221], off
	v_lshl_add_u64 v[220:221], s[22:23], 0, v[136:137]
	s_mov_b32 m0, s24
	s_nop 0
	global_load_lds_dwordx4 v[220:221], off
	v_lshl_add_u64 v[220:221], s[22:23], 0, v[132:133]
	s_add_i32 m0, s24, 0x2000
	s_nop 0
	global_load_lds_dwordx4 v[220:221], off
	v_lshl_add_u64 v[220:221], v[224:225], 0, s[6:7]
	s_mov_b32 m0, s37
	s_nop 0
	global_load_lds_dwordx4 v[220:221], off
	v_lshl_add_u64 v[220:221], v[226:227], 0, s[6:7]
	s_mov_b32 m0, s38
	s_nop 0
	global_load_lds_dwordx4 v[220:221], off
	s_waitcnt vmcnt(8)
	s_waitcnt lgkmcnt(0)
	s_barrier
	s_setprio 1
	s_waitcnt lgkmcnt(0)
	v_mfma_f32_16x16x32_bf16 v[62:65], v[150:153], v[188:191], v[62:65]
	v_mfma_f32_16x16x32_bf16 v[58:61], v[164:167], v[188:191], v[58:61]
	v_mfma_f32_16x16x32_bf16 v[54:57], v[150:153], v[196:199], v[54:57]
	v_mfma_f32_16x16x32_bf16 v[46:49], v[164:167], v[196:199], v[46:49]
	v_mfma_f32_16x16x32_bf16 v[38:41], v[150:153], v[204:207], v[38:41]
	v_mfma_f32_16x16x32_bf16 v[30:33], v[164:167], v[204:207], v[30:33]
	v_mfma_f32_16x16x32_bf16 v[22:25], v[150:153], v[212:215], v[22:25]
	v_mfma_f32_16x16x32_bf16 v[14:17], v[164:167], v[212:215], v[14:17]
	v_mfma_f32_16x16x32_bf16 v[62:65], v[160:163], v[192:195], v[62:65]
	v_mfma_f32_16x16x32_bf16 v[58:61], v[168:171], v[192:195], v[58:61]
	v_mfma_f32_16x16x32_bf16 v[54:57], v[160:163], v[200:203], v[54:57]
	v_mfma_f32_16x16x32_bf16 v[46:49], v[168:171], v[200:203], v[46:49]
	v_mfma_f32_16x16x32_bf16 v[38:41], v[160:163], v[208:211], v[38:41]
	v_mfma_f32_16x16x32_bf16 v[30:33], v[168:171], v[208:211], v[30:33]
	v_mfma_f32_16x16x32_bf16 v[22:25], v[160:163], v[216:219], v[22:25]
	v_mfma_f32_16x16x32_bf16 v[14:17], v[168:171], v[216:219], v[14:17]
	v_mfma_f32_16x16x32_bf16 v[50:53], v[172:175], v[188:191], v[50:53]
	v_mfma_f32_16x16x32_bf16 v[42:45], v[180:183], v[188:191], v[42:45]
	v_mfma_f32_16x16x32_bf16 v[34:37], v[172:175], v[196:199], v[34:37]
	v_mfma_f32_16x16x32_bf16 v[26:29], v[180:183], v[196:199], v[26:29]
	v_mfma_f32_16x16x32_bf16 v[18:21], v[172:175], v[204:207], v[18:21]
	v_mfma_f32_16x16x32_bf16 v[10:13], v[180:183], v[204:207], v[10:13]
	v_mfma_f32_16x16x32_bf16 v[6:9], v[172:175], v[212:215], v[6:9]
	v_mfma_f32_16x16x32_bf16 v[2:5], v[180:183], v[212:215], v[2:5]
	v_mfma_f32_16x16x32_bf16 v[50:53], v[176:179], v[192:195], v[50:53]
	v_mfma_f32_16x16x32_bf16 v[42:45], v[184:187], v[192:195], v[42:45]
	v_mfma_f32_16x16x32_bf16 v[34:37], v[176:179], v[200:203], v[34:37]
	v_mfma_f32_16x16x32_bf16 v[26:29], v[184:187], v[200:203], v[26:29]
	v_mfma_f32_16x16x32_bf16 v[18:21], v[176:179], v[208:211], v[18:21]
	v_mfma_f32_16x16x32_bf16 v[10:13], v[184:187], v[208:211], v[10:13]
	v_mfma_f32_16x16x32_bf16 v[6:9], v[176:179], v[216:219], v[6:9]
	v_mfma_f32_16x16x32_bf16 v[2:5], v[184:187], v[216:219], v[2:5]
	s_setprio 0
	s_barrier
	s_add_i32 s47, s47, 2
	s_add_u32 s20, s20, 0x100
	s_addc_u32 s21, s21, 0
	s_add_u32 s45, s45, 0x100
	s_addc_u32 s46, s46, 0
	s_cmp_gt_u32 s47, 29
	s_cbranch_scc0 .LBB0_537
	s_and_b64 vcc, exec, s[8:9]
	s_cbranch_vccz .LBB0_540
	s_barrier

; #define PG8_STAGE(bufoff, gbase, voff) do { _Pragma("unroll") for (int _i = 0; _i < 2; ++_i) \
;         __builtin_amdgcn_global_load_lds((const unsigned*)((const char*)(gbase) + (voff)[_i]), (PG8_LAS unsigned*)(lds + (bufoff) + ldsw + _i * 8192), 16, 0, 0); } while (0)
; #define PG8_WAIT_V(n) asm volatile("s_waitcnt vmcnt(" #n ")" ::: "memory")
; #define PG8_WAIT_L(n) asm volatile("s_waitcnt lgkmcnt(" #n ")" ::: "memory")
; #define PG8_BAR __builtin_amdgcn_s_barrier()
; #define PG8_SCHED __builtin_amdgcn_sched_barrier(0)
; template <class Epi, class Sched, bool ALIGN_EPI = true, bool SP2 = true>
; __device__ __forceinline__ void gemm_phase(PG8_LAS unsigned char* lds, const int K  , const Sched& S, const Epi& E) {
;     ...
;             PG8_LDB(B0, 0, 0); PG8_LDB(B1, 0, 1); PG8_SCHED; PG8_LDA(At, 0, 0); PG8_STAGE(PG8_SA(1, 1), a1 + hstep, voffA);
;             PG8_WAIT_V(8); PG8_WAIT_L(0); PG8_BAR; PG8_MMA(0, 0, At, B0); PG8_MMA(0, 1, At, B1); PG8_BAR; PG8_SCHED;
;             PG8_LDA(At, 0, 1); PG8_STAGE(PG8_SB(0, 0), b2, voffB); PG8_STAGE(PG8_SB(0, 1), b2 + hstep, voffB); PG8_STAGE(PG8_SA(0, 0), a2, voffA);
;             PG8_WAIT_V(8); PG8_WAIT_L(0); PG8_BAR; PG8_MMA(1, 0, At, B0); PG8_MMA(1, 1, At, B1); PG8_BAR; PG8_SCHED;
.LBB0_955:
	s_waitcnt vmcnt(0)
	ds_read_b128 v[130:133], v232
	ds_read_b128 v[134:137], v232 offset:1024
	ds_read_b128 v[138:141], v232 offset:2048
	ds_read_b128 v[142:145], v232 offset:3072
	ds_read_b128 v[146:149], v233
	ds_read_b128 v[150:153], v233 offset:1024
	ds_read_b128 v[154:157], v233 offset:2048
	ds_read_b128 v[158:161], v233 offset:3072
	s_add_i32 s73, s28, 2
	s_add_u32 s26, s24, 0xfff80080
	s_addc_u32 s27, s25, -1
	s_cmp_eq_u32 s13, s28
	s_cselect_b32 s28, s16, s26
	s_cselect_b32 s29, s17, s27
	s_cselect_b32 s27, s19, s21
	s_cselect_b32 s26, s18, s15
	v_lshl_add_u64 v[194:195], s[24:25], 0, v[214:215]
	s_add_i32 m0, s23, 0xc000
	ds_read_b128 v[162:165], v234
	ds_read_b128 v[166:169], v234 offset:1024
	ds_read_b128 v[170:173], v234 offset:2048
	ds_read_b128 v[174:177], v234 offset:3072
	ds_read_b128 v[178:181], v234 offset:4096
	ds_read_b128 v[182:185], v234 offset:5120
	ds_read_b128 v[186:189], v234 offset:6144
	ds_read_b128 v[190:193], v234 offset:7168
	global_load_lds_dwordx4 v[194:195], off
	v_lshl_add_u64 v[194:195], s[24:25], 0, v[216:217]
	s_add_i32 m0, s23, 0xe000
	s_nop 0
	global_load_lds_dwordx4 v[194:195], off
	s_waitcnt vmcnt(8)
	s_waitcnt lgkmcnt(0)
	s_barrier
	s_setprio 1
	s_waitcnt lgkmcnt(0)
	v_mfma_f32_16x16x32_bf16 v[126:129], v[130:133], v[162:165], v[126:129]
	v_mfma_f32_16x16x32_bf16 v[122:125], v[138:141], v[162:165], v[122:125]
	v_mfma_f32_16x16x32_bf16 v[118:121], v[130:133], v[170:173], v[118:121]
	v_mfma_f32_16x16x32_bf16 v[110:113], v[138:141], v[170:173], v[110:113]
	v_mfma_f32_16x16x32_bf16 v[102:105], v[130:133], v[178:181], v[102:105]
	v_mfma_f32_16x16x32_bf16 v[94:97], v[138:141], v[178:181], v[94:97]
	v_mfma_f32_16x16x32_bf16 v[86:89], v[130:133], v[186:189], v[86:89]
	v_mfma_f32_16x16x32_bf16 v[78:81], v[138:141], v[186:189], v[78:81]
	v_mfma_f32_16x16x32_bf16 v[126:129], v[134:137], v[166:169], v[126:129]
	v_mfma_f32_16x16x32_bf16 v[122:125], v[142:145], v[166:169], v[122:125]
	v_mfma_f32_16x16x32_bf16 v[118:121], v[134:137], v[174:177], v[118:121]
	v_mfma_f32_16x16x32_bf16 v[110:113], v[142:145], v[174:177], v[110:113]
	v_mfma_f32_16x16x32_bf16 v[102:105], v[134:137], v[182:185], v[102:105]
	v_mfma_f32_16x16x32_bf16 v[94:97], v[142:145], v[182:185], v[94:97]
	v_mfma_f32_16x16x32_bf16 v[86:89], v[134:137], v[190:193], v[86:89]
	v_mfma_f32_16x16x32_bf16 v[78:81], v[142:145], v[190:193], v[78:81]
	v_mfma_f32_16x16x32_bf16 v[114:117], v[146:149], v[162:165], v[114:117]
	v_mfma_f32_16x16x32_bf16 v[106:109], v[154:157], v[162:165], v[106:109]
	v_mfma_f32_16x16x32_bf16 v[98:101], v[146:149], v[170:173], v[98:101]
	v_mfma_f32_16x16x32_bf16 v[90:93], v[154:157], v[170:173], v[90:93]
	v_mfma_f32_16x16x32_bf16 v[82:85], v[146:149], v[178:181], v[82:85]
	v_mfma_f32_16x16x32_bf16 v[74:77], v[154:157], v[178:181], v[74:77]
	v_mfma_f32_16x16x32_bf16 v[70:73], v[146:149], v[186:189], v[70:73]
	v_mfma_f32_16x16x32_bf16 v[66:69], v[154:157], v[186:189], v[66:69]
	v_mfma_f32_16x16x32_bf16 v[114:117], v[150:153], v[166:169], v[114:117]
	v_mfma_f32_16x16x32_bf16 v[106:109], v[158:161], v[166:169], v[106:109]
	v_mfma_f32_16x16x32_bf16 v[98:101], v[150:153], v[174:177], v[98:101]
	v_mfma_f32_16x16x32_bf16 v[90:93], v[158:161], v[174:177], v[90:93]
	v_mfma_f32_16x16x32_bf16 v[82:85], v[150:153], v[182:185], v[82:85]
	v_mfma_f32_16x16x32_bf16 v[74:77], v[158:161], v[182:185], v[74:77]
	v_mfma_f32_16x16x32_bf16 v[70:73], v[150:153], v[190:193], v[70:73]
	v_mfma_f32_16x16x32_bf16 v[66:69], v[158:161], v[190:193], v[66:69]
	s_setprio 0
	s_barrier
	s_add_i32 s74, s47, s33
	v_lshl_add_u64 v[194:195], s[26:27], 0, v[208:209]
	s_mov_b32 m0, s74
	ds_read_b128 v[162:165], v234 offset:16384
	ds_read_b128 v[166:169], v234 offset:17408
	ds_read_b128 v[170:173], v234 offset:18432
	ds_read_b128 v[174:177], v234 offset:19456
	ds_read_b128 v[178:181], v234 offset:20480
	ds_read_b128 v[182:185], v234 offset:21504
	ds_read_b128 v[186:189], v234 offset:22528
	ds_read_b128 v[190:193], v234 offset:23552
	global_load_lds_dwordx4 v[194:195], off
	s_add_i32 m0, s74, 0x2000
	s_add_u32 s74, s26, 0x80000
	v_lshl_add_u64 v[196:197], s[26:27], 0, v[212:213]
	s_addc_u32 s75, s27, 0
	s_add_i32 s76, s48, s33
	global_load_lds_dwordx4 v[196:197], off
	v_lshl_add_u64 v[198:199], s[74:75], 0, v[208:209]
	s_mov_b32 m0, s76
	v_lshl_add_u64 v[200:201], s[28:29], 0, v[210:211]
	global_load_lds_dwordx4 v[198:199], off
	v_lshl_add_u64 v[198:199], s[74:75], 0, v[212:213]
	s_add_i32 m0, s76, 0x2000
	s_nop 0
	global_load_lds_dwordx4 v[198:199], off
	v_lshl_add_u64 v[198:199], s[28:29], 0, v[206:207]
	s_mov_b32 m0, s23
	s_nop 0
	global_load_lds_dwordx4 v[198:199], off
	s_mov_b32 m0, s34
	s_nop 0
	global_load_lds_dwordx4 v[200:201], off
	s_waitcnt vmcnt(8)
	s_waitcnt lgkmcnt(0)
	s_barrier
; #define PG8_STAGE(bufoff, gbase, voff) do { _Pragma("unroll") for (int _i = 0; _i < 2; ++_i) \
;         __builtin_amdgcn_global_load_lds((const unsigned*)((const char*)(gbase) + (voff)[_i]), (PG8_LAS unsigned*)(lds + (bufoff) + ldsw + _i * 8192), 16, 0, 0); } while (0)
; #define PG8_WAIT_V(n) asm volatile("s_waitcnt vmcnt(" #n ")" ::: "memory")
; #define PG8_WAIT_L(n) asm volatile("s_waitcnt lgkmcnt(" #n ")" ::: "memory")
; #define PG8_BAR __builtin_amdgcn_s_barrier()
; #define PG8_SCHED __builtin_amdgcn_sched_barrier(0)
; template <class Epi, class Sched, bool ALIGN_EPI = true, bool SP2 = true>
; __device__ __forceinline__ void gemm_phase(PG8_LAS unsigned char* lds, const int K  , const Sched& S, const Epi& E) {
;     ...
;             PG8_WAIT_V(8); PG8_WAIT_L(0); PG8_BAR; PG8_MMA(1, 0, At, B0); PG8_MMA(1, 1, At, B1); PG8_BAR; PG8_SCHED;
;             PG8_LDB(B0, 1, 0); PG8_LDB(B1, 1, 1); PG8_SCHED; PG8_LDA(At, 1, 0); PG8_STAGE(PG8_SA(0, 1), a2 + hstep, voffA);
;             PG8_WAIT_V(8); PG8_WAIT_L(0); PG8_BAR; PG8_MMA(0, 0, At, B0); PG8_MMA(0, 1, At, B1); PG8_BAR; PG8_SCHED;
	s_setprio 1
	s_waitcnt lgkmcnt(0)
	v_mfma_f32_16x16x32_bf16 v[62:65], v[130:133], v[162:165], v[62:65]
	v_mfma_f32_16x16x32_bf16 v[58:61], v[138:141], v[162:165], v[58:61]
	v_mfma_f32_16x16x32_bf16 v[54:57], v[130:133], v[170:173], v[54:57]
	v_mfma_f32_16x16x32_bf16 v[46:49], v[138:141], v[170:173], v[46:49]
	v_mfma_f32_16x16x32_bf16 v[38:41], v[130:133], v[178:181], v[38:41]
	v_mfma_f32_16x16x32_bf16 v[30:33], v[138:141], v[178:181], v[30:33]
	v_mfma_f32_16x16x32_bf16 v[22:25], v[130:133], v[186:189], v[22:25]
	v_mfma_f32_16x16x32_bf16 v[14:17], v[138:141], v[186:189], v[14:17]
	v_mfma_f32_16x16x32_bf16 v[62:65], v[134:137], v[166:169], v[62:65]
	v_mfma_f32_16x16x32_bf16 v[58:61], v[142:145], v[166:169], v[58:61]
	v_mfma_f32_16x16x32_bf16 v[54:57], v[134:137], v[174:177], v[54:57]
	v_mfma_f32_16x16x32_bf16 v[46:49], v[142:145], v[174:177], v[46:49]
	v_mfma_f32_16x16x32_bf16 v[38:41], v[134:137], v[182:185], v[38:41]
	v_mfma_f32_16x16x32_bf16 v[30:33], v[142:145], v[182:185], v[30:33]
	v_mfma_f32_16x16x32_bf16 v[22:25], v[134:137], v[190:193], v[22:25]
	v_mfma_f32_16x16x32_bf16 v[14:17], v[142:145], v[190:193], v[14:17]
	v_mfma_f32_16x16x32_bf16 v[50:53], v[146:149], v[162:165], v[50:53]
	v_mfma_f32_16x16x32_bf16 v[42:45], v[154:157], v[162:165], v[42:45]
	v_mfma_f32_16x16x32_bf16 v[34:37], v[146:149], v[170:173], v[34:37]
	v_mfma_f32_16x16x32_bf16 v[26:29], v[154:157], v[170:173], v[26:29]
	v_mfma_f32_16x16x32_bf16 v[18:21], v[146:149], v[178:181], v[18:21]
	v_mfma_f32_16x16x32_bf16 v[10:13], v[154:157], v[178:181], v[10:13]
	v_mfma_f32_16x16x32_bf16 v[6:9], v[146:149], v[186:189], v[6:9]
	v_mfma_f32_16x16x32_bf16 v[2:5], v[154:157], v[186:189], v[2:5]
	v_mfma_f32_16x16x32_bf16 v[50:53], v[150:153], v[166:169], v[50:53]
	v_mfma_f32_16x16x32_bf16 v[42:45], v[158:161], v[166:169], v[42:45]
	v_mfma_f32_16x16x32_bf16 v[34:37], v[150:153], v[174:177], v[34:37]
	v_mfma_f32_16x16x32_bf16 v[26:29], v[158:161], v[174:177], v[26:29]
	v_mfma_f32_16x16x32_bf16 v[18:21], v[150:153], v[182:185], v[18:21]
	v_mfma_f32_16x16x32_bf16 v[10:13], v[158:161], v[182:185], v[10:13]
	v_mfma_f32_16x16x32_bf16 v[6:9], v[150:153], v[190:193], v[6:9]
	v_mfma_f32_16x16x32_bf16 v[2:5], v[158:161], v[190:193], v[2:5]
	s_setprio 0
	s_barrier
	s_add_i32 s74, 0, 0x18000
	s_add_i32 s75, 0, 0x1c000
	v_add_u32_e32 v142, s74, v230
	v_add_u32_e32 v158, s75, v230
	ds_read_b128 v[130:133], v142
	ds_read_b128 v[134:137], v142 offset:1024
	ds_read_b128 v[138:141], v142 offset:2048
	ds_read_b128 v[142:145], v142 offset:3072
	ds_read_b128 v[146:149], v158
	ds_read_b128 v[150:153], v158 offset:1024
	ds_read_b128 v[154:157], v158 offset:2048
	ds_read_b128 v[158:161], v158 offset:3072
	s_add_u32 s28, s28, 0x80000
	s_addc_u32 s29, s29, 0
	s_mov_b32 m0, s35
	v_lshl_add_u64 v[202:203], s[28:29], 0, v[206:207]
	ds_read_b128 v[162:165], v234 offset:32768
	ds_read_b128 v[166:169], v234 offset:33792
	ds_read_b128 v[170:173], v234 offset:34816
	ds_read_b128 v[174:177], v234 offset:35840
	ds_read_b128 v[178:181], v234 offset:36864
	ds_read_b128 v[182:185], v234 offset:37888
	ds_read_b128 v[186:189], v234 offset:38912
	ds_read_b128 v[190:193], v234 offset:39936
	global_load_lds_dwordx4 v[202:203], off
	v_lshl_add_u64 v[202:203], s[28:29], 0, v[210:211]
	s_mov_b32 m0, s36
	s_nop 0
	global_load_lds_dwordx4 v[202:203], off
	s_waitcnt vmcnt(8)
	s_waitcnt lgkmcnt(0)
	s_barrier
	s_setprio 1
	s_waitcnt lgkmcnt(0)
	v_mfma_f32_16x16x32_bf16 v[126:129], v[130:133], v[162:165], v[126:129]
	v_mfma_f32_16x16x32_bf16 v[122:125], v[138:141], v[162:165], v[122:125]
	v_mfma_f32_16x16x32_bf16 v[118:121], v[130:133], v[170:173], v[118:121]
	v_mfma_f32_16x16x32_bf16 v[110:113], v[138:141], v[170:173], v[110:113]
	v_mfma_f32_16x16x32_bf16 v[102:105], v[130:133], v[178:181], v[102:105]
	v_mfma_f32_16x16x32_bf16 v[94:97], v[138:141], v[178:181], v[94:97]
	v_mfma_f32_16x16x32_bf16 v[86:89], v[130:133], v[186:189], v[86:89]
	v_mfma_f32_16x16x32_bf16 v[78:81], v[138:141], v[186:189], v[78:81]
	v_mfma_f32_16x16x32_bf16 v[126:129], v[134:137], v[166:169], v[126:129]
	v_mfma_f32_16x16x32_bf16 v[122:125], v[142:145], v[166:169], v[122:125]
	v_mfma_f32_16x16x32_bf16 v[118:121], v[134:137], v[174:177], v[118:121]
	v_mfma_f32_16x16x32_bf16 v[110:113], v[142:145], v[174:177], v[110:113]
	v_mfma_f32_16x16x32_bf16 v[102:105], v[134:137], v[182:185], v[102:105]
	v_mfma_f32_16x16x32_bf16 v[94:97], v[142:145], v[182:185], v[94:97]
	v_mfma_f32_16x16x32_bf16 v[86:89], v[134:137], v[190:193], v[86:89]
	v_mfma_f32_16x16x32_bf16 v[78:81], v[142:145], v[190:193], v[78:81]
	v_mfma_f32_16x16x32_bf16 v[114:117], v[146:149], v[162:165], v[114:117]
	v_mfma_f32_16x16x32_bf16 v[106:109], v[154:157], v[162:165], v[106:109]
	v_mfma_f32_16x16x32_bf16 v[98:101], v[146:149], v[170:173], v[98:101]
	v_mfma_f32_16x16x32_bf16 v[90:93], v[154:157], v[170:173], v[90:93]
	v_mfma_f32_16x16x32_bf16 v[82:85], v[146:149], v[178:181], v[82:85]
	v_mfma_f32_16x16x32_bf16 v[74:77], v[154:157], v[178:181], v[74:77]
	v_mfma_f32_16x16x32_bf16 v[70:73], v[146:149], v[186:189], v[70:73]
	v_mfma_f32_16x16x32_bf16 v[66:69], v[154:157], v[186:189], v[66:69]
	v_mfma_f32_16x16x32_bf16 v[114:117], v[150:153], v[166:169], v[114:117]
	v_mfma_f32_16x16x32_bf16 v[106:109], v[158:161], v[166:169], v[106:109]
	v_mfma_f32_16x16x32_bf16 v[98:101], v[150:153], v[174:177], v[98:101]
	v_mfma_f32_16x16x32_bf16 v[90:93], v[158:161], v[174:177], v[90:93]
	v_mfma_f32_16x16x32_bf16 v[82:85], v[150:153], v[182:185], v[82:85]
	v_mfma_f32_16x16x32_bf16 v[74:77], v[158:161], v[182:185], v[74:77]
	v_mfma_f32_16x16x32_bf16 v[70:73], v[150:153], v[190:193], v[70:73]
	v_mfma_f32_16x16x32_bf16 v[66:69], v[158:161], v[190:193], v[66:69]
	s_setprio 0
	s_barrier
; #define PG8_STAGE(bufoff, gbase, voff) do { _Pragma("unroll") for (int _i = 0; _i < 2; ++_i) \
;         __builtin_amdgcn_global_load_lds((const unsigned*)((const char*)(gbase) + (voff)[_i]), (PG8_LAS unsigned*)(lds + (bufoff) + ldsw + _i * 8192), 16, 0, 0); } while (0)
; #define PG8_WAIT_V(n) asm volatile("s_waitcnt vmcnt(" #n ")" ::: "memory")
; #define PG8_WAIT_L(n) asm volatile("s_waitcnt lgkmcnt(" #n ")" ::: "memory")
; #define PG8_BAR __builtin_amdgcn_s_barrier()
; #define PG8_SCHED __builtin_amdgcn_sched_barrier(0)
;     __device__ __forceinline__ int nt(const pg8::Unit& u) const { return u.kind == 0 ? ntiles : q_nt(u.kind - 1); }
; template <class Epi, class Sched, bool ALIGN_EPI = true, bool SP2 = true>
; __device__ __forceinline__ void gemm_phase(PG8_LAS unsigned char* lds, const int K  , const Sched& S, const Epi& E) {
;     ...
;         for (int t = 0; t < nt; t += 2) {
;     ...
;             PG8_LDA(At, 1, 1); PG8_STAGE(PG8_SB(1, 0), b3, voffB); PG8_STAGE(PG8_SB(1, 1), b3 + hstep, voffB); PG8_STAGE(PG8_SA(1, 0), a3, voffA);
;             PG8_WAIT_V(8); PG8_WAIT_L(0); PG8_BAR; PG8_MMA(1, 0, At, B0); PG8_MMA(1, 1, At, B1); PG8_BAR; PG8_SCHED;
;     ...
;         if constexpr (Epi::FP8) asm volatile("s_nop 15\n\ts_nop 15\n\ts_nop 15\n\ts_nop 15\n\ts_nop 15" ::: "memory");
;         if constexpr (ALIGN_EPI) { if (wr == 0) PG8_BAR; }
	s_add_i32 s28, s74, s33
	v_lshl_add_u64 v[194:195], v[194:195], 0, s[8:9]
	s_mov_b32 m0, s28
	ds_read_b128 v[162:165], v234 offset:49152
	ds_read_b128 v[166:169], v234 offset:50176
	ds_read_b128 v[170:173], v234 offset:51200
	ds_read_b128 v[174:177], v234 offset:52224
	ds_read_b128 v[178:181], v234 offset:53248
	ds_read_b128 v[182:185], v234 offset:54272
	ds_read_b128 v[186:189], v234 offset:55296
	ds_read_b128 v[190:193], v234 offset:56320
	global_load_lds_dwordx4 v[194:195], off
	s_add_i32 m0, s28, 0x2000
	s_add_u32 s26, s26, 0x80080
	v_lshl_add_u64 v[194:195], v[196:197], 0, s[8:9]
	s_addc_u32 s27, s27, 0
	s_add_i32 s28, s75, s33
	global_load_lds_dwordx4 v[194:195], off
	v_lshl_add_u64 v[194:195], s[26:27], 0, v[208:209]
	s_mov_b32 m0, s28
	s_nop 0
	global_load_lds_dwordx4 v[194:195], off
	v_lshl_add_u64 v[194:195], s[26:27], 0, v[212:213]
	s_add_i32 m0, s28, 0x2000
	s_nop 0
	global_load_lds_dwordx4 v[194:195], off
	v_lshl_add_u64 v[194:195], v[198:199], 0, s[8:9]
	s_mov_b32 m0, s42
	s_nop 0
	global_load_lds_dwordx4 v[194:195], off
	v_lshl_add_u64 v[194:195], v[200:201], 0, s[8:9]
	s_mov_b32 m0, s43
	s_nop 0
	global_load_lds_dwordx4 v[194:195], off
	s_waitcnt vmcnt(8)
	s_waitcnt lgkmcnt(0)
	s_barrier
	s_setprio 1
	s_waitcnt lgkmcnt(0)
	v_mfma_f32_16x16x32_bf16 v[62:65], v[130:133], v[162:165], v[62:65]
	v_mfma_f32_16x16x32_bf16 v[58:61], v[138:141], v[162:165], v[58:61]
	v_mfma_f32_16x16x32_bf16 v[54:57], v[130:133], v[170:173], v[54:57]
	v_mfma_f32_16x16x32_bf16 v[46:49], v[138:141], v[170:173], v[46:49]
	v_mfma_f32_16x16x32_bf16 v[38:41], v[130:133], v[178:181], v[38:41]
	v_mfma_f32_16x16x32_bf16 v[30:33], v[138:141], v[178:181], v[30:33]
	v_mfma_f32_16x16x32_bf16 v[22:25], v[130:133], v[186:189], v[22:25]
	v_mfma_f32_16x16x32_bf16 v[14:17], v[138:141], v[186:189], v[14:17]
	v_mfma_f32_16x16x32_bf16 v[62:65], v[134:137], v[166:169], v[62:65]
	v_mfma_f32_16x16x32_bf16 v[58:61], v[142:145], v[166:169], v[58:61]
	v_mfma_f32_16x16x32_bf16 v[54:57], v[134:137], v[174:177], v[54:57]
	v_mfma_f32_16x16x32_bf16 v[46:49], v[142:145], v[174:177], v[46:49]
	v_mfma_f32_16x16x32_bf16 v[38:41], v[134:137], v[182:185], v[38:41]
	v_mfma_f32_16x16x32_bf16 v[30:33], v[142:145], v[182:185], v[30:33]
	v_mfma_f32_16x16x32_bf16 v[22:25], v[134:137], v[190:193], v[22:25]
	v_mfma_f32_16x16x32_bf16 v[14:17], v[142:145], v[190:193], v[14:17]
	v_mfma_f32_16x16x32_bf16 v[50:53], v[146:149], v[162:165], v[50:53]
	v_mfma_f32_16x16x32_bf16 v[42:45], v[154:157], v[162:165], v[42:45]
	v_mfma_f32_16x16x32_bf16 v[34:37], v[146:149], v[170:173], v[34:37]
	v_mfma_f32_16x16x32_bf16 v[26:29], v[154:157], v[170:173], v[26:29]
	v_mfma_f32_16x16x32_bf16 v[18:21], v[146:149], v[178:181], v[18:21]
	v_mfma_f32_16x16x32_bf16 v[10:13], v[154:157], v[178:181], v[10:13]
	v_mfma_f32_16x16x32_bf16 v[6:9], v[146:149], v[186:189], v[6:9]
	v_mfma_f32_16x16x32_bf16 v[2:5], v[154:157], v[186:189], v[2:5]
	v_mfma_f32_16x16x32_bf16 v[50:53], v[150:153], v[166:169], v[50:53]
	v_mfma_f32_16x16x32_bf16 v[42:45], v[158:161], v[166:169], v[42:45]
	v_mfma_f32_16x16x32_bf16 v[34:37], v[150:153], v[174:177], v[34:37]
	v_mfma_f32_16x16x32_bf16 v[26:29], v[158:161], v[174:177], v[26:29]
	v_mfma_f32_16x16x32_bf16 v[18:21], v[150:153], v[182:185], v[18:21]
	v_mfma_f32_16x16x32_bf16 v[10:13], v[158:161], v[182:185], v[10:13]
	v_mfma_f32_16x16x32_bf16 v[6:9], v[150:153], v[190:193], v[6:9]
	v_mfma_f32_16x16x32_bf16 v[2:5], v[158:161], v[190:193], v[2:5]
	s_setprio 0
	s_barrier
	s_add_u32 s24, s24, 0x100
	s_addc_u32 s25, s25, 0
	s_add_u32 s15, s15, 0x100
	s_addc_u32 s21, s21, 0
	s_cmp_ge_u32 s73, s4
	s_mov_b32 s28, s73
	s_cbranch_scc0 .LBB0_955
	s_and_b64 vcc, exec, s[10:11]
	s_cbranch_vccz .LBB0_958
	s_barrier

; #define PG8_STAGE(bufoff, gbase, voff) do { _Pragma("unroll") for (int _i = 0; _i < 2; ++_i) \
;         __builtin_amdgcn_global_load_lds((const unsigned*)((const char*)(gbase) + (voff)[_i]), (PG8_LAS unsigned*)(lds + (bufoff) + ldsw + _i * 8192), 16, 0, 0); } while (0)
; #define PG8_WAIT_V(n) asm volatile("s_waitcnt vmcnt(" #n ")" ::: "memory")
; #define PG8_WAIT_L(n) asm volatile("s_waitcnt lgkmcnt(" #n ")" ::: "memory")
; #define PG8_BAR __builtin_amdgcn_s_barrier()
; #define PG8_SCHED __builtin_amdgcn_sched_barrier(0)
; template <class Epi, class Sched, bool ALIGN_EPI = true, bool SP2 = true>
; __device__ __forceinline__ void gemm_phase(PG8_LAS unsigned char* lds, const int K  , const Sched& S, const Epi& E) {
;     ...
;             PG8_LDB(B0, 0, 0); PG8_LDB(B1, 0, 1); PG8_SCHED; PG8_LDA(At, 0, 0); PG8_STAGE(PG8_SA(1, 1), a1 + hstep, voffA);
;             PG8_WAIT_V(8); PG8_WAIT_L(0); PG8_BAR; PG8_MMA(0, 0, At, B0); PG8_MMA(0, 1, At, B1); PG8_BAR; PG8_SCHED;
;             PG8_LDA(At, 0, 1); PG8_STAGE(PG8_SB(0, 0), b2, voffB); PG8_STAGE(PG8_SB(0, 1), b2 + hstep, voffB); PG8_STAGE(PG8_SA(0, 0), a2, voffA);
;             PG8_WAIT_V(8); PG8_WAIT_L(0); PG8_BAR; PG8_MMA(1, 0, At, B0); PG8_MMA(1, 1, At, B1); PG8_BAR; PG8_SCHED;
.LBB0_1099:
	ds_read_b128 v[148:151], v154
	ds_read_b128 v[160:163], v154 offset:1024
	ds_read_b128 v[164:167], v154 offset:2048
	ds_read_b128 v[168:171], v154 offset:3072
	ds_read_b128 v[172:175], v155
	ds_read_b128 v[176:179], v155 offset:1024
	ds_read_b128 v[180:183], v155 offset:2048
	ds_read_b128 v[184:187], v155 offset:3072
	s_add_u32 s24, s22, 0xfff80080
	s_addc_u32 s25, s23, -1
	s_cmp_eq_u32 s48, 28
	s_cselect_b32 s27, s15, s25
	s_cselect_b32 s26, s44, s24
	s_cselect_b32 s25, s11, s47
	s_cselect_b32 s24, s45, s46
	v_lshl_add_u64 v[220:221], s[22:23], 0, v[140:141]
	s_add_i32 m0, s21, 0xc000
	ds_read_b128 v[188:191], v156
	ds_read_b128 v[192:195], v156 offset:1024
	ds_read_b128 v[196:199], v156 offset:2048
	ds_read_b128 v[200:203], v156 offset:3072
	ds_read_b128 v[204:207], v156 offset:4096
	ds_read_b128 v[208:211], v156 offset:5120
	ds_read_b128 v[212:215], v156 offset:6144
	ds_read_b128 v[216:219], v156 offset:7168
	global_load_lds_dwordx4 v[220:221], off
	v_lshl_add_u64 v[220:221], s[22:23], 0, v[142:143]
	s_add_i32 m0, s21, 0xe000
	s_nop 0
	global_load_lds_dwordx4 v[220:221], off
	s_waitcnt vmcnt(8)
	s_waitcnt lgkmcnt(0)
	s_barrier
	s_setprio 1
	s_waitcnt lgkmcnt(0)
	v_mfma_f32_16x16x32_bf16 v[126:129], v[148:151], v[188:191], v[126:129]
	v_mfma_f32_16x16x32_bf16 v[118:121], v[164:167], v[188:191], v[118:121]
	v_mfma_f32_16x16x32_bf16 v[110:113], v[148:151], v[196:199], v[110:113]
	v_mfma_f32_16x16x32_bf16 v[102:105], v[164:167], v[196:199], v[102:105]
	v_mfma_f32_16x16x32_bf16 v[94:97], v[148:151], v[204:207], v[94:97]
	v_mfma_f32_16x16x32_bf16 v[86:89], v[164:167], v[204:207], v[86:89]
	v_mfma_f32_16x16x32_bf16 v[78:81], v[148:151], v[212:215], v[78:81]
	v_mfma_f32_16x16x32_bf16 v[70:73], v[164:167], v[212:215], v[70:73]
	v_mfma_f32_16x16x32_bf16 v[126:129], v[160:163], v[192:195], v[126:129]
	v_mfma_f32_16x16x32_bf16 v[118:121], v[168:171], v[192:195], v[118:121]
	v_mfma_f32_16x16x32_bf16 v[110:113], v[160:163], v[200:203], v[110:113]
	v_mfma_f32_16x16x32_bf16 v[102:105], v[168:171], v[200:203], v[102:105]
	v_mfma_f32_16x16x32_bf16 v[94:97], v[160:163], v[208:211], v[94:97]
	v_mfma_f32_16x16x32_bf16 v[86:89], v[168:171], v[208:211], v[86:89]
	v_mfma_f32_16x16x32_bf16 v[78:81], v[160:163], v[216:219], v[78:81]
	v_mfma_f32_16x16x32_bf16 v[70:73], v[168:171], v[216:219], v[70:73]
	v_mfma_f32_16x16x32_bf16 v[122:125], v[172:175], v[188:191], v[122:125]
	v_mfma_f32_16x16x32_bf16 v[114:117], v[180:183], v[188:191], v[114:117]
	v_mfma_f32_16x16x32_bf16 v[106:109], v[172:175], v[196:199], v[106:109]
	v_mfma_f32_16x16x32_bf16 v[98:101], v[180:183], v[196:199], v[98:101]
	v_mfma_f32_16x16x32_bf16 v[90:93], v[172:175], v[204:207], v[90:93]
	v_mfma_f32_16x16x32_bf16 v[82:85], v[180:183], v[204:207], v[82:85]
	v_mfma_f32_16x16x32_bf16 v[74:77], v[172:175], v[212:215], v[74:77]
	v_mfma_f32_16x16x32_bf16 v[66:69], v[180:183], v[212:215], v[66:69]
	v_mfma_f32_16x16x32_bf16 v[122:125], v[176:179], v[192:195], v[122:125]
	v_mfma_f32_16x16x32_bf16 v[114:117], v[184:187], v[192:195], v[114:117]
	v_mfma_f32_16x16x32_bf16 v[106:109], v[176:179], v[200:203], v[106:109]
	v_mfma_f32_16x16x32_bf16 v[98:101], v[184:187], v[200:203], v[98:101]
	v_mfma_f32_16x16x32_bf16 v[90:93], v[176:179], v[208:211], v[90:93]
	v_mfma_f32_16x16x32_bf16 v[82:85], v[184:187], v[208:211], v[82:85]
	v_mfma_f32_16x16x32_bf16 v[74:77], v[176:179], v[216:219], v[74:77]
	v_mfma_f32_16x16x32_bf16 v[66:69], v[184:187], v[216:219], v[66:69]
	s_setprio 0
	s_barrier
	s_add_i32 s49, s39, s29
	v_lshl_add_u64 v[220:221], s[24:25], 0, v[136:137]
	s_mov_b32 m0, s49
	ds_read_b128 v[188:191], v156 offset:16384
	ds_read_b128 v[192:195], v156 offset:17408
	ds_read_b128 v[196:199], v156 offset:18432
	ds_read_b128 v[200:203], v156 offset:19456
	ds_read_b128 v[204:207], v156 offset:20480
	ds_read_b128 v[208:211], v156 offset:21504
	ds_read_b128 v[212:215], v156 offset:22528
	ds_read_b128 v[216:219], v156 offset:23552
	global_load_lds_dwordx4 v[220:221], off
	s_add_i32 m0, s49, 0x2000
	s_add_u32 s50, s24, 0x80000
	v_lshl_add_u64 v[222:223], s[24:25], 0, v[132:133]
	s_addc_u32 s51, s25, 0
	s_add_i32 s49, s40, s29
	global_load_lds_dwordx4 v[222:223], off
	v_lshl_add_u64 v[224:225], s[50:51], 0, v[136:137]
	s_mov_b32 m0, s49
	v_lshl_add_u64 v[226:227], s[26:27], 0, v[134:135]
	global_load_lds_dwordx4 v[224:225], off
	v_lshl_add_u64 v[224:225], s[50:51], 0, v[132:133]
	s_add_i32 m0, s49, 0x2000
	s_nop 0
	global_load_lds_dwordx4 v[224:225], off
	v_lshl_add_u64 v[224:225], s[26:27], 0, v[138:139]
	s_mov_b32 m0, s21
	s_nop 0
	global_load_lds_dwordx4 v[224:225], off
	s_mov_b32 m0, s31
	s_nop 0
	global_load_lds_dwordx4 v[226:227], off
	s_waitcnt vmcnt(8)
	s_waitcnt lgkmcnt(0)
	s_barrier
; #define PG8_STAGE(bufoff, gbase, voff) do { _Pragma("unroll") for (int _i = 0; _i < 2; ++_i) \
;         __builtin_amdgcn_global_load_lds((const unsigned*)((const char*)(gbase) + (voff)[_i]), (PG8_LAS unsigned*)(lds + (bufoff) + ldsw + _i * 8192), 16, 0, 0); } while (0)
; #define PG8_WAIT_V(n) asm volatile("s_waitcnt vmcnt(" #n ")" ::: "memory")
; #define PG8_WAIT_L(n) asm volatile("s_waitcnt lgkmcnt(" #n ")" ::: "memory")
; #define PG8_BAR __builtin_amdgcn_s_barrier()
; #define PG8_SCHED __builtin_amdgcn_sched_barrier(0)
; template <class Epi, class Sched, bool ALIGN_EPI = true, bool SP2 = true>
; __device__ __forceinline__ void gemm_phase(PG8_LAS unsigned char* lds, const int K  , const Sched& S, const Epi& E) {
;     ...
;             PG8_WAIT_V(8); PG8_WAIT_L(0); PG8_BAR; PG8_MMA(1, 0, At, B0); PG8_MMA(1, 1, At, B1); PG8_BAR; PG8_SCHED;
;             PG8_LDB(B0, 1, 0); PG8_LDB(B1, 1, 1); PG8_SCHED; PG8_LDA(At, 1, 0); PG8_STAGE(PG8_SA(0, 1), a2 + hstep, voffA);
;             PG8_WAIT_V(8); PG8_WAIT_L(0); PG8_BAR; PG8_MMA(0, 0, At, B0); PG8_MMA(0, 1, At, B1); PG8_BAR; PG8_SCHED;
	s_setprio 1
	s_waitcnt lgkmcnt(0)
	v_mfma_f32_16x16x32_bf16 v[62:65], v[148:151], v[188:191], v[62:65]
	v_mfma_f32_16x16x32_bf16 v[54:57], v[164:167], v[188:191], v[54:57]
	v_mfma_f32_16x16x32_bf16 v[46:49], v[148:151], v[196:199], v[46:49]
	v_mfma_f32_16x16x32_bf16 v[38:41], v[164:167], v[196:199], v[38:41]
	v_mfma_f32_16x16x32_bf16 v[30:33], v[148:151], v[204:207], v[30:33]
	v_mfma_f32_16x16x32_bf16 v[22:25], v[164:167], v[204:207], v[22:25]
	v_mfma_f32_16x16x32_bf16 v[14:17], v[148:151], v[212:215], v[14:17]
	v_mfma_f32_16x16x32_bf16 v[6:9], v[164:167], v[212:215], v[6:9]
	v_mfma_f32_16x16x32_bf16 v[62:65], v[160:163], v[192:195], v[62:65]
	v_mfma_f32_16x16x32_bf16 v[54:57], v[168:171], v[192:195], v[54:57]
	v_mfma_f32_16x16x32_bf16 v[46:49], v[160:163], v[200:203], v[46:49]
	v_mfma_f32_16x16x32_bf16 v[38:41], v[168:171], v[200:203], v[38:41]
	v_mfma_f32_16x16x32_bf16 v[30:33], v[160:163], v[208:211], v[30:33]
	v_mfma_f32_16x16x32_bf16 v[22:25], v[168:171], v[208:211], v[22:25]
	v_mfma_f32_16x16x32_bf16 v[14:17], v[160:163], v[216:219], v[14:17]
	v_mfma_f32_16x16x32_bf16 v[6:9], v[168:171], v[216:219], v[6:9]
	v_mfma_f32_16x16x32_bf16 v[58:61], v[172:175], v[188:191], v[58:61]
	v_mfma_f32_16x16x32_bf16 v[50:53], v[180:183], v[188:191], v[50:53]
	v_mfma_f32_16x16x32_bf16 v[42:45], v[172:175], v[196:199], v[42:45]
	v_mfma_f32_16x16x32_bf16 v[34:37], v[180:183], v[196:199], v[34:37]
	v_mfma_f32_16x16x32_bf16 v[26:29], v[172:175], v[204:207], v[26:29]
	v_mfma_f32_16x16x32_bf16 v[18:21], v[180:183], v[204:207], v[18:21]
	v_mfma_f32_16x16x32_bf16 v[10:13], v[172:175], v[212:215], v[10:13]
	v_mfma_f32_16x16x32_bf16 v[2:5], v[180:183], v[212:215], v[2:5]
	v_mfma_f32_16x16x32_bf16 v[58:61], v[176:179], v[192:195], v[58:61]
	v_mfma_f32_16x16x32_bf16 v[50:53], v[184:187], v[192:195], v[50:53]
	v_mfma_f32_16x16x32_bf16 v[42:45], v[176:179], v[200:203], v[42:45]
	v_mfma_f32_16x16x32_bf16 v[34:37], v[184:187], v[200:203], v[34:37]
	v_mfma_f32_16x16x32_bf16 v[26:29], v[176:179], v[208:211], v[26:29]
	v_mfma_f32_16x16x32_bf16 v[18:21], v[184:187], v[208:211], v[18:21]
	v_mfma_f32_16x16x32_bf16 v[10:13], v[176:179], v[216:219], v[10:13]
	v_mfma_f32_16x16x32_bf16 v[2:5], v[184:187], v[216:219], v[2:5]
	s_setprio 0
	s_barrier
	s_add_i32 s49, 0, 0x18000
	v_add_u32_e32 v159, s49, v152
	s_add_i32 s50, 0, 0x1c000
	ds_read_b128 v[148:151], v159
	ds_read_b128 v[160:163], v159 offset:1024
	ds_read_b128 v[164:167], v159 offset:2048
	ds_read_b128 v[168:171], v159 offset:3072
	v_add_u32_e32 v159, s50, v152
	ds_read_b128 v[172:175], v159
	ds_read_b128 v[176:179], v159 offset:1024
	ds_read_b128 v[180:183], v159 offset:2048
	ds_read_b128 v[184:187], v159 offset:3072
	s_add_u32 s26, s26, 0x80000
	s_addc_u32 s27, s27, 0
	s_mov_b32 m0, s33
	v_lshl_add_u64 v[230:231], s[26:27], 0, v[138:139]
	ds_read_b128 v[188:191], v156 offset:32768
	ds_read_b128 v[192:195], v156 offset:33792
	ds_read_b128 v[196:199], v156 offset:34816
	ds_read_b128 v[200:203], v156 offset:35840
	ds_read_b128 v[204:207], v156 offset:36864
	ds_read_b128 v[208:211], v156 offset:37888
	ds_read_b128 v[212:215], v156 offset:38912
	ds_read_b128 v[216:219], v156 offset:39936
	global_load_lds_dwordx4 v[230:231], off
	v_lshl_add_u64 v[230:231], s[26:27], 0, v[134:135]
	s_mov_b32 m0, s34
	s_nop 0
	global_load_lds_dwordx4 v[230:231], off
	s_waitcnt vmcnt(8)
	s_waitcnt lgkmcnt(0)
	s_barrier
	s_setprio 1
	s_waitcnt lgkmcnt(0)
	v_mfma_f32_16x16x32_bf16 v[126:129], v[148:151], v[188:191], v[126:129]
	v_mfma_f32_16x16x32_bf16 v[118:121], v[164:167], v[188:191], v[118:121]
	v_mfma_f32_16x16x32_bf16 v[110:113], v[148:151], v[196:199], v[110:113]
	v_mfma_f32_16x16x32_bf16 v[102:105], v[164:167], v[196:199], v[102:105]
	v_mfma_f32_16x16x32_bf16 v[94:97], v[148:151], v[204:207], v[94:97]
	v_mfma_f32_16x16x32_bf16 v[86:89], v[164:167], v[204:207], v[86:89]
	v_mfma_f32_16x16x32_bf16 v[78:81], v[148:151], v[212:215], v[78:81]
	v_mfma_f32_16x16x32_bf16 v[70:73], v[164:167], v[212:215], v[70:73]
	v_mfma_f32_16x16x32_bf16 v[126:129], v[160:163], v[192:195], v[126:129]
	v_mfma_f32_16x16x32_bf16 v[118:121], v[168:171], v[192:195], v[118:121]
	v_mfma_f32_16x16x32_bf16 v[110:113], v[160:163], v[200:203], v[110:113]
	v_mfma_f32_16x16x32_bf16 v[102:105], v[168:171], v[200:203], v[102:105]
	v_mfma_f32_16x16x32_bf16 v[94:97], v[160:163], v[208:211], v[94:97]
	v_mfma_f32_16x16x32_bf16 v[86:89], v[168:171], v[208:211], v[86:89]
	v_mfma_f32_16x16x32_bf16 v[78:81], v[160:163], v[216:219], v[78:81]
	v_mfma_f32_16x16x32_bf16 v[70:73], v[168:171], v[216:219], v[70:73]
	v_mfma_f32_16x16x32_bf16 v[122:125], v[172:175], v[188:191], v[122:125]
	v_mfma_f32_16x16x32_bf16 v[114:117], v[180:183], v[188:191], v[114:117]
	v_mfma_f32_16x16x32_bf16 v[106:109], v[172:175], v[196:199], v[106:109]
	v_mfma_f32_16x16x32_bf16 v[98:101], v[180:183], v[196:199], v[98:101]
	v_mfma_f32_16x16x32_bf16 v[90:93], v[172:175], v[204:207], v[90:93]
	v_mfma_f32_16x16x32_bf16 v[82:85], v[180:183], v[204:207], v[82:85]
	v_mfma_f32_16x16x32_bf16 v[74:77], v[172:175], v[212:215], v[74:77]
	v_mfma_f32_16x16x32_bf16 v[66:69], v[180:183], v[212:215], v[66:69]
	v_mfma_f32_16x16x32_bf16 v[122:125], v[176:179], v[192:195], v[122:125]
	v_mfma_f32_16x16x32_bf16 v[114:117], v[184:187], v[192:195], v[114:117]
	v_mfma_f32_16x16x32_bf16 v[106:109], v[176:179], v[200:203], v[106:109]
	v_mfma_f32_16x16x32_bf16 v[98:101], v[184:187], v[200:203], v[98:101]
	v_mfma_f32_16x16x32_bf16 v[90:93], v[176:179], v[208:211], v[90:93]
	v_mfma_f32_16x16x32_bf16 v[82:85], v[184:187], v[208:211], v[82:85]
	v_mfma_f32_16x16x32_bf16 v[74:77], v[176:179], v[216:219], v[74:77]
	v_mfma_f32_16x16x32_bf16 v[66:69], v[184:187], v[216:219], v[66:69]
	s_setprio 0
	s_barrier
; #define PG8_STAGE(bufoff, gbase, voff) do { _Pragma("unroll") for (int _i = 0; _i < 2; ++_i) \
;         __builtin_amdgcn_global_load_lds((const unsigned*)((const char*)(gbase) + (voff)[_i]), (PG8_LAS unsigned*)(lds + (bufoff) + ldsw + _i * 8192), 16, 0, 0); } while (0)
; #define PG8_WAIT_V(n) asm volatile("s_waitcnt vmcnt(" #n ")" ::: "memory")
; #define PG8_WAIT_L(n) asm volatile("s_waitcnt lgkmcnt(" #n ")" ::: "memory")
; #define PG8_BAR __builtin_amdgcn_s_barrier()
; #define PG8_SCHED __builtin_amdgcn_sched_barrier(0)
;     __device__ __forceinline__ int nt(const pg8::Unit& u) const { return u.kind == 0 ? ntiles : q_nt(u.kind - 1); }
; template <class Epi, class Sched, bool ALIGN_EPI = true, bool SP2 = true>
; __device__ __forceinline__ void gemm_phase(PG8_LAS unsigned char* lds, const int K  , const Sched& S, const Epi& E) {
;     ...
;         for (int t = 0; t < nt; t += 2) {
;     ...
;             PG8_LDA(At, 1, 1); PG8_STAGE(PG8_SB(1, 0), b3, voffB); PG8_STAGE(PG8_SB(1, 1), b3 + hstep, voffB); PG8_STAGE(PG8_SA(1, 0), a3, voffA);
;             PG8_WAIT_V(8); PG8_WAIT_L(0); PG8_BAR; PG8_MMA(1, 0, At, B0); PG8_MMA(1, 1, At, B1); PG8_BAR; PG8_SCHED;
;     ...
;         if constexpr (Epi::FP8) asm volatile("s_nop 15\n\ts_nop 15\n\ts_nop 15\n\ts_nop 15\n\ts_nop 15" ::: "memory");
;         if constexpr (ALIGN_EPI) { if (wr == 0) PG8_BAR; }
	s_add_i32 s26, s49, s29
	v_lshl_add_u64 v[220:221], v[220:221], 0, s[4:5]
	s_mov_b32 m0, s26
	ds_read_b128 v[188:191], v156 offset:49152
	ds_read_b128 v[192:195], v156 offset:50176
	ds_read_b128 v[196:199], v156 offset:51200
	ds_read_b128 v[200:203], v156 offset:52224
	ds_read_b128 v[204:207], v156 offset:53248
	ds_read_b128 v[208:211], v156 offset:54272
	ds_read_b128 v[212:215], v156 offset:55296
	ds_read_b128 v[216:219], v156 offset:56320
	global_load_lds_dwordx4 v[220:221], off
	s_add_i32 m0, s26, 0x2000
	s_add_u32 s24, s24, 0x80080
	v_lshl_add_u64 v[220:221], v[222:223], 0, s[4:5]
	s_addc_u32 s25, s25, 0
	s_add_i32 s26, s50, s29
	global_load_lds_dwordx4 v[220:221], off
	v_lshl_add_u64 v[220:221], s[24:25], 0, v[136:137]
	s_mov_b32 m0, s26
	s_nop 0
	global_load_lds_dwordx4 v[220:221], off
	v_lshl_add_u64 v[220:221], s[24:25], 0, v[132:133]
	s_add_i32 m0, s26, 0x2000
	s_nop 0
	global_load_lds_dwordx4 v[220:221], off
	v_lshl_add_u64 v[220:221], v[224:225], 0, s[4:5]
	s_mov_b32 m0, s36
	s_nop 0
	global_load_lds_dwordx4 v[220:221], off
	v_lshl_add_u64 v[220:221], v[226:227], 0, s[4:5]
	s_mov_b32 m0, s37
	s_nop 0
	global_load_lds_dwordx4 v[220:221], off
	s_waitcnt vmcnt(8)
	s_waitcnt lgkmcnt(0)
	s_barrier
	s_setprio 1
	s_waitcnt lgkmcnt(0)
	v_mfma_f32_16x16x32_bf16 v[62:65], v[148:151], v[188:191], v[62:65]
	v_mfma_f32_16x16x32_bf16 v[54:57], v[164:167], v[188:191], v[54:57]
	v_mfma_f32_16x16x32_bf16 v[46:49], v[148:151], v[196:199], v[46:49]
	v_mfma_f32_16x16x32_bf16 v[38:41], v[164:167], v[196:199], v[38:41]
	v_mfma_f32_16x16x32_bf16 v[30:33], v[148:151], v[204:207], v[30:33]
	v_mfma_f32_16x16x32_bf16 v[22:25], v[164:167], v[204:207], v[22:25]
	v_mfma_f32_16x16x32_bf16 v[14:17], v[148:151], v[212:215], v[14:17]
	v_mfma_f32_16x16x32_bf16 v[6:9], v[164:167], v[212:215], v[6:9]
	v_mfma_f32_16x16x32_bf16 v[62:65], v[160:163], v[192:195], v[62:65]
	v_mfma_f32_16x16x32_bf16 v[54:57], v[168:171], v[192:195], v[54:57]
	v_mfma_f32_16x16x32_bf16 v[46:49], v[160:163], v[200:203], v[46:49]
	v_mfma_f32_16x16x32_bf16 v[38:41], v[168:171], v[200:203], v[38:41]
	v_mfma_f32_16x16x32_bf16 v[30:33], v[160:163], v[208:211], v[30:33]
	v_mfma_f32_16x16x32_bf16 v[22:25], v[168:171], v[208:211], v[22:25]
	v_mfma_f32_16x16x32_bf16 v[14:17], v[160:163], v[216:219], v[14:17]
	v_mfma_f32_16x16x32_bf16 v[6:9], v[168:171], v[216:219], v[6:9]
	v_mfma_f32_16x16x32_bf16 v[58:61], v[172:175], v[188:191], v[58:61]
	v_mfma_f32_16x16x32_bf16 v[50:53], v[180:183], v[188:191], v[50:53]
	v_mfma_f32_16x16x32_bf16 v[42:45], v[172:175], v[196:199], v[42:45]
	v_mfma_f32_16x16x32_bf16 v[34:37], v[180:183], v[196:199], v[34:37]
	v_mfma_f32_16x16x32_bf16 v[26:29], v[172:175], v[204:207], v[26:29]
	v_mfma_f32_16x16x32_bf16 v[18:21], v[180:183], v[204:207], v[18:21]
	v_mfma_f32_16x16x32_bf16 v[10:13], v[172:175], v[212:215], v[10:13]
	v_mfma_f32_16x16x32_bf16 v[2:5], v[180:183], v[212:215], v[2:5]
	v_mfma_f32_16x16x32_bf16 v[58:61], v[176:179], v[192:195], v[58:61]
	v_mfma_f32_16x16x32_bf16 v[50:53], v[184:187], v[192:195], v[50:53]
	v_mfma_f32_16x16x32_bf16 v[42:45], v[176:179], v[200:203], v[42:45]
	v_mfma_f32_16x16x32_bf16 v[34:37], v[184:187], v[200:203], v[34:37]
	v_mfma_f32_16x16x32_bf16 v[26:29], v[176:179], v[208:211], v[26:29]
	v_mfma_f32_16x16x32_bf16 v[18:21], v[184:187], v[208:211], v[18:21]
	v_mfma_f32_16x16x32_bf16 v[10:13], v[176:179], v[216:219], v[10:13]
	v_mfma_f32_16x16x32_bf16 v[2:5], v[184:187], v[216:219], v[2:5]
	s_setprio 0
	s_barrier
	s_add_i32 s48, s48, 2
	s_add_u32 s22, s22, 0x100
	s_addc_u32 s23, s23, 0
	s_add_u32 s46, s46, 0x100
	s_addc_u32 s47, s47, 0
	s_cmp_gt_u32 s48, 29
	s_cbranch_scc0 .LBB0_1099
	s_and_b64 vcc, exec, s[8:9]
	s_cbranch_vccz .LBB0_1102
	s_barrier

; #define PG8_STAGE(bufoff, gbase, voff) do { _Pragma("unroll") for (int _i = 0; _i < 2; ++_i) \
;         __builtin_amdgcn_global_load_lds((const unsigned*)((const char*)(gbase) + (voff)[_i]), (PG8_LAS unsigned*)(lds + (bufoff) + ldsw + _i * 8192), 16, 0, 0); } while (0)
; #define PG8_WAIT_V(n) asm volatile("s_waitcnt vmcnt(" #n ")" ::: "memory")
; #define PG8_WAIT_L(n) asm volatile("s_waitcnt lgkmcnt(" #n ")" ::: "memory")
; #define PG8_BAR __builtin_amdgcn_s_barrier()
; #define PG8_SCHED __builtin_amdgcn_sched_barrier(0)
; template <class Epi, class Sched, bool ALIGN_EPI = true, bool SP2 = true>
; __device__ __forceinline__ void gemm_phase(PG8_LAS unsigned char* lds, const int K  , const Sched& S, const Epi& E) {
;     ...
;             PG8_LDB(B0, 0, 0); PG8_LDB(B1, 0, 1); PG8_SCHED; PG8_LDA(At, 0, 0); PG8_STAGE(PG8_SA(1, 1), a1 + hstep, voffA);
;             PG8_WAIT_V(8); PG8_WAIT_L(0); PG8_BAR; PG8_MMA(0, 0, At, B0); PG8_MMA(0, 1, At, B1); PG8_BAR; PG8_SCHED;
;             PG8_LDA(At, 0, 1); PG8_STAGE(PG8_SB(0, 0), b2, voffB); PG8_STAGE(PG8_SB(0, 1), b2 + hstep, voffB); PG8_STAGE(PG8_SA(0, 0), a2, voffA);
;             PG8_WAIT_V(8); PG8_WAIT_L(0); PG8_BAR; PG8_MMA(1, 0, At, B0); PG8_MMA(1, 1, At, B1); PG8_BAR; PG8_SCHED;
.LBB0_1304:
	ds_read_b128 v[18:21], v233
	ds_read_b128 v[22:25], v233 offset:1024
	ds_read_b128 v[26:29], v233 offset:2048
	ds_read_b128 v[30:33], v233 offset:3072
	ds_read_b128 v[2:5], v234
	ds_read_b128 v[6:9], v234 offset:1024
	ds_read_b128 v[10:13], v234 offset:2048
	ds_read_b128 v[14:17], v234 offset:3072
	s_add_i32 s74, s22, 2
	s_add_u32 s20, s18, 0xfff50080
	s_addc_u32 s21, s19, -1
	s_cmp_eq_u32 s71, s22
	s_cselect_b32 s22, s14, s20
	s_cselect_b32 s23, s15, s21
	s_cselect_b32 s21, s17, s73
	s_cselect_b32 s20, s16, s72
	v_lshl_add_u64 v[186:187], s[18:19], 0, v[198:199]
	s_add_i32 m0, s26, 0xc000
	ds_read_b128 v[162:165], v235
	ds_read_b128 v[166:169], v235 offset:1024
	ds_read_b128 v[170:173], v235 offset:2048
	ds_read_b128 v[174:177], v235 offset:3072
	ds_read_b128 v[178:181], v235 offset:4096
	ds_read_b128 v[182:185], v235 offset:5120
	ds_read_b128 v[206:209], v235 offset:6144
	ds_read_b128 v[210:213], v235 offset:7168
	global_load_lds_dwordx4 v[186:187], off
	v_lshl_add_u64 v[186:187], s[18:19], 0, v[200:201]
	s_add_i32 m0, s26, 0xe000
	s_nop 0
	global_load_lds_dwordx4 v[186:187], off
	s_waitcnt vmcnt(8)
	s_waitcnt lgkmcnt(0)
	s_barrier
	s_setprio 1
	s_waitcnt lgkmcnt(0)
	v_mfma_scale_f32_16x16x128_f8f6f4 v[158:161], v[18:25], v[162:169], v[158:161], v229, v229 op_sel_hi:[0,0,0]
	v_mfma_scale_f32_16x16x128_f8f6f4 v[154:157], v[26:33], v[162:169], v[154:157], v229, v229 op_sel_hi:[0,0,0]
	v_mfma_scale_f32_16x16x128_f8f6f4 v[150:153], v[18:25], v[170:177], v[150:153], v229, v229 op_sel_hi:[0,0,0]
	v_mfma_scale_f32_16x16x128_f8f6f4 v[142:145], v[26:33], v[170:177], v[142:145], v229, v229 op_sel_hi:[0,0,0]
	v_mfma_scale_f32_16x16x128_f8f6f4 v[134:137], v[18:25], v[178:185], v[134:137], v229, v229 op_sel_hi:[0,0,0]
	v_mfma_scale_f32_16x16x128_f8f6f4 v[126:129], v[26:33], v[178:185], v[126:129], v229, v229 op_sel_hi:[0,0,0]
	v_mfma_scale_f32_16x16x128_f8f6f4 v[118:121], v[18:25], v[206:213], v[118:121], v229, v229 op_sel_hi:[0,0,0]
	v_mfma_scale_f32_16x16x128_f8f6f4 v[110:113], v[26:33], v[206:213], v[110:113], v229, v229 op_sel_hi:[0,0,0]
	v_mfma_scale_f32_16x16x128_f8f6f4 v[146:149], v[2:9], v[162:169], v[146:149], v229, v229 op_sel_hi:[0,0,0]
	v_mfma_scale_f32_16x16x128_f8f6f4 v[138:141], v[10:17], v[162:169], v[138:141], v229, v229 op_sel_hi:[0,0,0]
	v_mfma_scale_f32_16x16x128_f8f6f4 v[130:133], v[2:9], v[170:177], v[130:133], v229, v229 op_sel_hi:[0,0,0]
	v_mfma_scale_f32_16x16x128_f8f6f4 v[122:125], v[10:17], v[170:177], v[122:125], v229, v229 op_sel_hi:[0,0,0]
	v_mfma_scale_f32_16x16x128_f8f6f4 v[114:117], v[2:9], v[178:185], v[114:117], v229, v229 op_sel_hi:[0,0,0]
	v_mfma_scale_f32_16x16x128_f8f6f4 v[106:109], v[10:17], v[178:185], v[106:109], v229, v229 op_sel_hi:[0,0,0]
	v_mfma_scale_f32_16x16x128_f8f6f4 v[102:105], v[2:9], v[206:213], v[102:105], v229, v229 op_sel_hi:[0,0,0]
	v_mfma_scale_f32_16x16x128_f8f6f4 v[98:101], v[10:17], v[206:213], v[98:101], v229, v229 op_sel_hi:[0,0,0]
	s_setprio 0
	s_barrier
	s_add_i32 s75, s40, s25
	v_lshl_add_u64 v[162:163], s[20:21], 0, v[192:193]
	s_mov_b32 m0, s75
	ds_read_b128 v[170:173], v235 offset:16384
	ds_read_b128 v[174:177], v235 offset:17408
	ds_read_b128 v[178:181], v235 offset:18432
	ds_read_b128 v[182:185], v235 offset:19456
	ds_read_b128 v[206:209], v235 offset:20480
	ds_read_b128 v[210:213], v235 offset:21504
	ds_read_b128 v[214:217], v235 offset:22528
	ds_read_b128 v[218:221], v235 offset:23552
	global_load_lds_dwordx4 v[162:163], off
	s_add_i32 m0, s75, 0x2000
	s_add_u32 s76, s20, 0xb0000
	v_lshl_add_u64 v[164:165], s[20:21], 0, v[196:197]
	s_addc_u32 s77, s21, 0
	s_add_i32 s75, s41, s25
	global_load_lds_dwordx4 v[164:165], off
	v_lshl_add_u64 v[166:167], s[76:77], 0, v[192:193]
	s_mov_b32 m0, s75
	v_lshl_add_u64 v[168:169], s[22:23], 0, v[194:195]
	global_load_lds_dwordx4 v[166:167], off
	v_lshl_add_u64 v[166:167], s[76:77], 0, v[196:197]
	s_add_i32 m0, s75, 0x2000
	s_nop 0
	global_load_lds_dwordx4 v[166:167], off
	v_lshl_add_u64 v[166:167], s[22:23], 0, v[190:191]
	s_mov_b32 m0, s26
	s_nop 0
	global_load_lds_dwordx4 v[166:167], off
	s_mov_b32 m0, s27
	s_nop 0
	global_load_lds_dwordx4 v[168:169], off
	s_waitcnt vmcnt(8)
	s_waitcnt lgkmcnt(0)
	s_barrier
	s_setprio 1
	s_waitcnt lgkmcnt(0)
	v_mfma_scale_f32_16x16x128_f8f6f4 v[94:97], v[18:25], v[170:177], v[94:97], v229, v229 op_sel_hi:[0,0,0]
	v_mfma_scale_f32_16x16x128_f8f6f4 v[90:93], v[26:33], v[170:177], v[90:93], v229, v229 op_sel_hi:[0,0,0]
	v_mfma_scale_f32_16x16x128_f8f6f4 v[86:89], v[18:25], v[178:185], v[86:89], v229, v229 op_sel_hi:[0,0,0]
	v_mfma_scale_f32_16x16x128_f8f6f4 v[78:81], v[26:33], v[178:185], v[78:81], v229, v229 op_sel_hi:[0,0,0]
	v_mfma_scale_f32_16x16x128_f8f6f4 v[70:73], v[18:25], v[206:213], v[70:73], v229, v229 op_sel_hi:[0,0,0]
	v_mfma_scale_f32_16x16x128_f8f6f4 v[62:65], v[26:33], v[206:213], v[62:65], v229, v229 op_sel_hi:[0,0,0]
	v_mfma_scale_f32_16x16x128_f8f6f4 v[54:57], v[18:25], v[214:221], v[54:57], v229, v229 op_sel_hi:[0,0,0]
	v_mfma_scale_f32_16x16x128_f8f6f4 v[46:49], v[26:33], v[214:221], v[46:49], v229, v229 op_sel_hi:[0,0,0]
	v_mfma_scale_f32_16x16x128_f8f6f4 v[82:85], v[2:9], v[170:177], v[82:85], v229, v229 op_sel_hi:[0,0,0]
	v_mfma_scale_f32_16x16x128_f8f6f4 v[74:77], v[10:17], v[170:177], v[74:77], v229, v229 op_sel_hi:[0,0,0]
	v_mfma_scale_f32_16x16x128_f8f6f4 v[66:69], v[2:9], v[178:185], v[66:69], v229, v229 op_sel_hi:[0,0,0]
	v_mfma_scale_f32_16x16x128_f8f6f4 v[58:61], v[10:17], v[178:185], v[58:61], v229, v229 op_sel_hi:[0,0,0]
	v_mfma_scale_f32_16x16x128_f8f6f4 v[50:53], v[2:9], v[206:213], v[50:53], v229, v229 op_sel_hi:[0,0,0]
	v_mfma_scale_f32_16x16x128_f8f6f4 v[42:45], v[10:17], v[206:213], v[42:45], v229, v229 op_sel_hi:[0,0,0]
	v_mfma_scale_f32_16x16x128_f8f6f4 v[38:41], v[2:9], v[214:221], v[38:41], v229, v229 op_sel_hi:[0,0,0]
	v_mfma_scale_f32_16x16x128_f8f6f4 v[34:37], v[10:17], v[214:221], v[34:37], v229, v229 op_sel_hi:[0,0,0]
	s_setprio 0
	s_barrier
; #define PG8_STAGE(bufoff, gbase, voff) do { _Pragma("unroll") for (int _i = 0; _i < 2; ++_i) \
;         __builtin_amdgcn_global_load_lds((const unsigned*)((const char*)(gbase) + (voff)[_i]), (PG8_LAS unsigned*)(lds + (bufoff) + ldsw + _i * 8192), 16, 0, 0); } while (0)
; #define PG8_WAIT_V(n) asm volatile("s_waitcnt vmcnt(" #n ")" ::: "memory")
; #define PG8_WAIT_L(n) asm volatile("s_waitcnt lgkmcnt(" #n ")" ::: "memory")
; #define PG8_BAR __builtin_amdgcn_s_barrier()
; #define PG8_SCHED __builtin_amdgcn_sched_barrier(0)
; template <class Epi, class Sched, bool ALIGN_EPI = true, bool SP2 = true>
; __device__ __forceinline__ void gemm_phase(PG8_LAS unsigned char* lds, const int K  , const Sched& S, const Epi& E) {
;     ...
;             PG8_LDB(B0, 1, 0); PG8_LDB(B1, 1, 1); PG8_SCHED; PG8_LDA(At, 1, 0); PG8_STAGE(PG8_SA(0, 1), a2 + hstep, voffA);
;             PG8_WAIT_V(8); PG8_WAIT_L(0); PG8_BAR; PG8_MMA(0, 0, At, B0); PG8_MMA(0, 1, At, B1); PG8_BAR; PG8_SCHED;
;             PG8_LDA(At, 1, 1); PG8_STAGE(PG8_SB(1, 0), b3, voffB); PG8_STAGE(PG8_SB(1, 1), b3 + hstep, voffB); PG8_STAGE(PG8_SA(1, 0), a3, voffA);
;             PG8_WAIT_V(8); PG8_WAIT_L(0); PG8_BAR; PG8_MMA(1, 0, At, B0); PG8_MMA(1, 1, At, B1); PG8_BAR; PG8_SCHED;
;     ...
;         if constexpr (Epi::FP8) asm volatile("s_nop 15\n\ts_nop 15\n\ts_nop 15\n\ts_nop 15\n\ts_nop 15" ::: "memory");
;         if constexpr (ALIGN_EPI) { if (wr == 0) PG8_BAR; }
	s_add_i32 s75, 0, 0x18000
	s_add_i32 s76, 0, 0x1c000
	v_add_u32_e32 v14, s75, v231
	v_add_u32_e32 v30, s76, v231
	ds_read_b128 v[2:5], v14
	ds_read_b128 v[6:9], v14 offset:1024
	ds_read_b128 v[10:13], v14 offset:2048
	ds_read_b128 v[14:17], v14 offset:3072
	ds_read_b128 v[18:21], v30
	ds_read_b128 v[22:25], v30 offset:1024
	ds_read_b128 v[26:29], v30 offset:2048
	ds_read_b128 v[30:33], v30 offset:3072
	s_add_u32 s22, s22, 0xb0000
	s_addc_u32 s23, s23, 0
	s_mov_b32 m0, s28
	v_lshl_add_u64 v[186:187], s[22:23], 0, v[190:191]
	ds_read_b128 v[170:173], v235 offset:32768
	ds_read_b128 v[174:177], v235 offset:33792
	ds_read_b128 v[178:181], v235 offset:34816
	ds_read_b128 v[182:185], v235 offset:35840
	ds_read_b128 v[206:209], v235 offset:36864
	ds_read_b128 v[210:213], v235 offset:37888
	ds_read_b128 v[214:217], v235 offset:38912
	ds_read_b128 v[218:221], v235 offset:39936
	global_load_lds_dwordx4 v[186:187], off
	v_lshl_add_u64 v[186:187], s[22:23], 0, v[194:195]
	s_mov_b32 m0, s29
	s_nop 0
	global_load_lds_dwordx4 v[186:187], off
	s_waitcnt vmcnt(8)
	s_waitcnt lgkmcnt(0)
	s_barrier
	s_setprio 1
	s_waitcnt lgkmcnt(0)
	v_mfma_scale_f32_16x16x128_f8f6f4 v[158:161], v[2:9], v[170:177], v[158:161], v229, v229 op_sel_hi:[0,0,0]
	v_mfma_scale_f32_16x16x128_f8f6f4 v[154:157], v[10:17], v[170:177], v[154:157], v229, v229 op_sel_hi:[0,0,0]
	v_mfma_scale_f32_16x16x128_f8f6f4 v[150:153], v[2:9], v[178:185], v[150:153], v229, v229 op_sel_hi:[0,0,0]
	v_mfma_scale_f32_16x16x128_f8f6f4 v[142:145], v[10:17], v[178:185], v[142:145], v229, v229 op_sel_hi:[0,0,0]
	v_mfma_scale_f32_16x16x128_f8f6f4 v[134:137], v[2:9], v[206:213], v[134:137], v229, v229 op_sel_hi:[0,0,0]
	v_mfma_scale_f32_16x16x128_f8f6f4 v[126:129], v[10:17], v[206:213], v[126:129], v229, v229 op_sel_hi:[0,0,0]
	v_mfma_scale_f32_16x16x128_f8f6f4 v[118:121], v[2:9], v[214:221], v[118:121], v229, v229 op_sel_hi:[0,0,0]
	v_mfma_scale_f32_16x16x128_f8f6f4 v[110:113], v[10:17], v[214:221], v[110:113], v229, v229 op_sel_hi:[0,0,0]
	v_mfma_scale_f32_16x16x128_f8f6f4 v[146:149], v[18:25], v[170:177], v[146:149], v229, v229 op_sel_hi:[0,0,0]
	v_mfma_scale_f32_16x16x128_f8f6f4 v[138:141], v[26:33], v[170:177], v[138:141], v229, v229 op_sel_hi:[0,0,0]
	v_mfma_scale_f32_16x16x128_f8f6f4 v[130:133], v[18:25], v[178:185], v[130:133], v229, v229 op_sel_hi:[0,0,0]
	v_mfma_scale_f32_16x16x128_f8f6f4 v[122:125], v[26:33], v[178:185], v[122:125], v229, v229 op_sel_hi:[0,0,0]
	v_mfma_scale_f32_16x16x128_f8f6f4 v[114:117], v[18:25], v[206:213], v[114:117], v229, v229 op_sel_hi:[0,0,0]
	v_mfma_scale_f32_16x16x128_f8f6f4 v[106:109], v[26:33], v[206:213], v[106:109], v229, v229 op_sel_hi:[0,0,0]
	v_mfma_scale_f32_16x16x128_f8f6f4 v[102:105], v[18:25], v[214:221], v[102:105], v229, v229 op_sel_hi:[0,0,0]
	v_mfma_scale_f32_16x16x128_f8f6f4 v[98:101], v[26:33], v[214:221], v[98:101], v229, v229 op_sel_hi:[0,0,0]
	s_setprio 0
	s_barrier
	s_add_i32 s22, s75, s25
	v_lshl_add_u64 v[162:163], v[162:163], 0, s[8:9]
	s_mov_b32 m0, s22
	ds_read_b128 v[170:173], v235 offset:49152
	ds_read_b128 v[174:177], v235 offset:50176
	ds_read_b128 v[178:181], v235 offset:51200
	ds_read_b128 v[182:185], v235 offset:52224
	ds_read_b128 v[206:209], v235 offset:53248
	ds_read_b128 v[210:213], v235 offset:54272
	ds_read_b128 v[214:217], v235 offset:55296
	ds_read_b128 v[218:221], v235 offset:56320
	global_load_lds_dwordx4 v[162:163], off
	s_add_i32 m0, s22, 0x2000
	s_add_u32 s20, s20, 0xb0080
	v_lshl_add_u64 v[162:163], v[164:165], 0, s[8:9]
	s_addc_u32 s21, s21, 0
	s_add_i32 s22, s76, s25
	global_load_lds_dwordx4 v[162:163], off
	v_lshl_add_u64 v[162:163], s[20:21], 0, v[192:193]
	s_mov_b32 m0, s22
	s_nop 0
	global_load_lds_dwordx4 v[162:163], off
	v_lshl_add_u64 v[162:163], s[20:21], 0, v[196:197]
	s_add_i32 m0, s22, 0x2000
	s_nop 0
	global_load_lds_dwordx4 v[162:163], off
	v_lshl_add_u64 v[162:163], v[166:167], 0, s[8:9]
	s_mov_b32 m0, s36
	s_nop 0
	global_load_lds_dwordx4 v[162:163], off
	v_lshl_add_u64 v[162:163], v[168:169], 0, s[8:9]
	s_mov_b32 m0, s37
	s_nop 0
	global_load_lds_dwordx4 v[162:163], off
	s_waitcnt vmcnt(8)
	s_waitcnt lgkmcnt(0)
	s_barrier
	s_setprio 1
	s_waitcnt lgkmcnt(0)
	v_mfma_scale_f32_16x16x128_f8f6f4 v[94:97], v[2:9], v[170:177], v[94:97], v229, v229 op_sel_hi:[0,0,0]
	v_mfma_scale_f32_16x16x128_f8f6f4 v[90:93], v[10:17], v[170:177], v[90:93], v229, v229 op_sel_hi:[0,0,0]
	v_mfma_scale_f32_16x16x128_f8f6f4 v[86:89], v[2:9], v[178:185], v[86:89], v229, v229 op_sel_hi:[0,0,0]
	v_mfma_scale_f32_16x16x128_f8f6f4 v[78:81], v[10:17], v[178:185], v[78:81], v229, v229 op_sel_hi:[0,0,0]
	v_mfma_scale_f32_16x16x128_f8f6f4 v[70:73], v[2:9], v[206:213], v[70:73], v229, v229 op_sel_hi:[0,0,0]
	v_mfma_scale_f32_16x16x128_f8f6f4 v[62:65], v[10:17], v[206:213], v[62:65], v229, v229 op_sel_hi:[0,0,0]
	v_mfma_scale_f32_16x16x128_f8f6f4 v[54:57], v[2:9], v[214:221], v[54:57], v229, v229 op_sel_hi:[0,0,0]
	v_mfma_scale_f32_16x16x128_f8f6f4 v[46:49], v[10:17], v[214:221], v[46:49], v229, v229 op_sel_hi:[0,0,0]
	v_mfma_scale_f32_16x16x128_f8f6f4 v[82:85], v[18:25], v[170:177], v[82:85], v229, v229 op_sel_hi:[0,0,0]
	v_mfma_scale_f32_16x16x128_f8f6f4 v[74:77], v[26:33], v[170:177], v[74:77], v229, v229 op_sel_hi:[0,0,0]
	v_mfma_scale_f32_16x16x128_f8f6f4 v[66:69], v[18:25], v[178:185], v[66:69], v229, v229 op_sel_hi:[0,0,0]
	v_mfma_scale_f32_16x16x128_f8f6f4 v[58:61], v[26:33], v[178:185], v[58:61], v229, v229 op_sel_hi:[0,0,0]
	v_mfma_scale_f32_16x16x128_f8f6f4 v[50:53], v[18:25], v[206:213], v[50:53], v229, v229 op_sel_hi:[0,0,0]
	v_mfma_scale_f32_16x16x128_f8f6f4 v[42:45], v[26:33], v[206:213], v[42:45], v229, v229 op_sel_hi:[0,0,0]
	v_mfma_scale_f32_16x16x128_f8f6f4 v[38:41], v[18:25], v[214:221], v[38:41], v229, v229 op_sel_hi:[0,0,0]
	v_mfma_scale_f32_16x16x128_f8f6f4 v[34:37], v[26:33], v[214:221], v[34:37], v229, v229 op_sel_hi:[0,0,0]
	s_setprio 0
	s_barrier
	s_add_u32 s18, s18, 0x100
	s_addc_u32 s19, s19, 0
	s_add_u32 s72, s72, 0x100
	s_addc_u32 s73, s73, 0
	s_cmp_ge_u32 s74, s4
	s_mov_b32 s22, s74
	s_cbranch_scc0 .LBB0_1304
	s_nop 15
	s_nop 15
	s_nop 15
	s_nop 15
	s_nop 15
	s_and_b64 vcc, exec, s[10:11]
	s_cbranch_vccz .LBB0_1307
	s_barrier

; #define PG8_STAGE(bufoff, gbase, voff) do { _Pragma("unroll") for (int _i = 0; _i < 2; ++_i) \
;         __builtin_amdgcn_global_load_lds((const unsigned*)((const char*)(gbase) + (voff)[_i]), (PG8_LAS unsigned*)(lds + (bufoff) + ldsw + _i * 8192), 16, 0, 0); } while (0)
; #define PG8_WAIT_V(n) asm volatile("s_waitcnt vmcnt(" #n ")" ::: "memory")
; #define PG8_WAIT_L(n) asm volatile("s_waitcnt lgkmcnt(" #n ")" ::: "memory")
; #define PG8_BAR __builtin_amdgcn_s_barrier()
; #define PG8_SCHED __builtin_amdgcn_sched_barrier(0)
; template <class Epi, class Sched, bool ALIGN_EPI = true, bool SP2 = true>
; __device__ __forceinline__ void gemm_phase(PG8_LAS unsigned char* lds, const int K  , const Sched& S, const Epi& E) {
;     ...
;             PG8_LDB(B0, 0, 0); PG8_LDB(B1, 0, 1); PG8_SCHED; PG8_LDA(At, 0, 0); PG8_STAGE(PG8_SA(1, 1), a1 + hstep, voffA);
;             PG8_WAIT_V(8); PG8_WAIT_L(0); PG8_BAR; PG8_MMA(0, 0, At, B0); PG8_MMA(0, 1, At, B1); PG8_BAR; PG8_SCHED;
;             PG8_LDA(At, 0, 1); PG8_STAGE(PG8_SB(0, 0), b2, voffB); PG8_STAGE(PG8_SB(0, 1), b2 + hstep, voffB); PG8_STAGE(PG8_SA(0, 0), a2, voffA);
;             PG8_WAIT_V(8); PG8_WAIT_L(0); PG8_BAR; PG8_MMA(1, 0, At, B0); PG8_MMA(1, 1, At, B1); PG8_BAR; PG8_SCHED;
.LBB0_1448:
	ds_read_b128 v[148:151], v154
	ds_read_b128 v[160:163], v154 offset:1024
	ds_read_b128 v[164:167], v154 offset:2048
	ds_read_b128 v[168:171], v154 offset:3072
	ds_read_b128 v[172:175], v155
	ds_read_b128 v[176:179], v155 offset:1024
	ds_read_b128 v[180:183], v155 offset:2048
	ds_read_b128 v[184:187], v155 offset:3072
	s_add_u32 s26, s24, 0xfff80080
	s_addc_u32 s27, s25, -1
	s_cmp_eq_u32 s50, 28
	s_cselect_b32 s29, s17, s27
	s_cselect_b32 s28, s46, s26
	s_cselect_b32 s27, s11, s49
	s_cselect_b32 s26, s47, s48
	v_lshl_add_u64 v[220:221], s[24:25], 0, v[140:141]
	s_add_i32 m0, s23, 0xc000
	ds_read_b128 v[188:191], v156
	ds_read_b128 v[192:195], v156 offset:1024
	ds_read_b128 v[196:199], v156 offset:2048
	ds_read_b128 v[200:203], v156 offset:3072
	ds_read_b128 v[204:207], v156 offset:4096
	ds_read_b128 v[208:211], v156 offset:5120
	ds_read_b128 v[212:215], v156 offset:6144
	ds_read_b128 v[216:219], v156 offset:7168
	global_load_lds_dwordx4 v[220:221], off
	v_lshl_add_u64 v[220:221], s[24:25], 0, v[142:143]
	s_add_i32 m0, s23, 0xe000
	s_nop 0
	global_load_lds_dwordx4 v[220:221], off
	s_waitcnt vmcnt(8)
	s_waitcnt lgkmcnt(0)
	s_barrier
	s_setprio 1
	s_waitcnt lgkmcnt(0)
	v_mfma_f32_16x16x32_bf16 v[126:129], v[148:151], v[188:191], v[126:129]
	v_mfma_f32_16x16x32_bf16 v[118:121], v[164:167], v[188:191], v[118:121]
	v_mfma_f32_16x16x32_bf16 v[110:113], v[148:151], v[196:199], v[110:113]
	v_mfma_f32_16x16x32_bf16 v[102:105], v[164:167], v[196:199], v[102:105]
	v_mfma_f32_16x16x32_bf16 v[94:97], v[148:151], v[204:207], v[94:97]
	v_mfma_f32_16x16x32_bf16 v[86:89], v[164:167], v[204:207], v[86:89]
	v_mfma_f32_16x16x32_bf16 v[78:81], v[148:151], v[212:215], v[78:81]
	v_mfma_f32_16x16x32_bf16 v[70:73], v[164:167], v[212:215], v[70:73]
	v_mfma_f32_16x16x32_bf16 v[126:129], v[160:163], v[192:195], v[126:129]
	v_mfma_f32_16x16x32_bf16 v[118:121], v[168:171], v[192:195], v[118:121]
	v_mfma_f32_16x16x32_bf16 v[110:113], v[160:163], v[200:203], v[110:113]
	v_mfma_f32_16x16x32_bf16 v[102:105], v[168:171], v[200:203], v[102:105]
	v_mfma_f32_16x16x32_bf16 v[94:97], v[160:163], v[208:211], v[94:97]
	v_mfma_f32_16x16x32_bf16 v[86:89], v[168:171], v[208:211], v[86:89]
	v_mfma_f32_16x16x32_bf16 v[78:81], v[160:163], v[216:219], v[78:81]
	v_mfma_f32_16x16x32_bf16 v[70:73], v[168:171], v[216:219], v[70:73]
	v_mfma_f32_16x16x32_bf16 v[122:125], v[172:175], v[188:191], v[122:125]
	v_mfma_f32_16x16x32_bf16 v[114:117], v[180:183], v[188:191], v[114:117]
	v_mfma_f32_16x16x32_bf16 v[106:109], v[172:175], v[196:199], v[106:109]
	v_mfma_f32_16x16x32_bf16 v[98:101], v[180:183], v[196:199], v[98:101]
	v_mfma_f32_16x16x32_bf16 v[90:93], v[172:175], v[204:207], v[90:93]
	v_mfma_f32_16x16x32_bf16 v[82:85], v[180:183], v[204:207], v[82:85]
	v_mfma_f32_16x16x32_bf16 v[74:77], v[172:175], v[212:215], v[74:77]
	v_mfma_f32_16x16x32_bf16 v[66:69], v[180:183], v[212:215], v[66:69]
	v_mfma_f32_16x16x32_bf16 v[122:125], v[176:179], v[192:195], v[122:125]
	v_mfma_f32_16x16x32_bf16 v[114:117], v[184:187], v[192:195], v[114:117]
	v_mfma_f32_16x16x32_bf16 v[106:109], v[176:179], v[200:203], v[106:109]
	v_mfma_f32_16x16x32_bf16 v[98:101], v[184:187], v[200:203], v[98:101]
	v_mfma_f32_16x16x32_bf16 v[90:93], v[176:179], v[208:211], v[90:93]
	v_mfma_f32_16x16x32_bf16 v[82:85], v[184:187], v[208:211], v[82:85]
	v_mfma_f32_16x16x32_bf16 v[74:77], v[176:179], v[216:219], v[74:77]
	v_mfma_f32_16x16x32_bf16 v[66:69], v[184:187], v[216:219], v[66:69]
	s_setprio 0
	s_barrier
	s_add_i32 s51, s41, s31
	v_lshl_add_u64 v[220:221], s[26:27], 0, v[136:137]
	s_mov_b32 m0, s51
	ds_read_b128 v[188:191], v156 offset:16384
	ds_read_b128 v[192:195], v156 offset:17408
	ds_read_b128 v[196:199], v156 offset:18432
	ds_read_b128 v[200:203], v156 offset:19456
	ds_read_b128 v[204:207], v156 offset:20480
	ds_read_b128 v[208:211], v156 offset:21504
	ds_read_b128 v[212:215], v156 offset:22528
	ds_read_b128 v[216:219], v156 offset:23552
	global_load_lds_dwordx4 v[220:221], off
	s_add_i32 m0, s51, 0x2000
	s_add_u32 s68, s26, 0x80000
	v_lshl_add_u64 v[222:223], s[26:27], 0, v[132:133]
	s_addc_u32 s69, s27, 0
	s_add_i32 s51, s42, s31
	global_load_lds_dwordx4 v[222:223], off
	v_lshl_add_u64 v[224:225], s[68:69], 0, v[136:137]
	s_mov_b32 m0, s51
	v_lshl_add_u64 v[226:227], s[28:29], 0, v[134:135]
	global_load_lds_dwordx4 v[224:225], off
	v_lshl_add_u64 v[224:225], s[68:69], 0, v[132:133]
	s_add_i32 m0, s51, 0x2000
	s_nop 0
	global_load_lds_dwordx4 v[224:225], off
	v_lshl_add_u64 v[224:225], s[28:29], 0, v[138:139]
	s_mov_b32 m0, s23
	s_nop 0
	global_load_lds_dwordx4 v[224:225], off
	s_mov_b32 m0, s34
	s_nop 0
	global_load_lds_dwordx4 v[226:227], off
	s_waitcnt vmcnt(8)
	s_waitcnt lgkmcnt(0)
	s_barrier
; #define PG8_STAGE(bufoff, gbase, voff) do { _Pragma("unroll") for (int _i = 0; _i < 2; ++_i) \
;         __builtin_amdgcn_global_load_lds((const unsigned*)((const char*)(gbase) + (voff)[_i]), (PG8_LAS unsigned*)(lds + (bufoff) + ldsw + _i * 8192), 16, 0, 0); } while (0)
; #define PG8_WAIT_V(n) asm volatile("s_waitcnt vmcnt(" #n ")" ::: "memory")
; #define PG8_WAIT_L(n) asm volatile("s_waitcnt lgkmcnt(" #n ")" ::: "memory")
; #define PG8_BAR __builtin_amdgcn_s_barrier()
; #define PG8_SCHED __builtin_amdgcn_sched_barrier(0)
; template <class Epi, class Sched, bool ALIGN_EPI = true, bool SP2 = true>
; __device__ __forceinline__ void gemm_phase(PG8_LAS unsigned char* lds, const int K  , const Sched& S, const Epi& E) {
;     ...
;             PG8_WAIT_V(8); PG8_WAIT_L(0); PG8_BAR; PG8_MMA(1, 0, At, B0); PG8_MMA(1, 1, At, B1); PG8_BAR; PG8_SCHED;
;             PG8_LDB(B0, 1, 0); PG8_LDB(B1, 1, 1); PG8_SCHED; PG8_LDA(At, 1, 0); PG8_STAGE(PG8_SA(0, 1), a2 + hstep, voffA);
;             PG8_WAIT_V(8); PG8_WAIT_L(0); PG8_BAR; PG8_MMA(0, 0, At, B0); PG8_MMA(0, 1, At, B1); PG8_BAR; PG8_SCHED;
	s_setprio 1
	s_waitcnt lgkmcnt(0)
	v_mfma_f32_16x16x32_bf16 v[62:65], v[148:151], v[188:191], v[62:65]
	v_mfma_f32_16x16x32_bf16 v[54:57], v[164:167], v[188:191], v[54:57]
	v_mfma_f32_16x16x32_bf16 v[46:49], v[148:151], v[196:199], v[46:49]
	v_mfma_f32_16x16x32_bf16 v[38:41], v[164:167], v[196:199], v[38:41]
	v_mfma_f32_16x16x32_bf16 v[30:33], v[148:151], v[204:207], v[30:33]
	v_mfma_f32_16x16x32_bf16 v[22:25], v[164:167], v[204:207], v[22:25]
	v_mfma_f32_16x16x32_bf16 v[14:17], v[148:151], v[212:215], v[14:17]
	v_mfma_f32_16x16x32_bf16 v[6:9], v[164:167], v[212:215], v[6:9]
	v_mfma_f32_16x16x32_bf16 v[62:65], v[160:163], v[192:195], v[62:65]
	v_mfma_f32_16x16x32_bf16 v[54:57], v[168:171], v[192:195], v[54:57]
	v_mfma_f32_16x16x32_bf16 v[46:49], v[160:163], v[200:203], v[46:49]
	v_mfma_f32_16x16x32_bf16 v[38:41], v[168:171], v[200:203], v[38:41]
	v_mfma_f32_16x16x32_bf16 v[30:33], v[160:163], v[208:211], v[30:33]
	v_mfma_f32_16x16x32_bf16 v[22:25], v[168:171], v[208:211], v[22:25]
	v_mfma_f32_16x16x32_bf16 v[14:17], v[160:163], v[216:219], v[14:17]
	v_mfma_f32_16x16x32_bf16 v[6:9], v[168:171], v[216:219], v[6:9]
	v_mfma_f32_16x16x32_bf16 v[58:61], v[172:175], v[188:191], v[58:61]
	v_mfma_f32_16x16x32_bf16 v[50:53], v[180:183], v[188:191], v[50:53]
	v_mfma_f32_16x16x32_bf16 v[42:45], v[172:175], v[196:199], v[42:45]
	v_mfma_f32_16x16x32_bf16 v[34:37], v[180:183], v[196:199], v[34:37]
	v_mfma_f32_16x16x32_bf16 v[26:29], v[172:175], v[204:207], v[26:29]
	v_mfma_f32_16x16x32_bf16 v[18:21], v[180:183], v[204:207], v[18:21]
	v_mfma_f32_16x16x32_bf16 v[10:13], v[172:175], v[212:215], v[10:13]
	v_mfma_f32_16x16x32_bf16 v[2:5], v[180:183], v[212:215], v[2:5]
	v_mfma_f32_16x16x32_bf16 v[58:61], v[176:179], v[192:195], v[58:61]
	v_mfma_f32_16x16x32_bf16 v[50:53], v[184:187], v[192:195], v[50:53]
	v_mfma_f32_16x16x32_bf16 v[42:45], v[176:179], v[200:203], v[42:45]
	v_mfma_f32_16x16x32_bf16 v[34:37], v[184:187], v[200:203], v[34:37]
	v_mfma_f32_16x16x32_bf16 v[26:29], v[176:179], v[208:211], v[26:29]
	v_mfma_f32_16x16x32_bf16 v[18:21], v[184:187], v[208:211], v[18:21]
	v_mfma_f32_16x16x32_bf16 v[10:13], v[176:179], v[216:219], v[10:13]
	v_mfma_f32_16x16x32_bf16 v[2:5], v[184:187], v[216:219], v[2:5]
	s_setprio 0
	s_barrier
	s_add_i32 s51, 0, 0x18000
	v_add_u32_e32 v159, s51, v152
	s_add_i32 s68, 0, 0x1c000
	ds_read_b128 v[148:151], v159
	ds_read_b128 v[160:163], v159 offset:1024
	ds_read_b128 v[164:167], v159 offset:2048
	ds_read_b128 v[168:171], v159 offset:3072
	v_add_u32_e32 v159, s68, v152
	ds_read_b128 v[172:175], v159
	ds_read_b128 v[176:179], v159 offset:1024
	ds_read_b128 v[180:183], v159 offset:2048
	ds_read_b128 v[184:187], v159 offset:3072
	s_add_u32 s28, s28, 0x80000
	s_addc_u32 s29, s29, 0
	s_mov_b32 m0, s35
	v_lshl_add_u64 v[230:231], s[28:29], 0, v[138:139]
	ds_read_b128 v[188:191], v156 offset:32768
	ds_read_b128 v[192:195], v156 offset:33792
	ds_read_b128 v[196:199], v156 offset:34816
	ds_read_b128 v[200:203], v156 offset:35840
	ds_read_b128 v[204:207], v156 offset:36864
	ds_read_b128 v[208:211], v156 offset:37888
	ds_read_b128 v[212:215], v156 offset:38912
	ds_read_b128 v[216:219], v156 offset:39936
	global_load_lds_dwordx4 v[230:231], off
	v_lshl_add_u64 v[230:231], s[28:29], 0, v[134:135]
	s_mov_b32 m0, s36
	s_nop 0
	global_load_lds_dwordx4 v[230:231], off
	s_waitcnt vmcnt(8)
	s_waitcnt lgkmcnt(0)
	s_barrier
	s_setprio 1
	s_waitcnt lgkmcnt(0)
	v_mfma_f32_16x16x32_bf16 v[126:129], v[148:151], v[188:191], v[126:129]
	v_mfma_f32_16x16x32_bf16 v[118:121], v[164:167], v[188:191], v[118:121]
	v_mfma_f32_16x16x32_bf16 v[110:113], v[148:151], v[196:199], v[110:113]
	v_mfma_f32_16x16x32_bf16 v[102:105], v[164:167], v[196:199], v[102:105]
	v_mfma_f32_16x16x32_bf16 v[94:97], v[148:151], v[204:207], v[94:97]
	v_mfma_f32_16x16x32_bf16 v[86:89], v[164:167], v[204:207], v[86:89]
	v_mfma_f32_16x16x32_bf16 v[78:81], v[148:151], v[212:215], v[78:81]
	v_mfma_f32_16x16x32_bf16 v[70:73], v[164:167], v[212:215], v[70:73]
	v_mfma_f32_16x16x32_bf16 v[126:129], v[160:163], v[192:195], v[126:129]
	v_mfma_f32_16x16x32_bf16 v[118:121], v[168:171], v[192:195], v[118:121]
	v_mfma_f32_16x16x32_bf16 v[110:113], v[160:163], v[200:203], v[110:113]
	v_mfma_f32_16x16x32_bf16 v[102:105], v[168:171], v[200:203], v[102:105]
	v_mfma_f32_16x16x32_bf16 v[94:97], v[160:163], v[208:211], v[94:97]
	v_mfma_f32_16x16x32_bf16 v[86:89], v[168:171], v[208:211], v[86:89]
	v_mfma_f32_16x16x32_bf16 v[78:81], v[160:163], v[216:219], v[78:81]
	v_mfma_f32_16x16x32_bf16 v[70:73], v[168:171], v[216:219], v[70:73]
	v_mfma_f32_16x16x32_bf16 v[122:125], v[172:175], v[188:191], v[122:125]
	v_mfma_f32_16x16x32_bf16 v[114:117], v[180:183], v[188:191], v[114:117]
	v_mfma_f32_16x16x32_bf16 v[106:109], v[172:175], v[196:199], v[106:109]
	v_mfma_f32_16x16x32_bf16 v[98:101], v[180:183], v[196:199], v[98:101]
	v_mfma_f32_16x16x32_bf16 v[90:93], v[172:175], v[204:207], v[90:93]
	v_mfma_f32_16x16x32_bf16 v[82:85], v[180:183], v[204:207], v[82:85]
	v_mfma_f32_16x16x32_bf16 v[74:77], v[172:175], v[212:215], v[74:77]
	v_mfma_f32_16x16x32_bf16 v[66:69], v[180:183], v[212:215], v[66:69]
	v_mfma_f32_16x16x32_bf16 v[122:125], v[176:179], v[192:195], v[122:125]
	v_mfma_f32_16x16x32_bf16 v[114:117], v[184:187], v[192:195], v[114:117]
	v_mfma_f32_16x16x32_bf16 v[106:109], v[176:179], v[200:203], v[106:109]
	v_mfma_f32_16x16x32_bf16 v[98:101], v[184:187], v[200:203], v[98:101]
	v_mfma_f32_16x16x32_bf16 v[90:93], v[176:179], v[208:211], v[90:93]
	v_mfma_f32_16x16x32_bf16 v[82:85], v[184:187], v[208:211], v[82:85]
	v_mfma_f32_16x16x32_bf16 v[74:77], v[176:179], v[216:219], v[74:77]
	v_mfma_f32_16x16x32_bf16 v[66:69], v[184:187], v[216:219], v[66:69]
	s_setprio 0
	s_barrier
; #define PG8_STAGE(bufoff, gbase, voff) do { _Pragma("unroll") for (int _i = 0; _i < 2; ++_i) \
;         __builtin_amdgcn_global_load_lds((const unsigned*)((const char*)(gbase) + (voff)[_i]), (PG8_LAS unsigned*)(lds + (bufoff) + ldsw + _i * 8192), 16, 0, 0); } while (0)
; #define PG8_WAIT_V(n) asm volatile("s_waitcnt vmcnt(" #n ")" ::: "memory")
; #define PG8_WAIT_L(n) asm volatile("s_waitcnt lgkmcnt(" #n ")" ::: "memory")
; #define PG8_BAR __builtin_amdgcn_s_barrier()
; #define PG8_SCHED __builtin_amdgcn_sched_barrier(0)
;     __device__ __forceinline__ int nt(const pg8::Unit& u) const { return u.kind == 0 ? ntiles : q_nt(u.kind - 1); }
; template <class Epi, class Sched, bool ALIGN_EPI = true, bool SP2 = true>
; __device__ __forceinline__ void gemm_phase(PG8_LAS unsigned char* lds, const int K  , const Sched& S, const Epi& E) {
;     ...
;         for (int t = 0; t < nt; t += 2) {
;     ...
;             PG8_LDA(At, 1, 1); PG8_STAGE(PG8_SB(1, 0), b3, voffB); PG8_STAGE(PG8_SB(1, 1), b3 + hstep, voffB); PG8_STAGE(PG8_SA(1, 0), a3, voffA);
;             PG8_WAIT_V(8); PG8_WAIT_L(0); PG8_BAR; PG8_MMA(1, 0, At, B0); PG8_MMA(1, 1, At, B1); PG8_BAR; PG8_SCHED;
;     ...
;         if constexpr (Epi::FP8) asm volatile("s_nop 15\n\ts_nop 15\n\ts_nop 15\n\ts_nop 15\n\ts_nop 15" ::: "memory");
;         if constexpr (ALIGN_EPI) { if (wr == 0) PG8_BAR; }
	s_add_i32 s28, s51, s31
	v_lshl_add_u64 v[220:221], v[220:221], 0, s[4:5]
	s_mov_b32 m0, s28
	ds_read_b128 v[188:191], v156 offset:49152
	ds_read_b128 v[192:195], v156 offset:50176
	ds_read_b128 v[196:199], v156 offset:51200
	ds_read_b128 v[200:203], v156 offset:52224
	ds_read_b128 v[204:207], v156 offset:53248
	ds_read_b128 v[208:211], v156 offset:54272
	ds_read_b128 v[212:215], v156 offset:55296
	ds_read_b128 v[216:219], v156 offset:56320
	global_load_lds_dwordx4 v[220:221], off
	s_add_i32 m0, s28, 0x2000
	s_add_u32 s26, s26, 0x80080
	v_lshl_add_u64 v[220:221], v[222:223], 0, s[4:5]
	s_addc_u32 s27, s27, 0
	s_add_i32 s28, s68, s31
	global_load_lds_dwordx4 v[220:221], off
	v_lshl_add_u64 v[220:221], s[26:27], 0, v[136:137]
	s_mov_b32 m0, s28
	s_nop 0
	global_load_lds_dwordx4 v[220:221], off
	v_lshl_add_u64 v[220:221], s[26:27], 0, v[132:133]
	s_add_i32 m0, s28, 0x2000
	s_nop 0
	global_load_lds_dwordx4 v[220:221], off
	v_lshl_add_u64 v[220:221], v[224:225], 0, s[4:5]
	s_mov_b32 m0, s38
	s_nop 0
	global_load_lds_dwordx4 v[220:221], off
	v_lshl_add_u64 v[220:221], v[226:227], 0, s[4:5]
	s_mov_b32 m0, s39
	s_nop 0
	global_load_lds_dwordx4 v[220:221], off
	s_waitcnt vmcnt(8)
	s_waitcnt lgkmcnt(0)
	s_barrier
	s_setprio 1
	s_waitcnt lgkmcnt(0)
	v_mfma_f32_16x16x32_bf16 v[62:65], v[148:151], v[188:191], v[62:65]
	v_mfma_f32_16x16x32_bf16 v[54:57], v[164:167], v[188:191], v[54:57]
	v_mfma_f32_16x16x32_bf16 v[46:49], v[148:151], v[196:199], v[46:49]
	v_mfma_f32_16x16x32_bf16 v[38:41], v[164:167], v[196:199], v[38:41]
	v_mfma_f32_16x16x32_bf16 v[30:33], v[148:151], v[204:207], v[30:33]
	v_mfma_f32_16x16x32_bf16 v[22:25], v[164:167], v[204:207], v[22:25]
	v_mfma_f32_16x16x32_bf16 v[14:17], v[148:151], v[212:215], v[14:17]
	v_mfma_f32_16x16x32_bf16 v[6:9], v[164:167], v[212:215], v[6:9]
	v_mfma_f32_16x16x32_bf16 v[62:65], v[160:163], v[192:195], v[62:65]
	v_mfma_f32_16x16x32_bf16 v[54:57], v[168:171], v[192:195], v[54:57]
	v_mfma_f32_16x16x32_bf16 v[46:49], v[160:163], v[200:203], v[46:49]
	v_mfma_f32_16x16x32_bf16 v[38:41], v[168:171], v[200:203], v[38:41]
	v_mfma_f32_16x16x32_bf16 v[30:33], v[160:163], v[208:211], v[30:33]
	v_mfma_f32_16x16x32_bf16 v[22:25], v[168:171], v[208:211], v[22:25]
	v_mfma_f32_16x16x32_bf16 v[14:17], v[160:163], v[216:219], v[14:17]
	v_mfma_f32_16x16x32_bf16 v[6:9], v[168:171], v[216:219], v[6:9]
	v_mfma_f32_16x16x32_bf16 v[58:61], v[172:175], v[188:191], v[58:61]
	v_mfma_f32_16x16x32_bf16 v[50:53], v[180:183], v[188:191], v[50:53]
	v_mfma_f32_16x16x32_bf16 v[42:45], v[172:175], v[196:199], v[42:45]
	v_mfma_f32_16x16x32_bf16 v[34:37], v[180:183], v[196:199], v[34:37]
	v_mfma_f32_16x16x32_bf16 v[26:29], v[172:175], v[204:207], v[26:29]
	v_mfma_f32_16x16x32_bf16 v[18:21], v[180:183], v[204:207], v[18:21]
	v_mfma_f32_16x16x32_bf16 v[10:13], v[172:175], v[212:215], v[10:13]
	v_mfma_f32_16x16x32_bf16 v[2:5], v[180:183], v[212:215], v[2:5]
	v_mfma_f32_16x16x32_bf16 v[58:61], v[176:179], v[192:195], v[58:61]
	v_mfma_f32_16x16x32_bf16 v[50:53], v[184:187], v[192:195], v[50:53]
	v_mfma_f32_16x16x32_bf16 v[42:45], v[176:179], v[200:203], v[42:45]
	v_mfma_f32_16x16x32_bf16 v[34:37], v[184:187], v[200:203], v[34:37]
	v_mfma_f32_16x16x32_bf16 v[26:29], v[176:179], v[208:211], v[26:29]
	v_mfma_f32_16x16x32_bf16 v[18:21], v[184:187], v[208:211], v[18:21]
	v_mfma_f32_16x16x32_bf16 v[10:13], v[176:179], v[216:219], v[10:13]
	v_mfma_f32_16x16x32_bf16 v[2:5], v[184:187], v[216:219], v[2:5]
	s_setprio 0
	s_barrier
	s_add_i32 s50, s50, 2
	s_add_u32 s24, s24, 0x100
	s_addc_u32 s25, s25, 0
	s_add_u32 s48, s48, 0x100
	s_addc_u32 s49, s49, 0
	s_cmp_gt_u32 s50, 29
	s_cbranch_scc0 .LBB0_1448
	s_and_b64 vcc, exec, s[8:9]
	s_cbranch_vccz .LBB0_1451
	s_barrier

; #define PG8_STAGE(bufoff, gbase, voff) do { _Pragma("unroll") for (int _i = 0; _i < 2; ++_i) \
;         __builtin_amdgcn_global_load_lds((const unsigned*)((const char*)(gbase) + (voff)[_i]), (PG8_LAS unsigned*)(lds + (bufoff) + ldsw + _i * 8192), 16, 0, 0); } while (0)
; #define PG8_WAIT_V(n) asm volatile("s_waitcnt vmcnt(" #n ")" ::: "memory")
; #define PG8_WAIT_L(n) asm volatile("s_waitcnt lgkmcnt(" #n ")" ::: "memory")
; #define PG8_BAR __builtin_amdgcn_s_barrier()
; #define PG8_SCHED __builtin_amdgcn_sched_barrier(0)
; template <class Epi, class Sched, bool ALIGN_EPI = true, bool SP2 = true>
; __device__ __forceinline__ void gemm_phase(PG8_LAS unsigned char* lds, const int K  , const Sched& S, const Epi& E) {
;     ...
;             PG8_LDB(B0, 0, 0); PG8_LDB(B1, 0, 1); PG8_SCHED; PG8_LDA(At, 0, 0); PG8_STAGE(PG8_SA(1, 1), a1 + hstep, voffA);
;             PG8_WAIT_V(8); PG8_WAIT_L(0); PG8_BAR; PG8_MMA(0, 0, At, B0); PG8_MMA(0, 1, At, B1); PG8_BAR; PG8_SCHED;
;             PG8_LDA(At, 0, 1); PG8_STAGE(PG8_SB(0, 0), b2, voffB); PG8_STAGE(PG8_SB(0, 1), b2 + hstep, voffB); PG8_STAGE(PG8_SA(0, 0), a2, voffA);
;             PG8_WAIT_V(8); PG8_WAIT_L(0); PG8_BAR; PG8_MMA(1, 0, At, B0); PG8_MMA(1, 1, At, B1); PG8_BAR; PG8_SCHED;
.LBB0_1695:
	ds_read_b128 v[18:21], v233
	ds_read_b128 v[22:25], v233 offset:1024
	ds_read_b128 v[26:29], v233 offset:2048
	ds_read_b128 v[30:33], v233 offset:3072
	ds_read_b128 v[2:5], v234
	ds_read_b128 v[6:9], v234 offset:1024
	ds_read_b128 v[10:13], v234 offset:2048
	ds_read_b128 v[14:17], v234 offset:3072
	s_add_i32 s74, s24, 2
	s_add_u32 s22, s20, 0xfff50080
	s_addc_u32 s23, s21, -1
	s_cmp_eq_u32 s71, s24
	s_cselect_b32 s24, s16, s22
	s_cselect_b32 s25, s17, s23
	s_cselect_b32 s23, s19, s73
	s_cselect_b32 s22, s18, s72
	v_lshl_add_u64 v[186:187], s[20:21], 0, v[198:199]
	s_add_i32 m0, s28, 0xc000
	ds_read_b128 v[162:165], v235
	ds_read_b128 v[166:169], v235 offset:1024
	ds_read_b128 v[170:173], v235 offset:2048
	ds_read_b128 v[174:177], v235 offset:3072
	ds_read_b128 v[178:181], v235 offset:4096
	ds_read_b128 v[182:185], v235 offset:5120
	ds_read_b128 v[206:209], v235 offset:6144
	ds_read_b128 v[210:213], v235 offset:7168
	global_load_lds_dwordx4 v[186:187], off
	v_lshl_add_u64 v[186:187], s[20:21], 0, v[200:201]
	s_add_i32 m0, s28, 0xe000
	s_nop 0
	global_load_lds_dwordx4 v[186:187], off
	s_waitcnt vmcnt(8)
	s_waitcnt lgkmcnt(0)
	s_barrier
	s_setprio 1
	s_waitcnt lgkmcnt(0)
	v_mfma_scale_f32_16x16x128_f8f6f4 v[158:161], v[18:25], v[162:169], v[158:161], v229, v229 op_sel_hi:[0,0,0]
	v_mfma_scale_f32_16x16x128_f8f6f4 v[154:157], v[26:33], v[162:169], v[154:157], v229, v229 op_sel_hi:[0,0,0]
	v_mfma_scale_f32_16x16x128_f8f6f4 v[150:153], v[18:25], v[170:177], v[150:153], v229, v229 op_sel_hi:[0,0,0]
	v_mfma_scale_f32_16x16x128_f8f6f4 v[142:145], v[26:33], v[170:177], v[142:145], v229, v229 op_sel_hi:[0,0,0]
	v_mfma_scale_f32_16x16x128_f8f6f4 v[134:137], v[18:25], v[178:185], v[134:137], v229, v229 op_sel_hi:[0,0,0]
	v_mfma_scale_f32_16x16x128_f8f6f4 v[126:129], v[26:33], v[178:185], v[126:129], v229, v229 op_sel_hi:[0,0,0]
	v_mfma_scale_f32_16x16x128_f8f6f4 v[118:121], v[18:25], v[206:213], v[118:121], v229, v229 op_sel_hi:[0,0,0]
	v_mfma_scale_f32_16x16x128_f8f6f4 v[110:113], v[26:33], v[206:213], v[110:113], v229, v229 op_sel_hi:[0,0,0]
	v_mfma_scale_f32_16x16x128_f8f6f4 v[146:149], v[2:9], v[162:169], v[146:149], v229, v229 op_sel_hi:[0,0,0]
	v_mfma_scale_f32_16x16x128_f8f6f4 v[138:141], v[10:17], v[162:169], v[138:141], v229, v229 op_sel_hi:[0,0,0]
	v_mfma_scale_f32_16x16x128_f8f6f4 v[130:133], v[2:9], v[170:177], v[130:133], v229, v229 op_sel_hi:[0,0,0]
	v_mfma_scale_f32_16x16x128_f8f6f4 v[122:125], v[10:17], v[170:177], v[122:125], v229, v229 op_sel_hi:[0,0,0]
	v_mfma_scale_f32_16x16x128_f8f6f4 v[114:117], v[2:9], v[178:185], v[114:117], v229, v229 op_sel_hi:[0,0,0]
	v_mfma_scale_f32_16x16x128_f8f6f4 v[106:109], v[10:17], v[178:185], v[106:109], v229, v229 op_sel_hi:[0,0,0]
	v_mfma_scale_f32_16x16x128_f8f6f4 v[102:105], v[2:9], v[206:213], v[102:105], v229, v229 op_sel_hi:[0,0,0]
	v_mfma_scale_f32_16x16x128_f8f6f4 v[98:101], v[10:17], v[206:213], v[98:101], v229, v229 op_sel_hi:[0,0,0]
	s_setprio 0
	s_barrier
	s_add_i32 s75, s40, s27
	v_lshl_add_u64 v[162:163], s[22:23], 0, v[192:193]
	s_mov_b32 m0, s75
	ds_read_b128 v[170:173], v235 offset:16384
	ds_read_b128 v[174:177], v235 offset:17408
	ds_read_b128 v[178:181], v235 offset:18432
	ds_read_b128 v[182:185], v235 offset:19456
	ds_read_b128 v[206:209], v235 offset:20480
	ds_read_b128 v[210:213], v235 offset:21504
	ds_read_b128 v[214:217], v235 offset:22528
	ds_read_b128 v[218:221], v235 offset:23552
	global_load_lds_dwordx4 v[162:163], off
	s_add_i32 m0, s75, 0x2000
	s_add_u32 s78, s22, 0xb0000
	v_lshl_add_u64 v[164:165], s[22:23], 0, v[196:197]
	s_addc_u32 s79, s23, 0
	s_add_i32 s75, s41, s27
	global_load_lds_dwordx4 v[164:165], off
	v_lshl_add_u64 v[166:167], s[78:79], 0, v[192:193]
	s_mov_b32 m0, s75
	v_lshl_add_u64 v[168:169], s[24:25], 0, v[194:195]
	global_load_lds_dwordx4 v[166:167], off
	v_lshl_add_u64 v[166:167], s[78:79], 0, v[196:197]
	s_add_i32 m0, s75, 0x2000
	s_nop 0
	global_load_lds_dwordx4 v[166:167], off
	v_lshl_add_u64 v[166:167], s[24:25], 0, v[190:191]
	s_mov_b32 m0, s28
	s_nop 0
	global_load_lds_dwordx4 v[166:167], off
	s_mov_b32 m0, s29
	s_nop 0
	global_load_lds_dwordx4 v[168:169], off
	s_waitcnt vmcnt(8)
	s_waitcnt lgkmcnt(0)
	s_barrier
	s_setprio 1
	s_waitcnt lgkmcnt(0)
	v_mfma_scale_f32_16x16x128_f8f6f4 v[94:97], v[18:25], v[170:177], v[94:97], v229, v229 op_sel_hi:[0,0,0]
	v_mfma_scale_f32_16x16x128_f8f6f4 v[90:93], v[26:33], v[170:177], v[90:93], v229, v229 op_sel_hi:[0,0,0]
	v_mfma_scale_f32_16x16x128_f8f6f4 v[86:89], v[18:25], v[178:185], v[86:89], v229, v229 op_sel_hi:[0,0,0]
	v_mfma_scale_f32_16x16x128_f8f6f4 v[78:81], v[26:33], v[178:185], v[78:81], v229, v229 op_sel_hi:[0,0,0]
	v_mfma_scale_f32_16x16x128_f8f6f4 v[70:73], v[18:25], v[206:213], v[70:73], v229, v229 op_sel_hi:[0,0,0]
	v_mfma_scale_f32_16x16x128_f8f6f4 v[62:65], v[26:33], v[206:213], v[62:65], v229, v229 op_sel_hi:[0,0,0]
	v_mfma_scale_f32_16x16x128_f8f6f4 v[54:57], v[18:25], v[214:221], v[54:57], v229, v229 op_sel_hi:[0,0,0]
	v_mfma_scale_f32_16x16x128_f8f6f4 v[46:49], v[26:33], v[214:221], v[46:49], v229, v229 op_sel_hi:[0,0,0]
	v_mfma_scale_f32_16x16x128_f8f6f4 v[82:85], v[2:9], v[170:177], v[82:85], v229, v229 op_sel_hi:[0,0,0]
	v_mfma_scale_f32_16x16x128_f8f6f4 v[74:77], v[10:17], v[170:177], v[74:77], v229, v229 op_sel_hi:[0,0,0]
	v_mfma_scale_f32_16x16x128_f8f6f4 v[66:69], v[2:9], v[178:185], v[66:69], v229, v229 op_sel_hi:[0,0,0]
	v_mfma_scale_f32_16x16x128_f8f6f4 v[58:61], v[10:17], v[178:185], v[58:61], v229, v229 op_sel_hi:[0,0,0]
	v_mfma_scale_f32_16x16x128_f8f6f4 v[50:53], v[2:9], v[206:213], v[50:53], v229, v229 op_sel_hi:[0,0,0]
	v_mfma_scale_f32_16x16x128_f8f6f4 v[42:45], v[10:17], v[206:213], v[42:45], v229, v229 op_sel_hi:[0,0,0]
	v_mfma_scale_f32_16x16x128_f8f6f4 v[38:41], v[2:9], v[214:221], v[38:41], v229, v229 op_sel_hi:[0,0,0]
	v_mfma_scale_f32_16x16x128_f8f6f4 v[34:37], v[10:17], v[214:221], v[34:37], v229, v229 op_sel_hi:[0,0,0]
	s_setprio 0
	s_barrier
; #define PG8_STAGE(bufoff, gbase, voff) do { _Pragma("unroll") for (int _i = 0; _i < 2; ++_i) \
;         __builtin_amdgcn_global_load_lds((const unsigned*)((const char*)(gbase) + (voff)[_i]), (PG8_LAS unsigned*)(lds + (bufoff) + ldsw + _i * 8192), 16, 0, 0); } while (0)
; #define PG8_WAIT_V(n) asm volatile("s_waitcnt vmcnt(" #n ")" ::: "memory")
; #define PG8_WAIT_L(n) asm volatile("s_waitcnt lgkmcnt(" #n ")" ::: "memory")
; #define PG8_BAR __builtin_amdgcn_s_barrier()
; #define PG8_SCHED __builtin_amdgcn_sched_barrier(0)
; template <class Epi, class Sched, bool ALIGN_EPI = true, bool SP2 = true>
; __device__ __forceinline__ void gemm_phase(PG8_LAS unsigned char* lds, const int K  , const Sched& S, const Epi& E) {
;     ...
;             PG8_LDB(B0, 1, 0); PG8_LDB(B1, 1, 1); PG8_SCHED; PG8_LDA(At, 1, 0); PG8_STAGE(PG8_SA(0, 1), a2 + hstep, voffA);
;             PG8_WAIT_V(8); PG8_WAIT_L(0); PG8_BAR; PG8_MMA(0, 0, At, B0); PG8_MMA(0, 1, At, B1); PG8_BAR; PG8_SCHED;
;             PG8_LDA(At, 1, 1); PG8_STAGE(PG8_SB(1, 0), b3, voffB); PG8_STAGE(PG8_SB(1, 1), b3 + hstep, voffB); PG8_STAGE(PG8_SA(1, 0), a3, voffA);
;             PG8_WAIT_V(8); PG8_WAIT_L(0); PG8_BAR; PG8_MMA(1, 0, At, B0); PG8_MMA(1, 1, At, B1); PG8_BAR; PG8_SCHED;
;     ...
;         if constexpr (Epi::FP8) asm volatile("s_nop 15\n\ts_nop 15\n\ts_nop 15\n\ts_nop 15\n\ts_nop 15" ::: "memory");
;         if constexpr (ALIGN_EPI) { if (wr == 0) PG8_BAR; }
	s_add_i32 s75, 0, 0x18000
	s_add_i32 s78, 0, 0x1c000
	v_add_u32_e32 v14, s75, v231
	v_add_u32_e32 v30, s78, v231
	ds_read_b128 v[2:5], v14
	ds_read_b128 v[6:9], v14 offset:1024
	ds_read_b128 v[10:13], v14 offset:2048
	ds_read_b128 v[14:17], v14 offset:3072
	ds_read_b128 v[18:21], v30
	ds_read_b128 v[22:25], v30 offset:1024
	ds_read_b128 v[26:29], v30 offset:2048
	ds_read_b128 v[30:33], v30 offset:3072
	s_add_u32 s24, s24, 0xb0000
	s_addc_u32 s25, s25, 0
	s_mov_b32 m0, s30
	v_lshl_add_u64 v[186:187], s[24:25], 0, v[190:191]
	ds_read_b128 v[170:173], v235 offset:32768
	ds_read_b128 v[174:177], v235 offset:33792
	ds_read_b128 v[178:181], v235 offset:34816
	ds_read_b128 v[182:185], v235 offset:35840
	ds_read_b128 v[206:209], v235 offset:36864
	ds_read_b128 v[210:213], v235 offset:37888
	ds_read_b128 v[214:217], v235 offset:38912
	ds_read_b128 v[218:221], v235 offset:39936
	global_load_lds_dwordx4 v[186:187], off
	v_lshl_add_u64 v[186:187], s[24:25], 0, v[194:195]
	s_mov_b32 m0, s31
	s_nop 0
	global_load_lds_dwordx4 v[186:187], off
	s_waitcnt vmcnt(8)
	s_waitcnt lgkmcnt(0)
	s_barrier
	s_setprio 1
	s_waitcnt lgkmcnt(0)
	v_mfma_scale_f32_16x16x128_f8f6f4 v[158:161], v[2:9], v[170:177], v[158:161], v229, v229 op_sel_hi:[0,0,0]
	v_mfma_scale_f32_16x16x128_f8f6f4 v[154:157], v[10:17], v[170:177], v[154:157], v229, v229 op_sel_hi:[0,0,0]
	v_mfma_scale_f32_16x16x128_f8f6f4 v[150:153], v[2:9], v[178:185], v[150:153], v229, v229 op_sel_hi:[0,0,0]
	v_mfma_scale_f32_16x16x128_f8f6f4 v[142:145], v[10:17], v[178:185], v[142:145], v229, v229 op_sel_hi:[0,0,0]
	v_mfma_scale_f32_16x16x128_f8f6f4 v[134:137], v[2:9], v[206:213], v[134:137], v229, v229 op_sel_hi:[0,0,0]
	v_mfma_scale_f32_16x16x128_f8f6f4 v[126:129], v[10:17], v[206:213], v[126:129], v229, v229 op_sel_hi:[0,0,0]
	v_mfma_scale_f32_16x16x128_f8f6f4 v[118:121], v[2:9], v[214:221], v[118:121], v229, v229 op_sel_hi:[0,0,0]
	v_mfma_scale_f32_16x16x128_f8f6f4 v[110:113], v[10:17], v[214:221], v[110:113], v229, v229 op_sel_hi:[0,0,0]
	v_mfma_scale_f32_16x16x128_f8f6f4 v[146:149], v[18:25], v[170:177], v[146:149], v229, v229 op_sel_hi:[0,0,0]
	v_mfma_scale_f32_16x16x128_f8f6f4 v[138:141], v[26:33], v[170:177], v[138:141], v229, v229 op_sel_hi:[0,0,0]
	v_mfma_scale_f32_16x16x128_f8f6f4 v[130:133], v[18:25], v[178:185], v[130:133], v229, v229 op_sel_hi:[0,0,0]
	v_mfma_scale_f32_16x16x128_f8f6f4 v[122:125], v[26:33], v[178:185], v[122:125], v229, v229 op_sel_hi:[0,0,0]
	v_mfma_scale_f32_16x16x128_f8f6f4 v[114:117], v[18:25], v[206:213], v[114:117], v229, v229 op_sel_hi:[0,0,0]
	v_mfma_scale_f32_16x16x128_f8f6f4 v[106:109], v[26:33], v[206:213], v[106:109], v229, v229 op_sel_hi:[0,0,0]
	v_mfma_scale_f32_16x16x128_f8f6f4 v[102:105], v[18:25], v[214:221], v[102:105], v229, v229 op_sel_hi:[0,0,0]
	v_mfma_scale_f32_16x16x128_f8f6f4 v[98:101], v[26:33], v[214:221], v[98:101], v229, v229 op_sel_hi:[0,0,0]
	s_setprio 0
	s_barrier
	s_add_i32 s24, s75, s27
	v_lshl_add_u64 v[162:163], v[162:163], 0, s[10:11]
	s_mov_b32 m0, s24
	ds_read_b128 v[170:173], v235 offset:49152
	ds_read_b128 v[174:177], v235 offset:50176
	ds_read_b128 v[178:181], v235 offset:51200
	ds_read_b128 v[182:185], v235 offset:52224
	ds_read_b128 v[206:209], v235 offset:53248
	ds_read_b128 v[210:213], v235 offset:54272
	ds_read_b128 v[214:217], v235 offset:55296
	ds_read_b128 v[218:221], v235 offset:56320
	global_load_lds_dwordx4 v[162:163], off
	s_add_i32 m0, s24, 0x2000
	s_add_u32 s22, s22, 0xb0080
	v_lshl_add_u64 v[162:163], v[164:165], 0, s[10:11]
	s_addc_u32 s23, s23, 0
	s_add_i32 s24, s78, s27
	global_load_lds_dwordx4 v[162:163], off
	v_lshl_add_u64 v[162:163], s[22:23], 0, v[192:193]
	s_mov_b32 m0, s24
	s_nop 0
	global_load_lds_dwordx4 v[162:163], off
	v_lshl_add_u64 v[162:163], s[22:23], 0, v[196:197]
	s_add_i32 m0, s24, 0x2000
	s_nop 0
	global_load_lds_dwordx4 v[162:163], off
	v_lshl_add_u64 v[162:163], v[166:167], 0, s[10:11]
	s_mov_b32 m0, s36
	s_nop 0
	global_load_lds_dwordx4 v[162:163], off
	v_lshl_add_u64 v[162:163], v[168:169], 0, s[10:11]
	s_mov_b32 m0, s37
	s_nop 0
	global_load_lds_dwordx4 v[162:163], off
	s_waitcnt vmcnt(8)
	s_waitcnt lgkmcnt(0)
	s_barrier
	s_setprio 1
	s_waitcnt lgkmcnt(0)
	v_mfma_scale_f32_16x16x128_f8f6f4 v[94:97], v[2:9], v[170:177], v[94:97], v229, v229 op_sel_hi:[0,0,0]
	v_mfma_scale_f32_16x16x128_f8f6f4 v[90:93], v[10:17], v[170:177], v[90:93], v229, v229 op_sel_hi:[0,0,0]
	v_mfma_scale_f32_16x16x128_f8f6f4 v[86:89], v[2:9], v[178:185], v[86:89], v229, v229 op_sel_hi:[0,0,0]
	v_mfma_scale_f32_16x16x128_f8f6f4 v[78:81], v[10:17], v[178:185], v[78:81], v229, v229 op_sel_hi:[0,0,0]
	v_mfma_scale_f32_16x16x128_f8f6f4 v[70:73], v[2:9], v[206:213], v[70:73], v229, v229 op_sel_hi:[0,0,0]
	v_mfma_scale_f32_16x16x128_f8f6f4 v[62:65], v[10:17], v[206:213], v[62:65], v229, v229 op_sel_hi:[0,0,0]
	v_mfma_scale_f32_16x16x128_f8f6f4 v[54:57], v[2:9], v[214:221], v[54:57], v229, v229 op_sel_hi:[0,0,0]
	v_mfma_scale_f32_16x16x128_f8f6f4 v[46:49], v[10:17], v[214:221], v[46:49], v229, v229 op_sel_hi:[0,0,0]
	v_mfma_scale_f32_16x16x128_f8f6f4 v[82:85], v[18:25], v[170:177], v[82:85], v229, v229 op_sel_hi:[0,0,0]
	v_mfma_scale_f32_16x16x128_f8f6f4 v[74:77], v[26:33], v[170:177], v[74:77], v229, v229 op_sel_hi:[0,0,0]
	v_mfma_scale_f32_16x16x128_f8f6f4 v[66:69], v[18:25], v[178:185], v[66:69], v229, v229 op_sel_hi:[0,0,0]
	v_mfma_scale_f32_16x16x128_f8f6f4 v[58:61], v[26:33], v[178:185], v[58:61], v229, v229 op_sel_hi:[0,0,0]
	v_mfma_scale_f32_16x16x128_f8f6f4 v[50:53], v[18:25], v[206:213], v[50:53], v229, v229 op_sel_hi:[0,0,0]
	v_mfma_scale_f32_16x16x128_f8f6f4 v[42:45], v[26:33], v[206:213], v[42:45], v229, v229 op_sel_hi:[0,0,0]
	v_mfma_scale_f32_16x16x128_f8f6f4 v[38:41], v[18:25], v[214:221], v[38:41], v229, v229 op_sel_hi:[0,0,0]
	v_mfma_scale_f32_16x16x128_f8f6f4 v[34:37], v[26:33], v[214:221], v[34:37], v229, v229 op_sel_hi:[0,0,0]
	s_setprio 0
	s_barrier
	s_add_u32 s20, s20, 0x100
	s_addc_u32 s21, s21, 0
	s_add_u32 s72, s72, 0x100
	s_addc_u32 s73, s73, 0
	s_cmp_ge_u32 s74, s4
	s_mov_b32 s24, s74
	s_cbranch_scc0 .LBB0_1695
	s_nop 15
	s_nop 15
	s_nop 15
	s_nop 15
	s_nop 15
	s_and_b64 vcc, exec, s[12:13]
	s_cbranch_vccz .LBB0_1698
	s_barrier

; #define PG8_STAGE(bufoff, gbase, voff) do { _Pragma("unroll") for (int _i = 0; _i < 2; ++_i) \
;         __builtin_amdgcn_global_load_lds((const unsigned*)((const char*)(gbase) + (voff)[_i]), (PG8_LAS unsigned*)(lds + (bufoff) + ldsw + _i * 8192), 16, 0, 0); } while (0)
; #define PG8_WAIT_V(n) asm volatile("s_waitcnt vmcnt(" #n ")" ::: "memory")
; #define PG8_WAIT_L(n) asm volatile("s_waitcnt lgkmcnt(" #n ")" ::: "memory")
; #define PG8_BAR __builtin_amdgcn_s_barrier()
; #define PG8_SCHED __builtin_amdgcn_sched_barrier(0)
; template <class Epi, class Sched, bool ALIGN_EPI = true, bool SP2 = true>
; __device__ __forceinline__ void gemm_phase(PG8_LAS unsigned char* lds, const int K  , const Sched& S, const Epi& E) {
;     ...
;             PG8_LDB(B0, 0, 0); PG8_LDB(B1, 0, 1); PG8_SCHED; PG8_LDA(At, 0, 0); PG8_STAGE(PG8_SA(1, 1), a1 + hstep, voffA);
;             PG8_WAIT_V(8); PG8_WAIT_L(0); PG8_BAR; PG8_MMA(0, 0, At, B0); PG8_MMA(0, 1, At, B1); PG8_BAR; PG8_SCHED;
;             PG8_LDA(At, 0, 1); PG8_STAGE(PG8_SB(0, 0), b2, voffB); PG8_STAGE(PG8_SB(0, 1), b2 + hstep, voffB); PG8_STAGE(PG8_SA(0, 0), a2, voffA);
;             PG8_WAIT_V(8); PG8_WAIT_L(0); PG8_BAR; PG8_MMA(1, 0, At, B0); PG8_MMA(1, 1, At, B1); PG8_BAR; PG8_SCHED;
.LBB0_1847:
	ds_read_b128 v[130:133], v176
	ds_read_b128 v[134:137], v176 offset:1024
	ds_read_b128 v[138:141], v176 offset:2048
	ds_read_b128 v[142:145], v176 offset:3072
	ds_read_b128 v[168:171], v177
	ds_read_b128 v[184:187], v177 offset:1024
	ds_read_b128 v[188:191], v177 offset:2048
	ds_read_b128 v[192:195], v177 offset:3072
	s_add_u32 s22, s0, 0xfff80080
	s_addc_u32 s23, s1, -1
	s_cmp_eq_u32 s51, 28
	s_cselect_b32 s25, s7, s23
	s_cselect_b32 s24, s47, s22
	s_cselect_b32 s23, s11, s50
	s_cselect_b32 s22, s48, s49
	v_lshl_add_u64 v[230:231], s[0:1], 0, v[160:161]
	s_add_i32 m0, s27, 0xc000
	ds_read_b128 v[196:199], v178
	ds_read_b128 v[200:203], v178 offset:1024
	ds_read_b128 v[204:207], v178 offset:2048
	ds_read_b128 v[208:211], v178 offset:3072
	ds_read_b128 v[212:215], v178 offset:4096
	ds_read_b128 v[216:219], v178 offset:5120
	ds_read_b128 v[220:223], v178 offset:6144
	ds_read_b128 v[224:227], v178 offset:7168
	global_load_lds_dwordx4 v[230:231], off
	v_lshl_add_u64 v[230:231], s[0:1], 0, v[162:163]
	s_add_i32 m0, s27, 0xe000
	s_nop 0
	global_load_lds_dwordx4 v[230:231], off
	s_waitcnt vmcnt(8)
	s_waitcnt lgkmcnt(0)
	s_barrier
	s_setprio 1
	s_waitcnt lgkmcnt(0)
	v_mfma_f32_16x16x32_bf16 v[126:129], v[130:133], v[196:199], v[126:129]
	v_mfma_f32_16x16x32_bf16 v[122:125], v[138:141], v[196:199], v[122:125]
	v_mfma_f32_16x16x32_bf16 v[110:113], v[130:133], v[204:207], v[110:113]
	v_mfma_f32_16x16x32_bf16 v[106:109], v[138:141], v[204:207], v[106:109]
	v_mfma_f32_16x16x32_bf16 v[94:97], v[130:133], v[212:215], v[94:97]
	v_mfma_f32_16x16x32_bf16 v[90:93], v[138:141], v[212:215], v[90:93]
	v_mfma_f32_16x16x32_bf16 v[78:81], v[130:133], v[220:223], v[78:81]
	v_mfma_f32_16x16x32_bf16 v[74:77], v[138:141], v[220:223], v[74:77]
	v_mfma_f32_16x16x32_bf16 v[126:129], v[134:137], v[200:203], v[126:129]
	v_mfma_f32_16x16x32_bf16 v[122:125], v[142:145], v[200:203], v[122:125]
	v_mfma_f32_16x16x32_bf16 v[110:113], v[134:137], v[208:211], v[110:113]
	v_mfma_f32_16x16x32_bf16 v[106:109], v[142:145], v[208:211], v[106:109]
	v_mfma_f32_16x16x32_bf16 v[94:97], v[134:137], v[216:219], v[94:97]
	v_mfma_f32_16x16x32_bf16 v[90:93], v[142:145], v[216:219], v[90:93]
	v_mfma_f32_16x16x32_bf16 v[78:81], v[134:137], v[224:227], v[78:81]
	v_mfma_f32_16x16x32_bf16 v[74:77], v[142:145], v[224:227], v[74:77]
	v_mfma_f32_16x16x32_bf16 v[118:121], v[168:171], v[196:199], v[118:121]
	v_mfma_f32_16x16x32_bf16 v[114:117], v[188:191], v[196:199], v[114:117]
	v_mfma_f32_16x16x32_bf16 v[102:105], v[168:171], v[204:207], v[102:105]
	v_mfma_f32_16x16x32_bf16 v[98:101], v[188:191], v[204:207], v[98:101]
	v_mfma_f32_16x16x32_bf16 v[86:89], v[168:171], v[212:215], v[86:89]
	v_mfma_f32_16x16x32_bf16 v[82:85], v[188:191], v[212:215], v[82:85]
	v_mfma_f32_16x16x32_bf16 v[70:73], v[168:171], v[220:223], v[70:73]
	v_mfma_f32_16x16x32_bf16 v[66:69], v[188:191], v[220:223], v[66:69]
	v_mfma_f32_16x16x32_bf16 v[118:121], v[184:187], v[200:203], v[118:121]
	v_mfma_f32_16x16x32_bf16 v[114:117], v[192:195], v[200:203], v[114:117]
	v_mfma_f32_16x16x32_bf16 v[102:105], v[184:187], v[208:211], v[102:105]
	v_mfma_f32_16x16x32_bf16 v[98:101], v[192:195], v[208:211], v[98:101]
	v_mfma_f32_16x16x32_bf16 v[86:89], v[184:187], v[216:219], v[86:89]
	v_mfma_f32_16x16x32_bf16 v[82:85], v[192:195], v[216:219], v[82:85]
	v_mfma_f32_16x16x32_bf16 v[70:73], v[184:187], v[224:227], v[70:73]
	v_mfma_f32_16x16x32_bf16 v[66:69], v[192:195], v[224:227], v[66:69]
	s_setprio 0
	s_barrier
	s_add_i32 s68, s39, s26
	v_lshl_add_u64 v[230:231], s[22:23], 0, v[150:151]
	s_mov_b32 m0, s68
	ds_read_b128 v[196:199], v178 offset:16384
	ds_read_b128 v[200:203], v178 offset:17408
	ds_read_b128 v[204:207], v178 offset:18432
	ds_read_b128 v[208:211], v178 offset:19456
	ds_read_b128 v[212:215], v178 offset:20480
	ds_read_b128 v[216:219], v178 offset:21504
	ds_read_b128 v[220:223], v178 offset:22528
	ds_read_b128 v[224:227], v178 offset:23552
	global_load_lds_dwordx4 v[230:231], off
	s_add_i32 m0, s68, 0x2000
	s_add_u32 s68, s22, 0x80000
	v_lshl_add_u64 v[232:233], s[22:23], 0, v[154:155]
	s_addc_u32 s69, s23, 0
	s_add_i32 s70, s40, s26
	global_load_lds_dwordx4 v[232:233], off
	v_lshl_add_u64 v[234:235], s[68:69], 0, v[150:151]
	s_mov_b32 m0, s70
	v_lshl_add_u64 v[236:237], s[24:25], 0, v[152:153]
	global_load_lds_dwordx4 v[234:235], off
	v_lshl_add_u64 v[234:235], s[68:69], 0, v[154:155]
	s_add_i32 m0, s70, 0x2000
	s_nop 0
	global_load_lds_dwordx4 v[234:235], off
	v_lshl_add_u64 v[234:235], s[24:25], 0, v[148:149]
	s_mov_b32 m0, s27
	s_nop 0
	global_load_lds_dwordx4 v[234:235], off
	s_mov_b32 m0, s28
	s_nop 0
	global_load_lds_dwordx4 v[236:237], off
	s_waitcnt vmcnt(8)
	s_waitcnt lgkmcnt(0)
	s_barrier
; #define PG8_STAGE(bufoff, gbase, voff) do { _Pragma("unroll") for (int _i = 0; _i < 2; ++_i) \
;         __builtin_amdgcn_global_load_lds((const unsigned*)((const char*)(gbase) + (voff)[_i]), (PG8_LAS unsigned*)(lds + (bufoff) + ldsw + _i * 8192), 16, 0, 0); } while (0)
; #define PG8_WAIT_V(n) asm volatile("s_waitcnt vmcnt(" #n ")" ::: "memory")
; #define PG8_WAIT_L(n) asm volatile("s_waitcnt lgkmcnt(" #n ")" ::: "memory")
; #define PG8_BAR __builtin_amdgcn_s_barrier()
; #define PG8_SCHED __builtin_amdgcn_sched_barrier(0)
; template <class Epi, class Sched, bool ALIGN_EPI = true, bool SP2 = true>
; __device__ __forceinline__ void gemm_phase(PG8_LAS unsigned char* lds, const int K  , const Sched& S, const Epi& E) {
;     ...
;             PG8_WAIT_V(8); PG8_WAIT_L(0); PG8_BAR; PG8_MMA(1, 0, At, B0); PG8_MMA(1, 1, At, B1); PG8_BAR; PG8_SCHED;
;             PG8_LDB(B0, 1, 0); PG8_LDB(B1, 1, 1); PG8_SCHED; PG8_LDA(At, 1, 0); PG8_STAGE(PG8_SA(0, 1), a2 + hstep, voffA);
;             PG8_WAIT_V(8); PG8_WAIT_L(0); PG8_BAR; PG8_MMA(0, 0, At, B0); PG8_MMA(0, 1, At, B1); PG8_BAR; PG8_SCHED;
	s_setprio 1
	s_waitcnt lgkmcnt(0)
	v_mfma_f32_16x16x32_bf16 v[62:65], v[130:133], v[196:199], v[62:65]
	v_mfma_f32_16x16x32_bf16 v[58:61], v[138:141], v[196:199], v[58:61]
	v_mfma_f32_16x16x32_bf16 v[46:49], v[130:133], v[204:207], v[46:49]
	v_mfma_f32_16x16x32_bf16 v[42:45], v[138:141], v[204:207], v[42:45]
	v_mfma_f32_16x16x32_bf16 v[30:33], v[130:133], v[212:215], v[30:33]
	v_mfma_f32_16x16x32_bf16 v[26:29], v[138:141], v[212:215], v[26:29]
	v_mfma_f32_16x16x32_bf16 v[14:17], v[130:133], v[220:223], v[14:17]
	v_mfma_f32_16x16x32_bf16 v[10:13], v[138:141], v[220:223], v[10:13]
	v_mfma_f32_16x16x32_bf16 v[62:65], v[134:137], v[200:203], v[62:65]
	v_mfma_f32_16x16x32_bf16 v[58:61], v[142:145], v[200:203], v[58:61]
	v_mfma_f32_16x16x32_bf16 v[46:49], v[134:137], v[208:211], v[46:49]
	v_mfma_f32_16x16x32_bf16 v[42:45], v[142:145], v[208:211], v[42:45]
	v_mfma_f32_16x16x32_bf16 v[30:33], v[134:137], v[216:219], v[30:33]
	v_mfma_f32_16x16x32_bf16 v[26:29], v[142:145], v[216:219], v[26:29]
	v_mfma_f32_16x16x32_bf16 v[14:17], v[134:137], v[224:227], v[14:17]
	v_mfma_f32_16x16x32_bf16 v[10:13], v[142:145], v[224:227], v[10:13]
	v_mfma_f32_16x16x32_bf16 v[54:57], v[168:171], v[196:199], v[54:57]
	v_mfma_f32_16x16x32_bf16 v[50:53], v[188:191], v[196:199], v[50:53]
	v_mfma_f32_16x16x32_bf16 v[38:41], v[168:171], v[204:207], v[38:41]
	v_mfma_f32_16x16x32_bf16 v[34:37], v[188:191], v[204:207], v[34:37]
	v_mfma_f32_16x16x32_bf16 v[22:25], v[168:171], v[212:215], v[22:25]
	v_mfma_f32_16x16x32_bf16 v[18:21], v[188:191], v[212:215], v[18:21]
	v_mfma_f32_16x16x32_bf16 v[6:9], v[168:171], v[220:223], v[6:9]
	v_mfma_f32_16x16x32_bf16 v[2:5], v[188:191], v[220:223], v[2:5]
	v_mfma_f32_16x16x32_bf16 v[54:57], v[184:187], v[200:203], v[54:57]
	v_mfma_f32_16x16x32_bf16 v[50:53], v[192:195], v[200:203], v[50:53]
	v_mfma_f32_16x16x32_bf16 v[38:41], v[184:187], v[208:211], v[38:41]
	v_mfma_f32_16x16x32_bf16 v[34:37], v[192:195], v[208:211], v[34:37]
	v_mfma_f32_16x16x32_bf16 v[22:25], v[184:187], v[216:219], v[22:25]
	v_mfma_f32_16x16x32_bf16 v[18:21], v[192:195], v[216:219], v[18:21]
	v_mfma_f32_16x16x32_bf16 v[6:9], v[184:187], v[224:227], v[6:9]
	v_mfma_f32_16x16x32_bf16 v[2:5], v[192:195], v[224:227], v[2:5]
	s_setprio 0
	s_barrier
	s_add_i32 s68, 0, 0x18000
	s_add_i32 s69, 0, 0x1c000
	v_add_u32_e32 v142, s68, v172
	v_add_u32_e32 v192, s69, v172
	ds_read_b128 v[130:133], v142
	ds_read_b128 v[134:137], v142 offset:1024
	ds_read_b128 v[138:141], v142 offset:2048
	ds_read_b128 v[142:145], v142 offset:3072
	ds_read_b128 v[168:171], v192
	ds_read_b128 v[184:187], v192 offset:1024
	ds_read_b128 v[188:191], v192 offset:2048
	ds_read_b128 v[192:195], v192 offset:3072
	s_add_u32 s24, s24, 0x80000
	s_addc_u32 s25, s25, 0
	s_mov_b32 m0, s29
	v_lshl_add_u64 v[238:239], s[24:25], 0, v[148:149]
	ds_read_b128 v[196:199], v178 offset:32768
	ds_read_b128 v[200:203], v178 offset:33792
	ds_read_b128 v[204:207], v178 offset:34816
	ds_read_b128 v[208:211], v178 offset:35840
	ds_read_b128 v[212:215], v178 offset:36864
	ds_read_b128 v[216:219], v178 offset:37888
	ds_read_b128 v[220:223], v178 offset:38912
	ds_read_b128 v[224:227], v178 offset:39936
	global_load_lds_dwordx4 v[238:239], off
	v_lshl_add_u64 v[238:239], s[24:25], 0, v[152:153]
	s_mov_b32 m0, s30
	s_nop 0
	global_load_lds_dwordx4 v[238:239], off
	s_waitcnt vmcnt(8)
	s_waitcnt lgkmcnt(0)
	s_barrier
	s_setprio 1
	s_waitcnt lgkmcnt(0)
	v_mfma_f32_16x16x32_bf16 v[126:129], v[130:133], v[196:199], v[126:129]
	v_mfma_f32_16x16x32_bf16 v[122:125], v[138:141], v[196:199], v[122:125]
	v_mfma_f32_16x16x32_bf16 v[110:113], v[130:133], v[204:207], v[110:113]
	v_mfma_f32_16x16x32_bf16 v[106:109], v[138:141], v[204:207], v[106:109]
	v_mfma_f32_16x16x32_bf16 v[94:97], v[130:133], v[212:215], v[94:97]
	v_mfma_f32_16x16x32_bf16 v[90:93], v[138:141], v[212:215], v[90:93]
	v_mfma_f32_16x16x32_bf16 v[78:81], v[130:133], v[220:223], v[78:81]
	v_mfma_f32_16x16x32_bf16 v[74:77], v[138:141], v[220:223], v[74:77]
	v_mfma_f32_16x16x32_bf16 v[126:129], v[134:137], v[200:203], v[126:129]
	v_mfma_f32_16x16x32_bf16 v[122:125], v[142:145], v[200:203], v[122:125]
	v_mfma_f32_16x16x32_bf16 v[110:113], v[134:137], v[208:211], v[110:113]
	v_mfma_f32_16x16x32_bf16 v[106:109], v[142:145], v[208:211], v[106:109]
	v_mfma_f32_16x16x32_bf16 v[94:97], v[134:137], v[216:219], v[94:97]
	v_mfma_f32_16x16x32_bf16 v[90:93], v[142:145], v[216:219], v[90:93]
	v_mfma_f32_16x16x32_bf16 v[78:81], v[134:137], v[224:227], v[78:81]
	v_mfma_f32_16x16x32_bf16 v[74:77], v[142:145], v[224:227], v[74:77]
	v_mfma_f32_16x16x32_bf16 v[118:121], v[168:171], v[196:199], v[118:121]
	v_mfma_f32_16x16x32_bf16 v[114:117], v[188:191], v[196:199], v[114:117]
	v_mfma_f32_16x16x32_bf16 v[102:105], v[168:171], v[204:207], v[102:105]
	v_mfma_f32_16x16x32_bf16 v[98:101], v[188:191], v[204:207], v[98:101]
	v_mfma_f32_16x16x32_bf16 v[86:89], v[168:171], v[212:215], v[86:89]
	v_mfma_f32_16x16x32_bf16 v[82:85], v[188:191], v[212:215], v[82:85]
	v_mfma_f32_16x16x32_bf16 v[70:73], v[168:171], v[220:223], v[70:73]
	v_mfma_f32_16x16x32_bf16 v[66:69], v[188:191], v[220:223], v[66:69]
	v_mfma_f32_16x16x32_bf16 v[118:121], v[184:187], v[200:203], v[118:121]
	v_mfma_f32_16x16x32_bf16 v[114:117], v[192:195], v[200:203], v[114:117]
	v_mfma_f32_16x16x32_bf16 v[102:105], v[184:187], v[208:211], v[102:105]
	v_mfma_f32_16x16x32_bf16 v[98:101], v[192:195], v[208:211], v[98:101]
	v_mfma_f32_16x16x32_bf16 v[86:89], v[184:187], v[216:219], v[86:89]
	v_mfma_f32_16x16x32_bf16 v[82:85], v[192:195], v[216:219], v[82:85]
	v_mfma_f32_16x16x32_bf16 v[70:73], v[184:187], v[224:227], v[70:73]
	v_mfma_f32_16x16x32_bf16 v[66:69], v[192:195], v[224:227], v[66:69]
	s_setprio 0
	s_barrier
; #define PG8_STAGE(bufoff, gbase, voff) do { _Pragma("unroll") for (int _i = 0; _i < 2; ++_i) \
;         __builtin_amdgcn_global_load_lds((const unsigned*)((const char*)(gbase) + (voff)[_i]), (PG8_LAS unsigned*)(lds + (bufoff) + ldsw + _i * 8192), 16, 0, 0); } while (0)
; #define PG8_WAIT_V(n) asm volatile("s_waitcnt vmcnt(" #n ")" ::: "memory")
; #define PG8_WAIT_L(n) asm volatile("s_waitcnt lgkmcnt(" #n ")" ::: "memory")
; #define PG8_BAR __builtin_amdgcn_s_barrier()
; #define PG8_SCHED __builtin_amdgcn_sched_barrier(0)
;     __device__ __forceinline__ int nt(const pg8::Unit& u) const { return u.kind == 0 ? ntiles : q_nt(u.kind - 1); }
; template <class Epi, class Sched, bool ALIGN_EPI = true, bool SP2 = true>
; __device__ __forceinline__ void gemm_phase(PG8_LAS unsigned char* lds, const int K  , const Sched& S, const Epi& E) {
;     ...
;         for (int t = 0; t < nt; t += 2) {
;     ...
;             PG8_LDA(At, 1, 1); PG8_STAGE(PG8_SB(1, 0), b3, voffB); PG8_STAGE(PG8_SB(1, 1), b3 + hstep, voffB); PG8_STAGE(PG8_SA(1, 0), a3, voffA);
;             PG8_WAIT_V(8); PG8_WAIT_L(0); PG8_BAR; PG8_MMA(1, 0, At, B0); PG8_MMA(1, 1, At, B1); PG8_BAR; PG8_SCHED;
;     ...
;         if constexpr (Epi::FP8) asm volatile("s_nop 15\n\ts_nop 15\n\ts_nop 15\n\ts_nop 15\n\ts_nop 15" ::: "memory");
;         if constexpr (ALIGN_EPI) { if (wr == 0) PG8_BAR; }
	s_add_i32 s24, s68, s26
	v_lshl_add_u64 v[230:231], v[230:231], 0, s[4:5]
	s_mov_b32 m0, s24
	ds_read_b128 v[196:199], v178 offset:49152
	ds_read_b128 v[200:203], v178 offset:50176
	ds_read_b128 v[204:207], v178 offset:51200
	ds_read_b128 v[208:211], v178 offset:52224
	ds_read_b128 v[212:215], v178 offset:53248
	ds_read_b128 v[216:219], v178 offset:54272
	ds_read_b128 v[220:223], v178 offset:55296
	ds_read_b128 v[224:227], v178 offset:56320
	global_load_lds_dwordx4 v[230:231], off
	s_add_i32 m0, s24, 0x2000
	s_add_u32 s22, s22, 0x80080
	v_lshl_add_u64 v[230:231], v[232:233], 0, s[4:5]
	s_addc_u32 s23, s23, 0
	s_add_i32 s24, s69, s26
	global_load_lds_dwordx4 v[230:231], off
	v_lshl_add_u64 v[230:231], s[22:23], 0, v[150:151]
	s_mov_b32 m0, s24
	s_nop 0
	global_load_lds_dwordx4 v[230:231], off
	v_lshl_add_u64 v[230:231], s[22:23], 0, v[154:155]
	s_add_i32 m0, s24, 0x2000
	s_nop 0
	global_load_lds_dwordx4 v[230:231], off
	v_lshl_add_u64 v[230:231], v[234:235], 0, s[4:5]
	s_mov_b32 m0, s35
	s_nop 0
	global_load_lds_dwordx4 v[230:231], off
	v_lshl_add_u64 v[230:231], v[236:237], 0, s[4:5]
	s_mov_b32 m0, s36
	s_nop 0
	global_load_lds_dwordx4 v[230:231], off
	s_waitcnt vmcnt(8)
	s_waitcnt lgkmcnt(0)
	s_barrier
	s_setprio 1
	s_waitcnt lgkmcnt(0)
	v_mfma_f32_16x16x32_bf16 v[62:65], v[130:133], v[196:199], v[62:65]
	v_mfma_f32_16x16x32_bf16 v[58:61], v[138:141], v[196:199], v[58:61]
	v_mfma_f32_16x16x32_bf16 v[46:49], v[130:133], v[204:207], v[46:49]
	v_mfma_f32_16x16x32_bf16 v[42:45], v[138:141], v[204:207], v[42:45]
	v_mfma_f32_16x16x32_bf16 v[30:33], v[130:133], v[212:215], v[30:33]
	v_mfma_f32_16x16x32_bf16 v[26:29], v[138:141], v[212:215], v[26:29]
	v_mfma_f32_16x16x32_bf16 v[14:17], v[130:133], v[220:223], v[14:17]
	v_mfma_f32_16x16x32_bf16 v[10:13], v[138:141], v[220:223], v[10:13]
	v_mfma_f32_16x16x32_bf16 v[62:65], v[134:137], v[200:203], v[62:65]
	v_mfma_f32_16x16x32_bf16 v[58:61], v[142:145], v[200:203], v[58:61]
	v_mfma_f32_16x16x32_bf16 v[46:49], v[134:137], v[208:211], v[46:49]
	v_mfma_f32_16x16x32_bf16 v[42:45], v[142:145], v[208:211], v[42:45]
	v_mfma_f32_16x16x32_bf16 v[30:33], v[134:137], v[216:219], v[30:33]
	v_mfma_f32_16x16x32_bf16 v[26:29], v[142:145], v[216:219], v[26:29]
	v_mfma_f32_16x16x32_bf16 v[14:17], v[134:137], v[224:227], v[14:17]
	v_mfma_f32_16x16x32_bf16 v[10:13], v[142:145], v[224:227], v[10:13]
	v_mfma_f32_16x16x32_bf16 v[54:57], v[168:171], v[196:199], v[54:57]
	v_mfma_f32_16x16x32_bf16 v[50:53], v[188:191], v[196:199], v[50:53]
	v_mfma_f32_16x16x32_bf16 v[38:41], v[168:171], v[204:207], v[38:41]
	v_mfma_f32_16x16x32_bf16 v[34:37], v[188:191], v[204:207], v[34:37]
	v_mfma_f32_16x16x32_bf16 v[22:25], v[168:171], v[212:215], v[22:25]
	v_mfma_f32_16x16x32_bf16 v[18:21], v[188:191], v[212:215], v[18:21]
	v_mfma_f32_16x16x32_bf16 v[6:9], v[168:171], v[220:223], v[6:9]
	v_mfma_f32_16x16x32_bf16 v[2:5], v[188:191], v[220:223], v[2:5]
	v_mfma_f32_16x16x32_bf16 v[54:57], v[184:187], v[200:203], v[54:57]
	v_mfma_f32_16x16x32_bf16 v[50:53], v[192:195], v[200:203], v[50:53]
	v_mfma_f32_16x16x32_bf16 v[38:41], v[184:187], v[208:211], v[38:41]
	v_mfma_f32_16x16x32_bf16 v[34:37], v[192:195], v[208:211], v[34:37]
	v_mfma_f32_16x16x32_bf16 v[22:25], v[184:187], v[216:219], v[22:25]
	v_mfma_f32_16x16x32_bf16 v[18:21], v[192:195], v[216:219], v[18:21]
	v_mfma_f32_16x16x32_bf16 v[6:9], v[184:187], v[224:227], v[6:9]
	v_mfma_f32_16x16x32_bf16 v[2:5], v[192:195], v[224:227], v[2:5]
	s_setprio 0
	s_barrier
	s_add_i32 s51, s51, 2
	s_add_u32 s0, s0, 0x100
	s_addc_u32 s1, s1, 0
	s_add_u32 s49, s49, 0x100
	s_addc_u32 s50, s50, 0
	s_cmp_gt_u32 s51, 29
	s_cbranch_scc0 .LBB0_1847
	s_and_b64 vcc, exec, s[8:9]
	s_cbranch_vccz .LBB0_1850
	s_barrier

; #define PG8_STAGE(bufoff, gbase, voff) do { _Pragma("unroll") for (int _i = 0; _i < 2; ++_i) \
;         __builtin_amdgcn_global_load_lds((const unsigned*)((const char*)(gbase) + (voff)[_i]), (PG8_LAS unsigned*)(lds + (bufoff) + ldsw + _i * 8192), 16, 0, 0); } while (0)
; #define PG8_WAIT_V(n) asm volatile("s_waitcnt vmcnt(" #n ")" ::: "memory")
; #define PG8_WAIT_L(n) asm volatile("s_waitcnt lgkmcnt(" #n ")" ::: "memory")
; #define PG8_BAR __builtin_amdgcn_s_barrier()
; #define PG8_SCHED __builtin_amdgcn_sched_barrier(0)
; template <class Epi, class Sched, bool ALIGN_EPI = true, bool SP2 = true>
; __device__ __forceinline__ void gemm_phase(PG8_LAS unsigned char* lds, const int K  , const Sched& S, const Epi& E) {
;     ...
;             PG8_LDB(B0, 0, 0); PG8_LDB(B1, 0, 1); PG8_SCHED; PG8_LDA(At, 0, 0); PG8_STAGE(PG8_SA(1, 1), a1 + hstep, voffA);
;             PG8_WAIT_V(8); PG8_WAIT_L(0); PG8_BAR; PG8_MMA(0, 0, At, B0); PG8_MMA(0, 1, At, B1); PG8_BAR; PG8_SCHED;
;             PG8_LDA(At, 0, 1); PG8_STAGE(PG8_SB(0, 0), b2, voffB); PG8_STAGE(PG8_SB(0, 1), b2 + hstep, voffB); PG8_STAGE(PG8_SA(0, 0), a2, voffA);
;             PG8_WAIT_V(8); PG8_WAIT_L(0); PG8_BAR; PG8_MMA(1, 0, At, B0); PG8_MMA(1, 1, At, B1); PG8_BAR; PG8_SCHED;
.LBB0_2296:
	ds_read_b128 v[130:133], v203
	ds_read_b128 v[134:137], v203 offset:1024
	ds_read_b128 v[138:141], v203 offset:2048
	ds_read_b128 v[142:145], v203 offset:3072
	ds_read_b128 v[146:149], v204
	ds_read_b128 v[150:153], v204 offset:1024
	ds_read_b128 v[154:157], v204 offset:2048
	ds_read_b128 v[158:161], v204 offset:3072
	s_add_u32 s22, s20, 0xfff80080
	s_addc_u32 s23, s21, -1
	s_cmp_eq_u32 s54, 28
	s_cselect_b32 s25, s13, s23
	s_cselect_b32 s24, s50, s22
	s_cselect_b32 s23, s11, s53
	s_cselect_b32 s22, s51, s52
	v_lshl_add_u64 v[198:199], s[20:21], 0, v[190:191]
	s_add_i32 m0, s19, 0xc000
	ds_read_b128 v[162:165], v205
	ds_read_b128 v[166:169], v205 offset:1024
	ds_read_b128 v[170:173], v205 offset:2048
	ds_read_b128 v[174:177], v205 offset:3072
	ds_read_b128 v[178:181], v205 offset:4096
	ds_read_b128 v[206:209], v205 offset:5120
	ds_read_b128 v[210:213], v205 offset:6144
	ds_read_b128 v[214:217], v205 offset:7168
	global_load_lds_dwordx4 v[198:199], off
	v_lshl_add_u64 v[198:199], s[20:21], 0, v[192:193]
	s_add_i32 m0, s19, 0xe000
	s_nop 0
	global_load_lds_dwordx4 v[198:199], off
	s_waitcnt vmcnt(8)
	s_waitcnt lgkmcnt(0)
	s_barrier
	s_setprio 1
	s_waitcnt lgkmcnt(0)
	v_mfma_f32_16x16x32_bf16 v[126:129], v[130:133], v[162:165], v[126:129]
	v_mfma_f32_16x16x32_bf16 v[122:125], v[138:141], v[162:165], v[122:125]
	v_mfma_f32_16x16x32_bf16 v[114:117], v[130:133], v[170:173], v[114:117]
	v_mfma_f32_16x16x32_bf16 v[106:109], v[138:141], v[170:173], v[106:109]
	v_mfma_f32_16x16x32_bf16 v[98:101], v[130:133], v[178:181], v[98:101]
	v_mfma_f32_16x16x32_bf16 v[90:93], v[138:141], v[178:181], v[90:93]
	v_mfma_f32_16x16x32_bf16 v[82:85], v[130:133], v[210:213], v[82:85]
	v_mfma_f32_16x16x32_bf16 v[74:77], v[138:141], v[210:213], v[74:77]
	v_mfma_f32_16x16x32_bf16 v[126:129], v[134:137], v[166:169], v[126:129]
	v_mfma_f32_16x16x32_bf16 v[122:125], v[142:145], v[166:169], v[122:125]
	v_mfma_f32_16x16x32_bf16 v[114:117], v[134:137], v[174:177], v[114:117]
	v_mfma_f32_16x16x32_bf16 v[106:109], v[142:145], v[174:177], v[106:109]
	v_mfma_f32_16x16x32_bf16 v[98:101], v[134:137], v[206:209], v[98:101]
	v_mfma_f32_16x16x32_bf16 v[90:93], v[142:145], v[206:209], v[90:93]
	v_mfma_f32_16x16x32_bf16 v[82:85], v[134:137], v[214:217], v[82:85]
	v_mfma_f32_16x16x32_bf16 v[74:77], v[142:145], v[214:217], v[74:77]
	v_mfma_f32_16x16x32_bf16 v[118:121], v[146:149], v[162:165], v[118:121]
	v_mfma_f32_16x16x32_bf16 v[110:113], v[154:157], v[162:165], v[110:113]
	v_mfma_f32_16x16x32_bf16 v[102:105], v[146:149], v[170:173], v[102:105]
	v_mfma_f32_16x16x32_bf16 v[94:97], v[154:157], v[170:173], v[94:97]
	v_mfma_f32_16x16x32_bf16 v[86:89], v[146:149], v[178:181], v[86:89]
	v_mfma_f32_16x16x32_bf16 v[78:81], v[154:157], v[178:181], v[78:81]
	v_mfma_f32_16x16x32_bf16 v[70:73], v[146:149], v[210:213], v[70:73]
	v_mfma_f32_16x16x32_bf16 v[66:69], v[154:157], v[210:213], v[66:69]
	v_mfma_f32_16x16x32_bf16 v[118:121], v[150:153], v[166:169], v[118:121]
	v_mfma_f32_16x16x32_bf16 v[110:113], v[158:161], v[166:169], v[110:113]
	v_mfma_f32_16x16x32_bf16 v[102:105], v[150:153], v[174:177], v[102:105]
	v_mfma_f32_16x16x32_bf16 v[94:97], v[158:161], v[174:177], v[94:97]
	v_mfma_f32_16x16x32_bf16 v[86:89], v[150:153], v[206:209], v[86:89]
	v_mfma_f32_16x16x32_bf16 v[78:81], v[158:161], v[206:209], v[78:81]
	v_mfma_f32_16x16x32_bf16 v[70:73], v[150:153], v[214:217], v[70:73]
	v_mfma_f32_16x16x32_bf16 v[66:69], v[158:161], v[214:217], v[66:69]
	s_setprio 0
	s_barrier
	s_add_i32 s55, s42, s29
	v_lshl_add_u64 v[198:199], s[22:23], 0, v[184:185]
	s_mov_b32 m0, s55
	ds_read_b128 v[162:165], v205 offset:16384
	ds_read_b128 v[166:169], v205 offset:17408
	ds_read_b128 v[170:173], v205 offset:18432
	ds_read_b128 v[174:177], v205 offset:19456
	ds_read_b128 v[178:181], v205 offset:20480
	ds_read_b128 v[206:209], v205 offset:21504
	ds_read_b128 v[210:213], v205 offset:22528
	ds_read_b128 v[214:217], v205 offset:23552
	global_load_lds_dwordx4 v[198:199], off
	s_add_i32 m0, s55, 0x2000
	s_add_u32 s56, s22, 0x80000
	v_lshl_add_u64 v[218:219], s[22:23], 0, v[188:189]
	s_addc_u32 s57, s23, 0
	s_add_i32 s55, s43, s29
	global_load_lds_dwordx4 v[218:219], off
	v_lshl_add_u64 v[220:221], s[56:57], 0, v[184:185]
	s_mov_b32 m0, s55
	v_lshl_add_u64 v[222:223], s[24:25], 0, v[186:187]
	global_load_lds_dwordx4 v[220:221], off
	v_lshl_add_u64 v[220:221], s[56:57], 0, v[188:189]
	s_add_i32 m0, s55, 0x2000
	s_nop 0
	global_load_lds_dwordx4 v[220:221], off
	v_lshl_add_u64 v[220:221], s[24:25], 0, v[182:183]
	s_mov_b32 m0, s19
	s_nop 0
	global_load_lds_dwordx4 v[220:221], off
	s_mov_b32 m0, s30
	s_nop 0
	global_load_lds_dwordx4 v[222:223], off
	s_waitcnt vmcnt(8)
	s_waitcnt lgkmcnt(0)
	s_barrier
; #define PG8_STAGE(bufoff, gbase, voff) do { _Pragma("unroll") for (int _i = 0; _i < 2; ++_i) \
;         __builtin_amdgcn_global_load_lds((const unsigned*)((const char*)(gbase) + (voff)[_i]), (PG8_LAS unsigned*)(lds + (bufoff) + ldsw + _i * 8192), 16, 0, 0); } while (0)
; #define PG8_WAIT_V(n) asm volatile("s_waitcnt vmcnt(" #n ")" ::: "memory")
; #define PG8_WAIT_L(n) asm volatile("s_waitcnt lgkmcnt(" #n ")" ::: "memory")
; #define PG8_BAR __builtin_amdgcn_s_barrier()
; #define PG8_SCHED __builtin_amdgcn_sched_barrier(0)
; template <class Epi, class Sched, bool ALIGN_EPI = true, bool SP2 = true>
; __device__ __forceinline__ void gemm_phase(PG8_LAS unsigned char* lds, const int K  , const Sched& S, const Epi& E) {
;     ...
;             PG8_WAIT_V(8); PG8_WAIT_L(0); PG8_BAR; PG8_MMA(1, 0, At, B0); PG8_MMA(1, 1, At, B1); PG8_BAR; PG8_SCHED;
;             PG8_LDB(B0, 1, 0); PG8_LDB(B1, 1, 1); PG8_SCHED; PG8_LDA(At, 1, 0); PG8_STAGE(PG8_SA(0, 1), a2 + hstep, voffA);
;             PG8_WAIT_V(8); PG8_WAIT_L(0); PG8_BAR; PG8_MMA(0, 0, At, B0); PG8_MMA(0, 1, At, B1); PG8_BAR; PG8_SCHED;
	s_setprio 1
	s_waitcnt lgkmcnt(0)
	v_mfma_f32_16x16x32_bf16 v[62:65], v[130:133], v[162:165], v[62:65]
	v_mfma_f32_16x16x32_bf16 v[58:61], v[138:141], v[162:165], v[58:61]
	v_mfma_f32_16x16x32_bf16 v[50:53], v[130:133], v[170:173], v[50:53]
	v_mfma_f32_16x16x32_bf16 v[42:45], v[138:141], v[170:173], v[42:45]
	v_mfma_f32_16x16x32_bf16 v[34:37], v[130:133], v[178:181], v[34:37]
	v_mfma_f32_16x16x32_bf16 v[26:29], v[138:141], v[178:181], v[26:29]
	v_mfma_f32_16x16x32_bf16 v[18:21], v[130:133], v[210:213], v[18:21]
	v_mfma_f32_16x16x32_bf16 v[10:13], v[138:141], v[210:213], v[10:13]
	v_mfma_f32_16x16x32_bf16 v[62:65], v[134:137], v[166:169], v[62:65]
	v_mfma_f32_16x16x32_bf16 v[58:61], v[142:145], v[166:169], v[58:61]
	v_mfma_f32_16x16x32_bf16 v[50:53], v[134:137], v[174:177], v[50:53]
	v_mfma_f32_16x16x32_bf16 v[42:45], v[142:145], v[174:177], v[42:45]
	v_mfma_f32_16x16x32_bf16 v[34:37], v[134:137], v[206:209], v[34:37]
	v_mfma_f32_16x16x32_bf16 v[26:29], v[142:145], v[206:209], v[26:29]
	v_mfma_f32_16x16x32_bf16 v[18:21], v[134:137], v[214:217], v[18:21]
	v_mfma_f32_16x16x32_bf16 v[10:13], v[142:145], v[214:217], v[10:13]
	v_mfma_f32_16x16x32_bf16 v[54:57], v[146:149], v[162:165], v[54:57]
	v_mfma_f32_16x16x32_bf16 v[46:49], v[154:157], v[162:165], v[46:49]
	v_mfma_f32_16x16x32_bf16 v[38:41], v[146:149], v[170:173], v[38:41]
	v_mfma_f32_16x16x32_bf16 v[30:33], v[154:157], v[170:173], v[30:33]
	v_mfma_f32_16x16x32_bf16 v[22:25], v[146:149], v[178:181], v[22:25]
	v_mfma_f32_16x16x32_bf16 v[14:17], v[154:157], v[178:181], v[14:17]
	v_mfma_f32_16x16x32_bf16 v[6:9], v[146:149], v[210:213], v[6:9]
	v_mfma_f32_16x16x32_bf16 v[2:5], v[154:157], v[210:213], v[2:5]
	v_mfma_f32_16x16x32_bf16 v[54:57], v[150:153], v[166:169], v[54:57]
	v_mfma_f32_16x16x32_bf16 v[46:49], v[158:161], v[166:169], v[46:49]
	v_mfma_f32_16x16x32_bf16 v[38:41], v[150:153], v[174:177], v[38:41]
	v_mfma_f32_16x16x32_bf16 v[30:33], v[158:161], v[174:177], v[30:33]
	v_mfma_f32_16x16x32_bf16 v[22:25], v[150:153], v[206:209], v[22:25]
	v_mfma_f32_16x16x32_bf16 v[14:17], v[158:161], v[206:209], v[14:17]
	v_mfma_f32_16x16x32_bf16 v[6:9], v[150:153], v[214:217], v[6:9]
	v_mfma_f32_16x16x32_bf16 v[2:5], v[158:161], v[214:217], v[2:5]
	s_setprio 0
	s_barrier
	s_add_i32 s55, 0, 0x18000
	s_add_i32 s56, 0, 0x1c000
	v_add_u32_e32 v142, s55, v201
	v_add_u32_e32 v158, s56, v201
	ds_read_b128 v[130:133], v142
	ds_read_b128 v[134:137], v142 offset:1024
	ds_read_b128 v[138:141], v142 offset:2048
	ds_read_b128 v[142:145], v142 offset:3072
	ds_read_b128 v[146:149], v158
	ds_read_b128 v[150:153], v158 offset:1024
	ds_read_b128 v[154:157], v158 offset:2048
	ds_read_b128 v[158:161], v158 offset:3072
	s_add_u32 s24, s24, 0x80000
	s_addc_u32 s25, s25, 0
	s_mov_b32 m0, s31
	v_lshl_add_u64 v[224:225], s[24:25], 0, v[182:183]
	ds_read_b128 v[162:165], v205 offset:32768
	ds_read_b128 v[166:169], v205 offset:33792
	ds_read_b128 v[170:173], v205 offset:34816
	ds_read_b128 v[174:177], v205 offset:35840
	ds_read_b128 v[178:181], v205 offset:36864
	ds_read_b128 v[206:209], v205 offset:37888
	ds_read_b128 v[210:213], v205 offset:38912
	ds_read_b128 v[214:217], v205 offset:39936
	global_load_lds_dwordx4 v[224:225], off
	v_lshl_add_u64 v[224:225], s[24:25], 0, v[186:187]
	s_mov_b32 m0, s33
	s_nop 0
	global_load_lds_dwordx4 v[224:225], off
	s_waitcnt vmcnt(8)
	s_waitcnt lgkmcnt(0)
	s_barrier
	s_setprio 1
	s_waitcnt lgkmcnt(0)
	v_mfma_f32_16x16x32_bf16 v[126:129], v[130:133], v[162:165], v[126:129]
	v_mfma_f32_16x16x32_bf16 v[122:125], v[138:141], v[162:165], v[122:125]
	v_mfma_f32_16x16x32_bf16 v[114:117], v[130:133], v[170:173], v[114:117]
	v_mfma_f32_16x16x32_bf16 v[106:109], v[138:141], v[170:173], v[106:109]
	v_mfma_f32_16x16x32_bf16 v[98:101], v[130:133], v[178:181], v[98:101]
	v_mfma_f32_16x16x32_bf16 v[90:93], v[138:141], v[178:181], v[90:93]
	v_mfma_f32_16x16x32_bf16 v[82:85], v[130:133], v[210:213], v[82:85]
	v_mfma_f32_16x16x32_bf16 v[74:77], v[138:141], v[210:213], v[74:77]
	v_mfma_f32_16x16x32_bf16 v[126:129], v[134:137], v[166:169], v[126:129]
	v_mfma_f32_16x16x32_bf16 v[122:125], v[142:145], v[166:169], v[122:125]
	v_mfma_f32_16x16x32_bf16 v[114:117], v[134:137], v[174:177], v[114:117]
	v_mfma_f32_16x16x32_bf16 v[106:109], v[142:145], v[174:177], v[106:109]
	v_mfma_f32_16x16x32_bf16 v[98:101], v[134:137], v[206:209], v[98:101]
	v_mfma_f32_16x16x32_bf16 v[90:93], v[142:145], v[206:209], v[90:93]
	v_mfma_f32_16x16x32_bf16 v[82:85], v[134:137], v[214:217], v[82:85]
	v_mfma_f32_16x16x32_bf16 v[74:77], v[142:145], v[214:217], v[74:77]
	v_mfma_f32_16x16x32_bf16 v[118:121], v[146:149], v[162:165], v[118:121]
	v_mfma_f32_16x16x32_bf16 v[110:113], v[154:157], v[162:165], v[110:113]
	v_mfma_f32_16x16x32_bf16 v[102:105], v[146:149], v[170:173], v[102:105]
	v_mfma_f32_16x16x32_bf16 v[94:97], v[154:157], v[170:173], v[94:97]
	v_mfma_f32_16x16x32_bf16 v[86:89], v[146:149], v[178:181], v[86:89]
	v_mfma_f32_16x16x32_bf16 v[78:81], v[154:157], v[178:181], v[78:81]
	v_mfma_f32_16x16x32_bf16 v[70:73], v[146:149], v[210:213], v[70:73]
	v_mfma_f32_16x16x32_bf16 v[66:69], v[154:157], v[210:213], v[66:69]
	v_mfma_f32_16x16x32_bf16 v[118:121], v[150:153], v[166:169], v[118:121]
	v_mfma_f32_16x16x32_bf16 v[110:113], v[158:161], v[166:169], v[110:113]
	v_mfma_f32_16x16x32_bf16 v[102:105], v[150:153], v[174:177], v[102:105]
	v_mfma_f32_16x16x32_bf16 v[94:97], v[158:161], v[174:177], v[94:97]
	v_mfma_f32_16x16x32_bf16 v[86:89], v[150:153], v[206:209], v[86:89]
	v_mfma_f32_16x16x32_bf16 v[78:81], v[158:161], v[206:209], v[78:81]
	v_mfma_f32_16x16x32_bf16 v[70:73], v[150:153], v[214:217], v[70:73]
	v_mfma_f32_16x16x32_bf16 v[66:69], v[158:161], v[214:217], v[66:69]
	s_setprio 0
	s_barrier
; #define PG8_STAGE(bufoff, gbase, voff) do { _Pragma("unroll") for (int _i = 0; _i < 2; ++_i) \
;         __builtin_amdgcn_global_load_lds((const unsigned*)((const char*)(gbase) + (voff)[_i]), (PG8_LAS unsigned*)(lds + (bufoff) + ldsw + _i * 8192), 16, 0, 0); } while (0)
; #define PG8_WAIT_V(n) asm volatile("s_waitcnt vmcnt(" #n ")" ::: "memory")
; #define PG8_WAIT_L(n) asm volatile("s_waitcnt lgkmcnt(" #n ")" ::: "memory")
; #define PG8_BAR __builtin_amdgcn_s_barrier()
; #define PG8_SCHED __builtin_amdgcn_sched_barrier(0)
;     __device__ __forceinline__ int nt(const pg8::Unit& u) const { return u.kind == 0 ? ntiles : q_nt(u.kind - 1); }
; template <class Epi, class Sched, bool ALIGN_EPI = true, bool SP2 = true>
; __device__ __forceinline__ void gemm_phase(PG8_LAS unsigned char* lds, const int K  , const Sched& S, const Epi& E) {
;     ...
;         for (int t = 0; t < nt; t += 2) {
;     ...
;             PG8_LDA(At, 1, 1); PG8_STAGE(PG8_SB(1, 0), b3, voffB); PG8_STAGE(PG8_SB(1, 1), b3 + hstep, voffB); PG8_STAGE(PG8_SA(1, 0), a3, voffA);
;             PG8_WAIT_V(8); PG8_WAIT_L(0); PG8_BAR; PG8_MMA(1, 0, At, B0); PG8_MMA(1, 1, At, B1); PG8_BAR; PG8_SCHED;
;     ...
;         if constexpr (Epi::FP8) asm volatile("s_nop 15\n\ts_nop 15\n\ts_nop 15\n\ts_nop 15\n\ts_nop 15" ::: "memory");
;         if constexpr (ALIGN_EPI) { if (wr == 0) PG8_BAR; }
	s_add_i32 s24, s55, s29
	v_lshl_add_u64 v[198:199], v[198:199], 0, s[6:7]
	s_mov_b32 m0, s24
	ds_read_b128 v[162:165], v205 offset:49152
	ds_read_b128 v[166:169], v205 offset:50176
	ds_read_b128 v[170:173], v205 offset:51200
	ds_read_b128 v[174:177], v205 offset:52224
	ds_read_b128 v[178:181], v205 offset:53248
	ds_read_b128 v[206:209], v205 offset:54272
	ds_read_b128 v[210:213], v205 offset:55296
	ds_read_b128 v[214:217], v205 offset:56320
	global_load_lds_dwordx4 v[198:199], off
	s_add_i32 m0, s24, 0x2000
	s_add_u32 s22, s22, 0x80080
	v_lshl_add_u64 v[198:199], v[218:219], 0, s[6:7]
	s_addc_u32 s23, s23, 0
	s_add_i32 s24, s56, s29
	global_load_lds_dwordx4 v[198:199], off
	v_lshl_add_u64 v[198:199], s[22:23], 0, v[184:185]
	s_mov_b32 m0, s24
	s_nop 0
	global_load_lds_dwordx4 v[198:199], off
	v_lshl_add_u64 v[198:199], s[22:23], 0, v[188:189]
	s_add_i32 m0, s24, 0x2000
	s_nop 0
	global_load_lds_dwordx4 v[198:199], off
	v_lshl_add_u64 v[198:199], v[220:221], 0, s[6:7]
	s_mov_b32 m0, s38
	s_nop 0
	global_load_lds_dwordx4 v[198:199], off
	v_lshl_add_u64 v[198:199], v[222:223], 0, s[6:7]
	s_mov_b32 m0, s39
	s_nop 0
	global_load_lds_dwordx4 v[198:199], off
	s_waitcnt vmcnt(8)
	s_waitcnt lgkmcnt(0)
	s_barrier
	s_setprio 1
	s_waitcnt lgkmcnt(0)
	v_mfma_f32_16x16x32_bf16 v[62:65], v[130:133], v[162:165], v[62:65]
	v_mfma_f32_16x16x32_bf16 v[58:61], v[138:141], v[162:165], v[58:61]
	v_mfma_f32_16x16x32_bf16 v[50:53], v[130:133], v[170:173], v[50:53]
	v_mfma_f32_16x16x32_bf16 v[42:45], v[138:141], v[170:173], v[42:45]
	v_mfma_f32_16x16x32_bf16 v[34:37], v[130:133], v[178:181], v[34:37]
	v_mfma_f32_16x16x32_bf16 v[26:29], v[138:141], v[178:181], v[26:29]
	v_mfma_f32_16x16x32_bf16 v[18:21], v[130:133], v[210:213], v[18:21]
	v_mfma_f32_16x16x32_bf16 v[10:13], v[138:141], v[210:213], v[10:13]
	v_mfma_f32_16x16x32_bf16 v[62:65], v[134:137], v[166:169], v[62:65]
	v_mfma_f32_16x16x32_bf16 v[58:61], v[142:145], v[166:169], v[58:61]
	v_mfma_f32_16x16x32_bf16 v[50:53], v[134:137], v[174:177], v[50:53]
	v_mfma_f32_16x16x32_bf16 v[42:45], v[142:145], v[174:177], v[42:45]
	v_mfma_f32_16x16x32_bf16 v[34:37], v[134:137], v[206:209], v[34:37]
	v_mfma_f32_16x16x32_bf16 v[26:29], v[142:145], v[206:209], v[26:29]
	v_mfma_f32_16x16x32_bf16 v[18:21], v[134:137], v[214:217], v[18:21]
	v_mfma_f32_16x16x32_bf16 v[10:13], v[142:145], v[214:217], v[10:13]
	v_mfma_f32_16x16x32_bf16 v[54:57], v[146:149], v[162:165], v[54:57]
	v_mfma_f32_16x16x32_bf16 v[46:49], v[154:157], v[162:165], v[46:49]
	v_mfma_f32_16x16x32_bf16 v[38:41], v[146:149], v[170:173], v[38:41]
	v_mfma_f32_16x16x32_bf16 v[30:33], v[154:157], v[170:173], v[30:33]
	v_mfma_f32_16x16x32_bf16 v[22:25], v[146:149], v[178:181], v[22:25]
	v_mfma_f32_16x16x32_bf16 v[14:17], v[154:157], v[178:181], v[14:17]
	v_mfma_f32_16x16x32_bf16 v[6:9], v[146:149], v[210:213], v[6:9]
	v_mfma_f32_16x16x32_bf16 v[2:5], v[154:157], v[210:213], v[2:5]
	v_mfma_f32_16x16x32_bf16 v[54:57], v[150:153], v[166:169], v[54:57]
	v_mfma_f32_16x16x32_bf16 v[46:49], v[158:161], v[166:169], v[46:49]
	v_mfma_f32_16x16x32_bf16 v[38:41], v[150:153], v[174:177], v[38:41]
	v_mfma_f32_16x16x32_bf16 v[30:33], v[158:161], v[174:177], v[30:33]
	v_mfma_f32_16x16x32_bf16 v[22:25], v[150:153], v[206:209], v[22:25]
	v_mfma_f32_16x16x32_bf16 v[14:17], v[158:161], v[206:209], v[14:17]
	v_mfma_f32_16x16x32_bf16 v[6:9], v[150:153], v[214:217], v[6:9]
	v_mfma_f32_16x16x32_bf16 v[2:5], v[158:161], v[214:217], v[2:5]
	s_setprio 0
	s_barrier
	s_add_i32 s54, s54, 2
	s_add_u32 s20, s20, 0x100
	s_addc_u32 s21, s21, 0
	s_add_u32 s52, s52, 0x100
	s_addc_u32 s53, s53, 0
	s_cmp_gt_u32 s54, 29
	s_cbranch_scc0 .LBB0_2296
	s_and_b64 vcc, exec, s[8:9]
	s_cbranch_vccz .LBB0_2299
	s_barrier

; #define PG8_STAGE(bufoff, gbase, voff) do { _Pragma("unroll") for (int _i = 0; _i < 2; ++_i) \
;         __builtin_amdgcn_global_load_lds((const unsigned*)((const char*)(gbase) + (voff)[_i]), (PG8_LAS unsigned*)(lds + (bufoff) + ldsw + _i * 8192), 16, 0, 0); } while (0)
; #define PG8_WAIT_V(n) asm volatile("s_waitcnt vmcnt(" #n ")" ::: "memory")
; #define PG8_WAIT_L(n) asm volatile("s_waitcnt lgkmcnt(" #n ")" ::: "memory")
; #define PG8_BAR __builtin_amdgcn_s_barrier()
; #define PG8_SCHED __builtin_amdgcn_sched_barrier(0)
; template <class Epi, class Sched, bool ALIGN_EPI = true, bool SP2 = true>
; __device__ __forceinline__ void gemm_phase(PG8_LAS unsigned char* lds, const int K  , const Sched& S, const Epi& E) {
;     ...
;             PG8_LDB(B0, 0, 0); PG8_LDB(B1, 0, 1); PG8_SCHED; PG8_LDA(At, 0, 0); PG8_STAGE(PG8_SA(1, 1), a1 + hstep, voffA);
;             PG8_WAIT_V(8); PG8_WAIT_L(0); PG8_BAR; PG8_MMA(0, 0, At, B0); PG8_MMA(0, 1, At, B1); PG8_BAR; PG8_SCHED;
;             PG8_LDA(At, 0, 1); PG8_STAGE(PG8_SB(0, 0), b2, voffB); PG8_STAGE(PG8_SB(0, 1), b2 + hstep, voffB); PG8_STAGE(PG8_SA(0, 0), a2, voffA);
;             PG8_WAIT_V(8); PG8_WAIT_L(0); PG8_BAR; PG8_MMA(1, 0, At, B0); PG8_MMA(1, 1, At, B1); PG8_BAR; PG8_SCHED;
.LBB0_2433:
	ds_read_b128 v[146:149], v152
	ds_read_b128 v[158:161], v152 offset:1024
	ds_read_b128 v[162:165], v152 offset:2048
	ds_read_b128 v[166:169], v152 offset:3072
	ds_read_b128 v[170:173], v153
	ds_read_b128 v[174:177], v153 offset:1024
	ds_read_b128 v[178:181], v153 offset:2048
	ds_read_b128 v[182:185], v153 offset:3072
	s_add_u32 s22, s20, 0xfff80080
	s_addc_u32 s23, s21, -1
	s_cmp_eq_u32 s48, 28
	s_cselect_b32 s25, s13, s23
	s_cselect_b32 s24, s44, s22
	s_cselect_b32 s23, s11, s47
	s_cselect_b32 s22, s45, s46
	v_lshl_add_u64 v[218:219], s[20:21], 0, v[138:139]
	s_add_i32 m0, s19, 0xc000
	ds_read_b128 v[186:189], v154
	ds_read_b128 v[190:193], v154 offset:1024
	ds_read_b128 v[194:197], v154 offset:2048
	ds_read_b128 v[198:201], v154 offset:3072
	ds_read_b128 v[202:205], v154 offset:4096
	ds_read_b128 v[206:209], v154 offset:5120
	ds_read_b128 v[210:213], v154 offset:6144
	ds_read_b128 v[214:217], v154 offset:7168
	global_load_lds_dwordx4 v[218:219], off
	v_lshl_add_u64 v[218:219], s[20:21], 0, v[140:141]
	s_add_i32 m0, s19, 0xe000
	s_nop 0
	global_load_lds_dwordx4 v[218:219], off
	s_waitcnt vmcnt(8)
	s_waitcnt lgkmcnt(0)
	s_barrier
	s_setprio 1
	s_waitcnt lgkmcnt(0)
	v_mfma_f32_16x16x32_bf16 v[126:129], v[146:149], v[186:189], v[126:129]
	v_mfma_f32_16x16x32_bf16 v[118:121], v[162:165], v[186:189], v[118:121]
	v_mfma_f32_16x16x32_bf16 v[110:113], v[146:149], v[194:197], v[110:113]
	v_mfma_f32_16x16x32_bf16 v[102:105], v[162:165], v[194:197], v[102:105]
	v_mfma_f32_16x16x32_bf16 v[94:97], v[146:149], v[202:205], v[94:97]
	v_mfma_f32_16x16x32_bf16 v[86:89], v[162:165], v[202:205], v[86:89]
	v_mfma_f32_16x16x32_bf16 v[78:81], v[146:149], v[210:213], v[78:81]
	v_mfma_f32_16x16x32_bf16 v[70:73], v[162:165], v[210:213], v[70:73]
	v_mfma_f32_16x16x32_bf16 v[126:129], v[158:161], v[190:193], v[126:129]
	v_mfma_f32_16x16x32_bf16 v[118:121], v[166:169], v[190:193], v[118:121]
	v_mfma_f32_16x16x32_bf16 v[110:113], v[158:161], v[198:201], v[110:113]
	v_mfma_f32_16x16x32_bf16 v[102:105], v[166:169], v[198:201], v[102:105]
	v_mfma_f32_16x16x32_bf16 v[94:97], v[158:161], v[206:209], v[94:97]
	v_mfma_f32_16x16x32_bf16 v[86:89], v[166:169], v[206:209], v[86:89]
	v_mfma_f32_16x16x32_bf16 v[78:81], v[158:161], v[214:217], v[78:81]
	v_mfma_f32_16x16x32_bf16 v[70:73], v[166:169], v[214:217], v[70:73]
	v_mfma_f32_16x16x32_bf16 v[122:125], v[170:173], v[186:189], v[122:125]
	v_mfma_f32_16x16x32_bf16 v[114:117], v[178:181], v[186:189], v[114:117]
	v_mfma_f32_16x16x32_bf16 v[106:109], v[170:173], v[194:197], v[106:109]
	v_mfma_f32_16x16x32_bf16 v[98:101], v[178:181], v[194:197], v[98:101]
	v_mfma_f32_16x16x32_bf16 v[90:93], v[170:173], v[202:205], v[90:93]
	v_mfma_f32_16x16x32_bf16 v[82:85], v[178:181], v[202:205], v[82:85]
	v_mfma_f32_16x16x32_bf16 v[74:77], v[170:173], v[210:213], v[74:77]
	v_mfma_f32_16x16x32_bf16 v[66:69], v[178:181], v[210:213], v[66:69]
	v_mfma_f32_16x16x32_bf16 v[122:125], v[174:177], v[190:193], v[122:125]
	v_mfma_f32_16x16x32_bf16 v[114:117], v[182:185], v[190:193], v[114:117]
	v_mfma_f32_16x16x32_bf16 v[106:109], v[174:177], v[198:201], v[106:109]
	v_mfma_f32_16x16x32_bf16 v[98:101], v[182:185], v[198:201], v[98:101]
	v_mfma_f32_16x16x32_bf16 v[90:93], v[174:177], v[206:209], v[90:93]
	v_mfma_f32_16x16x32_bf16 v[82:85], v[182:185], v[206:209], v[82:85]
	v_mfma_f32_16x16x32_bf16 v[74:77], v[174:177], v[214:217], v[74:77]
	v_mfma_f32_16x16x32_bf16 v[66:69], v[182:185], v[214:217], v[66:69]
	s_setprio 0
	s_barrier
	s_add_i32 s49, s39, s28
	v_lshl_add_u64 v[218:219], s[22:23], 0, v[134:135]
	s_mov_b32 m0, s49
	ds_read_b128 v[186:189], v154 offset:16384
	ds_read_b128 v[190:193], v154 offset:17408
	ds_read_b128 v[194:197], v154 offset:18432
	ds_read_b128 v[198:201], v154 offset:19456
	ds_read_b128 v[202:205], v154 offset:20480
	ds_read_b128 v[206:209], v154 offset:21504
	ds_read_b128 v[210:213], v154 offset:22528
	ds_read_b128 v[214:217], v154 offset:23552
	global_load_lds_dwordx4 v[218:219], off
	s_add_i32 m0, s49, 0x2000
	s_add_u32 s50, s22, 0x80000
	v_lshl_add_u64 v[220:221], s[22:23], 0, v[130:131]
	s_addc_u32 s51, s23, 0
	s_add_i32 s49, s40, s28
	global_load_lds_dwordx4 v[220:221], off
	v_lshl_add_u64 v[222:223], s[50:51], 0, v[134:135]
	s_mov_b32 m0, s49
	v_lshl_add_u64 v[224:225], s[24:25], 0, v[132:133]
	global_load_lds_dwordx4 v[222:223], off
	v_lshl_add_u64 v[222:223], s[50:51], 0, v[130:131]
	s_add_i32 m0, s49, 0x2000
	s_nop 0
	global_load_lds_dwordx4 v[222:223], off
	v_lshl_add_u64 v[222:223], s[24:25], 0, v[136:137]
	s_mov_b32 m0, s19
	s_nop 0
	global_load_lds_dwordx4 v[222:223], off
	s_mov_b32 m0, s31
	s_nop 0
	global_load_lds_dwordx4 v[224:225], off
	s_waitcnt vmcnt(8)
	s_waitcnt lgkmcnt(0)
	s_barrier
; #define PG8_STAGE(bufoff, gbase, voff) do { _Pragma("unroll") for (int _i = 0; _i < 2; ++_i) \
;         __builtin_amdgcn_global_load_lds((const unsigned*)((const char*)(gbase) + (voff)[_i]), (PG8_LAS unsigned*)(lds + (bufoff) + ldsw + _i * 8192), 16, 0, 0); } while (0)
; #define PG8_WAIT_V(n) asm volatile("s_waitcnt vmcnt(" #n ")" ::: "memory")
; #define PG8_WAIT_L(n) asm volatile("s_waitcnt lgkmcnt(" #n ")" ::: "memory")
; #define PG8_BAR __builtin_amdgcn_s_barrier()
; #define PG8_SCHED __builtin_amdgcn_sched_barrier(0)
; template <class Epi, class Sched, bool ALIGN_EPI = true, bool SP2 = true>
; __device__ __forceinline__ void gemm_phase(PG8_LAS unsigned char* lds, const int K  , const Sched& S, const Epi& E) {
;     ...
;             PG8_WAIT_V(8); PG8_WAIT_L(0); PG8_BAR; PG8_MMA(1, 0, At, B0); PG8_MMA(1, 1, At, B1); PG8_BAR; PG8_SCHED;
;             PG8_LDB(B0, 1, 0); PG8_LDB(B1, 1, 1); PG8_SCHED; PG8_LDA(At, 1, 0); PG8_STAGE(PG8_SA(0, 1), a2 + hstep, voffA);
;             PG8_WAIT_V(8); PG8_WAIT_L(0); PG8_BAR; PG8_MMA(0, 0, At, B0); PG8_MMA(0, 1, At, B1); PG8_BAR; PG8_SCHED;
	s_setprio 1
	s_waitcnt lgkmcnt(0)
	v_mfma_f32_16x16x32_bf16 v[62:65], v[146:149], v[186:189], v[62:65]
	v_mfma_f32_16x16x32_bf16 v[54:57], v[162:165], v[186:189], v[54:57]
	v_mfma_f32_16x16x32_bf16 v[46:49], v[146:149], v[194:197], v[46:49]
	v_mfma_f32_16x16x32_bf16 v[38:41], v[162:165], v[194:197], v[38:41]
	v_mfma_f32_16x16x32_bf16 v[30:33], v[146:149], v[202:205], v[30:33]
	v_mfma_f32_16x16x32_bf16 v[22:25], v[162:165], v[202:205], v[22:25]
	v_mfma_f32_16x16x32_bf16 v[14:17], v[146:149], v[210:213], v[14:17]
	v_mfma_f32_16x16x32_bf16 v[6:9], v[162:165], v[210:213], v[6:9]
	v_mfma_f32_16x16x32_bf16 v[62:65], v[158:161], v[190:193], v[62:65]
	v_mfma_f32_16x16x32_bf16 v[54:57], v[166:169], v[190:193], v[54:57]
	v_mfma_f32_16x16x32_bf16 v[46:49], v[158:161], v[198:201], v[46:49]
	v_mfma_f32_16x16x32_bf16 v[38:41], v[166:169], v[198:201], v[38:41]
	v_mfma_f32_16x16x32_bf16 v[30:33], v[158:161], v[206:209], v[30:33]
	v_mfma_f32_16x16x32_bf16 v[22:25], v[166:169], v[206:209], v[22:25]
	v_mfma_f32_16x16x32_bf16 v[14:17], v[158:161], v[214:217], v[14:17]
	v_mfma_f32_16x16x32_bf16 v[6:9], v[166:169], v[214:217], v[6:9]
	v_mfma_f32_16x16x32_bf16 v[58:61], v[170:173], v[186:189], v[58:61]
	v_mfma_f32_16x16x32_bf16 v[50:53], v[178:181], v[186:189], v[50:53]
	v_mfma_f32_16x16x32_bf16 v[42:45], v[170:173], v[194:197], v[42:45]
	v_mfma_f32_16x16x32_bf16 v[34:37], v[178:181], v[194:197], v[34:37]
	v_mfma_f32_16x16x32_bf16 v[26:29], v[170:173], v[202:205], v[26:29]
	v_mfma_f32_16x16x32_bf16 v[18:21], v[178:181], v[202:205], v[18:21]
	v_mfma_f32_16x16x32_bf16 v[10:13], v[170:173], v[210:213], v[10:13]
	v_mfma_f32_16x16x32_bf16 v[2:5], v[178:181], v[210:213], v[2:5]
	v_mfma_f32_16x16x32_bf16 v[58:61], v[174:177], v[190:193], v[58:61]
	v_mfma_f32_16x16x32_bf16 v[50:53], v[182:185], v[190:193], v[50:53]
	v_mfma_f32_16x16x32_bf16 v[42:45], v[174:177], v[198:201], v[42:45]
	v_mfma_f32_16x16x32_bf16 v[34:37], v[182:185], v[198:201], v[34:37]
	v_mfma_f32_16x16x32_bf16 v[26:29], v[174:177], v[206:209], v[26:29]
	v_mfma_f32_16x16x32_bf16 v[18:21], v[182:185], v[206:209], v[18:21]
	v_mfma_f32_16x16x32_bf16 v[10:13], v[174:177], v[214:217], v[10:13]
	v_mfma_f32_16x16x32_bf16 v[2:5], v[182:185], v[214:217], v[2:5]
	s_setprio 0
	s_barrier
	s_add_i32 s49, 0, 0x18000
	v_add_u32_e32 v157, s49, v150
	s_add_i32 s50, 0, 0x1c000
	ds_read_b128 v[146:149], v157
	ds_read_b128 v[158:161], v157 offset:1024
	ds_read_b128 v[162:165], v157 offset:2048
	ds_read_b128 v[166:169], v157 offset:3072
	v_add_u32_e32 v157, s50, v150
	ds_read_b128 v[170:173], v157
	ds_read_b128 v[174:177], v157 offset:1024
	ds_read_b128 v[178:181], v157 offset:2048
	ds_read_b128 v[182:185], v157 offset:3072
	s_add_u32 s24, s24, 0x80000
	s_addc_u32 s25, s25, 0
	s_mov_b32 m0, s33
	v_lshl_add_u64 v[226:227], s[24:25], 0, v[136:137]
	ds_read_b128 v[186:189], v154 offset:32768
	ds_read_b128 v[190:193], v154 offset:33792
	ds_read_b128 v[194:197], v154 offset:34816
	ds_read_b128 v[198:201], v154 offset:35840
	ds_read_b128 v[202:205], v154 offset:36864
	ds_read_b128 v[206:209], v154 offset:37888
	ds_read_b128 v[210:213], v154 offset:38912
	ds_read_b128 v[214:217], v154 offset:39936
	global_load_lds_dwordx4 v[226:227], off
	v_lshl_add_u64 v[226:227], s[24:25], 0, v[132:133]
	s_mov_b32 m0, s34
	s_nop 0
	global_load_lds_dwordx4 v[226:227], off
	s_waitcnt vmcnt(8)
	s_waitcnt lgkmcnt(0)
	s_barrier
	s_setprio 1
	s_waitcnt lgkmcnt(0)
	v_mfma_f32_16x16x32_bf16 v[126:129], v[146:149], v[186:189], v[126:129]
	v_mfma_f32_16x16x32_bf16 v[118:121], v[162:165], v[186:189], v[118:121]
	v_mfma_f32_16x16x32_bf16 v[110:113], v[146:149], v[194:197], v[110:113]
	v_mfma_f32_16x16x32_bf16 v[102:105], v[162:165], v[194:197], v[102:105]
	v_mfma_f32_16x16x32_bf16 v[94:97], v[146:149], v[202:205], v[94:97]
	v_mfma_f32_16x16x32_bf16 v[86:89], v[162:165], v[202:205], v[86:89]
	v_mfma_f32_16x16x32_bf16 v[78:81], v[146:149], v[210:213], v[78:81]
	v_mfma_f32_16x16x32_bf16 v[70:73], v[162:165], v[210:213], v[70:73]
	v_mfma_f32_16x16x32_bf16 v[126:129], v[158:161], v[190:193], v[126:129]
	v_mfma_f32_16x16x32_bf16 v[118:121], v[166:169], v[190:193], v[118:121]
	v_mfma_f32_16x16x32_bf16 v[110:113], v[158:161], v[198:201], v[110:113]
	v_mfma_f32_16x16x32_bf16 v[102:105], v[166:169], v[198:201], v[102:105]
	v_mfma_f32_16x16x32_bf16 v[94:97], v[158:161], v[206:209], v[94:97]
	v_mfma_f32_16x16x32_bf16 v[86:89], v[166:169], v[206:209], v[86:89]
	v_mfma_f32_16x16x32_bf16 v[78:81], v[158:161], v[214:217], v[78:81]
	v_mfma_f32_16x16x32_bf16 v[70:73], v[166:169], v[214:217], v[70:73]
	v_mfma_f32_16x16x32_bf16 v[122:125], v[170:173], v[186:189], v[122:125]
	v_mfma_f32_16x16x32_bf16 v[114:117], v[178:181], v[186:189], v[114:117]
	v_mfma_f32_16x16x32_bf16 v[106:109], v[170:173], v[194:197], v[106:109]
	v_mfma_f32_16x16x32_bf16 v[98:101], v[178:181], v[194:197], v[98:101]
	v_mfma_f32_16x16x32_bf16 v[90:93], v[170:173], v[202:205], v[90:93]
	v_mfma_f32_16x16x32_bf16 v[82:85], v[178:181], v[202:205], v[82:85]
	v_mfma_f32_16x16x32_bf16 v[74:77], v[170:173], v[210:213], v[74:77]
	v_mfma_f32_16x16x32_bf16 v[66:69], v[178:181], v[210:213], v[66:69]
	v_mfma_f32_16x16x32_bf16 v[122:125], v[174:177], v[190:193], v[122:125]
	v_mfma_f32_16x16x32_bf16 v[114:117], v[182:185], v[190:193], v[114:117]
	v_mfma_f32_16x16x32_bf16 v[106:109], v[174:177], v[198:201], v[106:109]
	v_mfma_f32_16x16x32_bf16 v[98:101], v[182:185], v[198:201], v[98:101]
	v_mfma_f32_16x16x32_bf16 v[90:93], v[174:177], v[206:209], v[90:93]
	v_mfma_f32_16x16x32_bf16 v[82:85], v[182:185], v[206:209], v[82:85]
	v_mfma_f32_16x16x32_bf16 v[74:77], v[174:177], v[214:217], v[74:77]
	v_mfma_f32_16x16x32_bf16 v[66:69], v[182:185], v[214:217], v[66:69]
	s_setprio 0
	s_barrier
; #define PG8_STAGE(bufoff, gbase, voff) do { _Pragma("unroll") for (int _i = 0; _i < 2; ++_i) \
;         __builtin_amdgcn_global_load_lds((const unsigned*)((const char*)(gbase) + (voff)[_i]), (PG8_LAS unsigned*)(lds + (bufoff) + ldsw + _i * 8192), 16, 0, 0); } while (0)
; #define PG8_WAIT_V(n) asm volatile("s_waitcnt vmcnt(" #n ")" ::: "memory")
; #define PG8_WAIT_L(n) asm volatile("s_waitcnt lgkmcnt(" #n ")" ::: "memory")
; #define PG8_BAR __builtin_amdgcn_s_barrier()
; #define PG8_SCHED __builtin_amdgcn_sched_barrier(0)
;     __device__ __forceinline__ int nt(const pg8::Unit& u) const { return u.kind == 0 ? ntiles : q_nt(u.kind - 1); }
; template <class Epi, class Sched, bool ALIGN_EPI = true, bool SP2 = true>
; __device__ __forceinline__ void gemm_phase(PG8_LAS unsigned char* lds, const int K  , const Sched& S, const Epi& E) {
;     ...
;         for (int t = 0; t < nt; t += 2) {
;     ...
;             PG8_LDA(At, 1, 1); PG8_STAGE(PG8_SB(1, 0), b3, voffB); PG8_STAGE(PG8_SB(1, 1), b3 + hstep, voffB); PG8_STAGE(PG8_SA(1, 0), a3, voffA);
;             PG8_WAIT_V(8); PG8_WAIT_L(0); PG8_BAR; PG8_MMA(1, 0, At, B0); PG8_MMA(1, 1, At, B1); PG8_BAR; PG8_SCHED;
;     ...
;         if constexpr (Epi::FP8) asm volatile("s_nop 15\n\ts_nop 15\n\ts_nop 15\n\ts_nop 15\n\ts_nop 15" ::: "memory");
;         if constexpr (ALIGN_EPI) { if (wr == 0) PG8_BAR; }
	s_add_i32 s24, s49, s28
	v_lshl_add_u64 v[218:219], v[218:219], 0, s[6:7]
	s_mov_b32 m0, s24
	ds_read_b128 v[186:189], v154 offset:49152
	ds_read_b128 v[190:193], v154 offset:50176
	ds_read_b128 v[194:197], v154 offset:51200
	ds_read_b128 v[198:201], v154 offset:52224
	ds_read_b128 v[202:205], v154 offset:53248
	ds_read_b128 v[206:209], v154 offset:54272
	ds_read_b128 v[210:213], v154 offset:55296
	ds_read_b128 v[214:217], v154 offset:56320
	global_load_lds_dwordx4 v[218:219], off
	s_add_i32 m0, s24, 0x2000
	s_add_u32 s22, s22, 0x80080
	v_lshl_add_u64 v[218:219], v[220:221], 0, s[6:7]
	s_addc_u32 s23, s23, 0
	s_add_i32 s24, s50, s28
	global_load_lds_dwordx4 v[218:219], off
	v_lshl_add_u64 v[218:219], s[22:23], 0, v[134:135]
	s_mov_b32 m0, s24
	s_nop 0
	global_load_lds_dwordx4 v[218:219], off
	v_lshl_add_u64 v[218:219], s[22:23], 0, v[130:131]
	s_add_i32 m0, s24, 0x2000
	s_nop 0
	global_load_lds_dwordx4 v[218:219], off
	v_lshl_add_u64 v[218:219], v[222:223], 0, s[6:7]
	s_mov_b32 m0, s36
	s_nop 0
	global_load_lds_dwordx4 v[218:219], off
	v_lshl_add_u64 v[218:219], v[224:225], 0, s[6:7]
	s_mov_b32 m0, s37
	s_nop 0
	global_load_lds_dwordx4 v[218:219], off
	s_waitcnt vmcnt(8)
	s_waitcnt lgkmcnt(0)
	s_barrier
	s_setprio 1
	s_waitcnt lgkmcnt(0)
	v_mfma_f32_16x16x32_bf16 v[62:65], v[146:149], v[186:189], v[62:65]
	v_mfma_f32_16x16x32_bf16 v[54:57], v[162:165], v[186:189], v[54:57]
	v_mfma_f32_16x16x32_bf16 v[46:49], v[146:149], v[194:197], v[46:49]
	v_mfma_f32_16x16x32_bf16 v[38:41], v[162:165], v[194:197], v[38:41]
	v_mfma_f32_16x16x32_bf16 v[30:33], v[146:149], v[202:205], v[30:33]
	v_mfma_f32_16x16x32_bf16 v[22:25], v[162:165], v[202:205], v[22:25]
	v_mfma_f32_16x16x32_bf16 v[14:17], v[146:149], v[210:213], v[14:17]
	v_mfma_f32_16x16x32_bf16 v[6:9], v[162:165], v[210:213], v[6:9]
	v_mfma_f32_16x16x32_bf16 v[62:65], v[158:161], v[190:193], v[62:65]
	v_mfma_f32_16x16x32_bf16 v[54:57], v[166:169], v[190:193], v[54:57]
	v_mfma_f32_16x16x32_bf16 v[46:49], v[158:161], v[198:201], v[46:49]
	v_mfma_f32_16x16x32_bf16 v[38:41], v[166:169], v[198:201], v[38:41]
	v_mfma_f32_16x16x32_bf16 v[30:33], v[158:161], v[206:209], v[30:33]
	v_mfma_f32_16x16x32_bf16 v[22:25], v[166:169], v[206:209], v[22:25]
	v_mfma_f32_16x16x32_bf16 v[14:17], v[158:161], v[214:217], v[14:17]
	v_mfma_f32_16x16x32_bf16 v[6:9], v[166:169], v[214:217], v[6:9]
	v_mfma_f32_16x16x32_bf16 v[58:61], v[170:173], v[186:189], v[58:61]
	v_mfma_f32_16x16x32_bf16 v[50:53], v[178:181], v[186:189], v[50:53]
	v_mfma_f32_16x16x32_bf16 v[42:45], v[170:173], v[194:197], v[42:45]
	v_mfma_f32_16x16x32_bf16 v[34:37], v[178:181], v[194:197], v[34:37]
	v_mfma_f32_16x16x32_bf16 v[26:29], v[170:173], v[202:205], v[26:29]
	v_mfma_f32_16x16x32_bf16 v[18:21], v[178:181], v[202:205], v[18:21]
	v_mfma_f32_16x16x32_bf16 v[10:13], v[170:173], v[210:213], v[10:13]
	v_mfma_f32_16x16x32_bf16 v[2:5], v[178:181], v[210:213], v[2:5]
	v_mfma_f32_16x16x32_bf16 v[58:61], v[174:177], v[190:193], v[58:61]
	v_mfma_f32_16x16x32_bf16 v[50:53], v[182:185], v[190:193], v[50:53]
	v_mfma_f32_16x16x32_bf16 v[42:45], v[174:177], v[198:201], v[42:45]
	v_mfma_f32_16x16x32_bf16 v[34:37], v[182:185], v[198:201], v[34:37]
	v_mfma_f32_16x16x32_bf16 v[26:29], v[174:177], v[206:209], v[26:29]
	v_mfma_f32_16x16x32_bf16 v[18:21], v[182:185], v[206:209], v[18:21]
	v_mfma_f32_16x16x32_bf16 v[10:13], v[174:177], v[214:217], v[10:13]
	v_mfma_f32_16x16x32_bf16 v[2:5], v[182:185], v[214:217], v[2:5]
	s_setprio 0
	s_barrier
	s_add_i32 s48, s48, 2
	s_add_u32 s20, s20, 0x100
	s_addc_u32 s21, s21, 0
	s_add_u32 s46, s46, 0x100
	s_addc_u32 s47, s47, 0
	s_cmp_gt_u32 s48, 29
	s_cbranch_scc0 .LBB0_2433
	s_and_b64 vcc, exec, s[8:9]
	s_cbranch_vccz .LBB0_2436
	s_barrier

; #define PG8_STAGE(bufoff, gbase, voff) do { _Pragma("unroll") for (int _i = 0; _i < 2; ++_i) \
;         __builtin_amdgcn_global_load_lds((const unsigned*)((const char*)(gbase) + (voff)[_i]), (PG8_LAS unsigned*)(lds + (bufoff) + ldsw + _i * 8192), 16, 0, 0); } while (0)
; #define PG8_WAIT_V(n) asm volatile("s_waitcnt vmcnt(" #n ")" ::: "memory")
; #define PG8_WAIT_L(n) asm volatile("s_waitcnt lgkmcnt(" #n ")" ::: "memory")
; #define PG8_BAR __builtin_amdgcn_s_barrier()
; #define PG8_SCHED __builtin_amdgcn_sched_barrier(0)
; template <class Epi, class Sched, bool ALIGN_EPI = true, bool SP2 = true>
; __device__ __forceinline__ void gemm_phase(PG8_LAS unsigned char* lds, const int K  , const Sched& S, const Epi& E) {
;     ...
;             PG8_LDB(B0, 0, 0); PG8_LDB(B1, 0, 1); PG8_SCHED; PG8_LDA(At, 0, 0); PG8_STAGE(PG8_SA(1, 1), a1 + hstep, voffA);
;             PG8_WAIT_V(8); PG8_WAIT_L(0); PG8_BAR; PG8_MMA(0, 0, At, B0); PG8_MMA(0, 1, At, B1); PG8_BAR; PG8_SCHED;
;             PG8_LDA(At, 0, 1); PG8_STAGE(PG8_SB(0, 0), b2, voffB); PG8_STAGE(PG8_SB(0, 1), b2 + hstep, voffB); PG8_STAGE(PG8_SA(0, 0), a2, voffA);
;             PG8_WAIT_V(8); PG8_WAIT_L(0); PG8_BAR; PG8_MMA(1, 0, At, B0); PG8_MMA(1, 1, At, B1); PG8_BAR; PG8_SCHED;
.LBB0_2516:
	ds_read_b128 v[16:19], v206
	ds_read_b128 v[20:23], v206 offset:1024
	ds_read_b128 v[24:27], v206 offset:2048
	ds_read_b128 v[28:31], v206 offset:3072
	ds_read_b128 v[0:3], v207
	ds_read_b128 v[4:7], v207 offset:1024
	ds_read_b128 v[8:11], v207 offset:2048
	ds_read_b128 v[12:15], v207 offset:3072
	s_add_u32 s18, s16, 0xfff50080
	s_addc_u32 s19, s17, -1
	s_cmp_eq_u32 s57, 40
	s_cselect_b32 s21, s7, s19
	s_cselect_b32 s20, s6, s18
	s_cselect_b32 s19, s15, s56
	s_cselect_b32 s18, s14, s55
	v_lshl_add_u64 v[200:201], s[16:17], 0, v[176:177]
	s_add_i32 m0, s25, 0xc000
	ds_read_b128 v[160:163], v208
	ds_read_b128 v[164:167], v208 offset:1024
	ds_read_b128 v[184:187], v208 offset:2048
	ds_read_b128 v[188:191], v208 offset:3072
	ds_read_b128 v[192:195], v208 offset:4096
	ds_read_b128 v[196:199], v208 offset:5120
	ds_read_b128 v[210:213], v208 offset:6144
	ds_read_b128 v[214:217], v208 offset:7168
	global_load_lds_dwordx4 v[200:201], off
	v_lshl_add_u64 v[200:201], s[16:17], 0, v[178:179]
	s_add_i32 m0, s25, 0xe000
	s_nop 0
	global_load_lds_dwordx4 v[200:201], off
	s_waitcnt vmcnt(8)
	s_waitcnt lgkmcnt(0)
	s_barrier
	s_setprio 1
	s_waitcnt lgkmcnt(0)
	v_mfma_scale_f32_16x16x128_f8f6f4 v[156:159], v[16:23], v[160:167], v[156:159], v202, v202 op_sel_hi:[0,0,0]
	v_mfma_scale_f32_16x16x128_f8f6f4 v[152:155], v[24:31], v[160:167], v[152:155], v202, v202 op_sel_hi:[0,0,0]
	v_mfma_scale_f32_16x16x128_f8f6f4 v[140:143], v[16:23], v[184:191], v[140:143], v202, v202 op_sel_hi:[0,0,0]
	v_mfma_scale_f32_16x16x128_f8f6f4 v[136:139], v[24:31], v[184:191], v[136:139], v202, v202 op_sel_hi:[0,0,0]
	v_mfma_scale_f32_16x16x128_f8f6f4 v[124:127], v[16:23], v[192:199], v[124:127], v202, v202 op_sel_hi:[0,0,0]
	v_mfma_scale_f32_16x16x128_f8f6f4 v[120:123], v[24:31], v[192:199], v[120:123], v202, v202 op_sel_hi:[0,0,0]
	v_mfma_scale_f32_16x16x128_f8f6f4 v[108:111], v[16:23], v[210:217], v[108:111], v202, v202 op_sel_hi:[0,0,0]
	v_mfma_scale_f32_16x16x128_f8f6f4 v[104:107], v[24:31], v[210:217], v[104:107], v202, v202 op_sel_hi:[0,0,0]
	v_mfma_scale_f32_16x16x128_f8f6f4 v[148:151], v[0:7], v[160:167], v[148:151], v202, v202 op_sel_hi:[0,0,0]
	v_mfma_scale_f32_16x16x128_f8f6f4 v[144:147], v[8:15], v[160:167], v[144:147], v202, v202 op_sel_hi:[0,0,0]
	v_mfma_scale_f32_16x16x128_f8f6f4 v[132:135], v[0:7], v[184:191], v[132:135], v202, v202 op_sel_hi:[0,0,0]
	v_mfma_scale_f32_16x16x128_f8f6f4 v[128:131], v[8:15], v[184:191], v[128:131], v202, v202 op_sel_hi:[0,0,0]
	v_mfma_scale_f32_16x16x128_f8f6f4 v[116:119], v[0:7], v[192:199], v[116:119], v202, v202 op_sel_hi:[0,0,0]
	v_mfma_scale_f32_16x16x128_f8f6f4 v[112:115], v[8:15], v[192:199], v[112:115], v202, v202 op_sel_hi:[0,0,0]
	v_mfma_scale_f32_16x16x128_f8f6f4 v[100:103], v[0:7], v[210:217], v[100:103], v202, v202 op_sel_hi:[0,0,0]
	v_mfma_scale_f32_16x16x128_f8f6f4 v[96:99], v[8:15], v[210:217], v[96:99], v202, v202 op_sel_hi:[0,0,0]
	s_setprio 0
	s_barrier
	s_add_i32 s58, s38, s24
	v_lshl_add_u64 v[160:161], s[18:19], 0, v[170:171]
	s_mov_b32 m0, s58
	ds_read_b128 v[184:187], v208 offset:16384
	ds_read_b128 v[188:191], v208 offset:17408
	ds_read_b128 v[192:195], v208 offset:18432
	ds_read_b128 v[196:199], v208 offset:19456
	ds_read_b128 v[210:213], v208 offset:20480
	ds_read_b128 v[214:217], v208 offset:21504
	ds_read_b128 v[218:221], v208 offset:22528
	ds_read_b128 v[222:225], v208 offset:23552
	global_load_lds_dwordx4 v[160:161], off
	s_add_i32 m0, s58, 0x2000
	s_add_u32 s58, s18, 0xb0000
	v_lshl_add_u64 v[162:163], s[18:19], 0, v[174:175]
	s_addc_u32 s59, s19, 0
	s_add_i32 s60, s39, s24
	global_load_lds_dwordx4 v[162:163], off
	v_lshl_add_u64 v[164:165], s[58:59], 0, v[170:171]
	s_mov_b32 m0, s60
	v_lshl_add_u64 v[166:167], s[20:21], 0, v[172:173]
	global_load_lds_dwordx4 v[164:165], off
	v_lshl_add_u64 v[164:165], s[58:59], 0, v[174:175]
	s_add_i32 m0, s60, 0x2000
	s_nop 0
	global_load_lds_dwordx4 v[164:165], off
	v_lshl_add_u64 v[164:165], s[20:21], 0, v[168:169]
	s_mov_b32 m0, s25
	s_nop 0
	global_load_lds_dwordx4 v[164:165], off
	s_mov_b32 m0, s26
	s_nop 0
	global_load_lds_dwordx4 v[166:167], off
	s_waitcnt vmcnt(8)
	s_waitcnt lgkmcnt(0)
	s_barrier
	s_setprio 1
	s_waitcnt lgkmcnt(0)
	v_mfma_scale_f32_16x16x128_f8f6f4 v[92:95], v[16:23], v[184:191], v[92:95], v202, v202 op_sel_hi:[0,0,0]
	v_mfma_scale_f32_16x16x128_f8f6f4 v[88:91], v[24:31], v[184:191], v[88:91], v202, v202 op_sel_hi:[0,0,0]
	v_mfma_scale_f32_16x16x128_f8f6f4 v[76:79], v[16:23], v[192:199], v[76:79], v202, v202 op_sel_hi:[0,0,0]
	v_mfma_scale_f32_16x16x128_f8f6f4 v[72:75], v[24:31], v[192:199], v[72:75], v202, v202 op_sel_hi:[0,0,0]
	v_mfma_scale_f32_16x16x128_f8f6f4 v[60:63], v[16:23], v[210:217], v[60:63], v202, v202 op_sel_hi:[0,0,0]
	v_mfma_scale_f32_16x16x128_f8f6f4 v[56:59], v[24:31], v[210:217], v[56:59], v202, v202 op_sel_hi:[0,0,0]
	v_mfma_scale_f32_16x16x128_f8f6f4 v[44:47], v[16:23], v[218:225], v[44:47], v202, v202 op_sel_hi:[0,0,0]
	v_mfma_scale_f32_16x16x128_f8f6f4 v[40:43], v[24:31], v[218:225], v[40:43], v202, v202 op_sel_hi:[0,0,0]
	v_mfma_scale_f32_16x16x128_f8f6f4 v[84:87], v[0:7], v[184:191], v[84:87], v202, v202 op_sel_hi:[0,0,0]
	v_mfma_scale_f32_16x16x128_f8f6f4 v[80:83], v[8:15], v[184:191], v[80:83], v202, v202 op_sel_hi:[0,0,0]
	v_mfma_scale_f32_16x16x128_f8f6f4 v[68:71], v[0:7], v[192:199], v[68:71], v202, v202 op_sel_hi:[0,0,0]
	v_mfma_scale_f32_16x16x128_f8f6f4 v[64:67], v[8:15], v[192:199], v[64:67], v202, v202 op_sel_hi:[0,0,0]
	v_mfma_scale_f32_16x16x128_f8f6f4 v[52:55], v[0:7], v[210:217], v[52:55], v202, v202 op_sel_hi:[0,0,0]
	v_mfma_scale_f32_16x16x128_f8f6f4 v[48:51], v[8:15], v[210:217], v[48:51], v202, v202 op_sel_hi:[0,0,0]
	v_mfma_scale_f32_16x16x128_f8f6f4 v[36:39], v[0:7], v[218:225], v[36:39], v202, v202 op_sel_hi:[0,0,0]
	v_mfma_scale_f32_16x16x128_f8f6f4 v[32:35], v[8:15], v[218:225], v[32:35], v202, v202 op_sel_hi:[0,0,0]
	s_setprio 0
	s_barrier
; #define PG8_STAGE(bufoff, gbase, voff) do { _Pragma("unroll") for (int _i = 0; _i < 2; ++_i) \
;         __builtin_amdgcn_global_load_lds((const unsigned*)((const char*)(gbase) + (voff)[_i]), (PG8_LAS unsigned*)(lds + (bufoff) + ldsw + _i * 8192), 16, 0, 0); } while (0)
; #define PG8_WAIT_V(n) asm volatile("s_waitcnt vmcnt(" #n ")" ::: "memory")
; #define PG8_WAIT_L(n) asm volatile("s_waitcnt lgkmcnt(" #n ")" ::: "memory")
; #define PG8_BAR __builtin_amdgcn_s_barrier()
; #define PG8_SCHED __builtin_amdgcn_sched_barrier(0)
; template <class Epi, class Sched, bool ALIGN_EPI = true, bool SP2 = true>
; __device__ __forceinline__ void gemm_phase(PG8_LAS unsigned char* lds, const int K  , const Sched& S, const Epi& E) {
;     ...
;             PG8_LDB(B0, 1, 0); PG8_LDB(B1, 1, 1); PG8_SCHED; PG8_LDA(At, 1, 0); PG8_STAGE(PG8_SA(0, 1), a2 + hstep, voffA);
;             PG8_WAIT_V(8); PG8_WAIT_L(0); PG8_BAR; PG8_MMA(0, 0, At, B0); PG8_MMA(0, 1, At, B1); PG8_BAR; PG8_SCHED;
;             PG8_LDA(At, 1, 1); PG8_STAGE(PG8_SB(1, 0), b3, voffB); PG8_STAGE(PG8_SB(1, 1), b3 + hstep, voffB); PG8_STAGE(PG8_SA(1, 0), a3, voffA);
;             PG8_WAIT_V(8); PG8_WAIT_L(0); PG8_BAR; PG8_MMA(1, 0, At, B0); PG8_MMA(1, 1, At, B1); PG8_BAR; PG8_SCHED;
;     ...
;         if constexpr (Epi::FP8) asm volatile("s_nop 15\n\ts_nop 15\n\ts_nop 15\n\ts_nop 15\n\ts_nop 15" ::: "memory");
;         if constexpr (ALIGN_EPI) { if (wr == 0) PG8_BAR; }
	s_add_i32 s58, 0, 0x18000
	s_add_i32 s59, 0, 0x1c000
	v_add_u32_e32 v12, s58, v204
	v_add_u32_e32 v28, s59, v204
	ds_read_b128 v[0:3], v12
	ds_read_b128 v[4:7], v12 offset:1024
	ds_read_b128 v[8:11], v12 offset:2048
	ds_read_b128 v[12:15], v12 offset:3072
	ds_read_b128 v[16:19], v28
	ds_read_b128 v[20:23], v28 offset:1024
	ds_read_b128 v[24:27], v28 offset:2048
	ds_read_b128 v[28:31], v28 offset:3072
	s_add_u32 s20, s20, 0xb0000
	s_addc_u32 s21, s21, 0
	s_mov_b32 m0, s27
	v_lshl_add_u64 v[200:201], s[20:21], 0, v[168:169]
	ds_read_b128 v[184:187], v208 offset:32768
	ds_read_b128 v[188:191], v208 offset:33792
	ds_read_b128 v[192:195], v208 offset:34816
	ds_read_b128 v[196:199], v208 offset:35840
	ds_read_b128 v[210:213], v208 offset:36864
	ds_read_b128 v[214:217], v208 offset:37888
	ds_read_b128 v[218:221], v208 offset:38912
	ds_read_b128 v[222:225], v208 offset:39936
	global_load_lds_dwordx4 v[200:201], off
	v_lshl_add_u64 v[200:201], s[20:21], 0, v[172:173]
	s_mov_b32 m0, s28
	s_nop 0
	global_load_lds_dwordx4 v[200:201], off
	s_waitcnt vmcnt(8)
	s_waitcnt lgkmcnt(0)
	s_barrier
	s_setprio 1
	s_waitcnt lgkmcnt(0)
	v_mfma_scale_f32_16x16x128_f8f6f4 v[156:159], v[0:7], v[184:191], v[156:159], v202, v202 op_sel_hi:[0,0,0]
	v_mfma_scale_f32_16x16x128_f8f6f4 v[152:155], v[8:15], v[184:191], v[152:155], v202, v202 op_sel_hi:[0,0,0]
	v_mfma_scale_f32_16x16x128_f8f6f4 v[140:143], v[0:7], v[192:199], v[140:143], v202, v202 op_sel_hi:[0,0,0]
	v_mfma_scale_f32_16x16x128_f8f6f4 v[136:139], v[8:15], v[192:199], v[136:139], v202, v202 op_sel_hi:[0,0,0]
	v_mfma_scale_f32_16x16x128_f8f6f4 v[124:127], v[0:7], v[210:217], v[124:127], v202, v202 op_sel_hi:[0,0,0]
	v_mfma_scale_f32_16x16x128_f8f6f4 v[120:123], v[8:15], v[210:217], v[120:123], v202, v202 op_sel_hi:[0,0,0]
	v_mfma_scale_f32_16x16x128_f8f6f4 v[108:111], v[0:7], v[218:225], v[108:111], v202, v202 op_sel_hi:[0,0,0]
	v_mfma_scale_f32_16x16x128_f8f6f4 v[104:107], v[8:15], v[218:225], v[104:107], v202, v202 op_sel_hi:[0,0,0]
	v_mfma_scale_f32_16x16x128_f8f6f4 v[148:151], v[16:23], v[184:191], v[148:151], v202, v202 op_sel_hi:[0,0,0]
	v_mfma_scale_f32_16x16x128_f8f6f4 v[144:147], v[24:31], v[184:191], v[144:147], v202, v202 op_sel_hi:[0,0,0]
	v_mfma_scale_f32_16x16x128_f8f6f4 v[132:135], v[16:23], v[192:199], v[132:135], v202, v202 op_sel_hi:[0,0,0]
	v_mfma_scale_f32_16x16x128_f8f6f4 v[128:131], v[24:31], v[192:199], v[128:131], v202, v202 op_sel_hi:[0,0,0]
	v_mfma_scale_f32_16x16x128_f8f6f4 v[116:119], v[16:23], v[210:217], v[116:119], v202, v202 op_sel_hi:[0,0,0]
	v_mfma_scale_f32_16x16x128_f8f6f4 v[112:115], v[24:31], v[210:217], v[112:115], v202, v202 op_sel_hi:[0,0,0]
	v_mfma_scale_f32_16x16x128_f8f6f4 v[100:103], v[16:23], v[218:225], v[100:103], v202, v202 op_sel_hi:[0,0,0]
	v_mfma_scale_f32_16x16x128_f8f6f4 v[96:99], v[24:31], v[218:225], v[96:99], v202, v202 op_sel_hi:[0,0,0]
	s_setprio 0
	s_barrier
	s_add_i32 s20, s58, s24
	v_lshl_add_u64 v[160:161], v[160:161], 0, s[8:9]
	s_mov_b32 m0, s20
	ds_read_b128 v[184:187], v208 offset:49152
	ds_read_b128 v[188:191], v208 offset:50176
	ds_read_b128 v[192:195], v208 offset:51200
	ds_read_b128 v[196:199], v208 offset:52224
	ds_read_b128 v[210:213], v208 offset:53248
	ds_read_b128 v[214:217], v208 offset:54272
	ds_read_b128 v[218:221], v208 offset:55296
	ds_read_b128 v[222:225], v208 offset:56320
	global_load_lds_dwordx4 v[160:161], off
	s_add_i32 m0, s20, 0x2000
	s_add_u32 s18, s18, 0xb0080
	v_lshl_add_u64 v[160:161], v[162:163], 0, s[8:9]
	s_addc_u32 s19, s19, 0
	s_add_i32 s20, s59, s24
	global_load_lds_dwordx4 v[160:161], off
	v_lshl_add_u64 v[160:161], s[18:19], 0, v[170:171]
	s_mov_b32 m0, s20
	s_nop 0
	global_load_lds_dwordx4 v[160:161], off
	v_lshl_add_u64 v[160:161], s[18:19], 0, v[174:175]
	s_add_i32 m0, s20, 0x2000
	s_nop 0
	global_load_lds_dwordx4 v[160:161], off
	v_lshl_add_u64 v[160:161], v[164:165], 0, s[8:9]
	s_mov_b32 m0, s35
	s_nop 0
	global_load_lds_dwordx4 v[160:161], off
	v_lshl_add_u64 v[160:161], v[166:167], 0, s[8:9]
	s_mov_b32 m0, s36
	s_nop 0
	global_load_lds_dwordx4 v[160:161], off
	s_waitcnt vmcnt(8)
	s_waitcnt lgkmcnt(0)
	s_barrier
	s_setprio 1
	s_waitcnt lgkmcnt(0)
	v_mfma_scale_f32_16x16x128_f8f6f4 v[92:95], v[0:7], v[184:191], v[92:95], v202, v202 op_sel_hi:[0,0,0]
	v_mfma_scale_f32_16x16x128_f8f6f4 v[88:91], v[8:15], v[184:191], v[88:91], v202, v202 op_sel_hi:[0,0,0]
	v_mfma_scale_f32_16x16x128_f8f6f4 v[76:79], v[0:7], v[192:199], v[76:79], v202, v202 op_sel_hi:[0,0,0]
	v_mfma_scale_f32_16x16x128_f8f6f4 v[72:75], v[8:15], v[192:199], v[72:75], v202, v202 op_sel_hi:[0,0,0]
	v_mfma_scale_f32_16x16x128_f8f6f4 v[60:63], v[0:7], v[210:217], v[60:63], v202, v202 op_sel_hi:[0,0,0]
	v_mfma_scale_f32_16x16x128_f8f6f4 v[56:59], v[8:15], v[210:217], v[56:59], v202, v202 op_sel_hi:[0,0,0]
	v_mfma_scale_f32_16x16x128_f8f6f4 v[44:47], v[0:7], v[218:225], v[44:47], v202, v202 op_sel_hi:[0,0,0]
	v_mfma_scale_f32_16x16x128_f8f6f4 v[40:43], v[8:15], v[218:225], v[40:43], v202, v202 op_sel_hi:[0,0,0]
	v_mfma_scale_f32_16x16x128_f8f6f4 v[84:87], v[16:23], v[184:191], v[84:87], v202, v202 op_sel_hi:[0,0,0]
	v_mfma_scale_f32_16x16x128_f8f6f4 v[80:83], v[24:31], v[184:191], v[80:83], v202, v202 op_sel_hi:[0,0,0]
	v_mfma_scale_f32_16x16x128_f8f6f4 v[68:71], v[16:23], v[192:199], v[68:71], v202, v202 op_sel_hi:[0,0,0]
	v_mfma_scale_f32_16x16x128_f8f6f4 v[64:67], v[24:31], v[192:199], v[64:67], v202, v202 op_sel_hi:[0,0,0]
	v_mfma_scale_f32_16x16x128_f8f6f4 v[52:55], v[16:23], v[210:217], v[52:55], v202, v202 op_sel_hi:[0,0,0]
	v_mfma_scale_f32_16x16x128_f8f6f4 v[48:51], v[24:31], v[210:217], v[48:51], v202, v202 op_sel_hi:[0,0,0]
	v_mfma_scale_f32_16x16x128_f8f6f4 v[36:39], v[16:23], v[218:225], v[36:39], v202, v202 op_sel_hi:[0,0,0]
	v_mfma_scale_f32_16x16x128_f8f6f4 v[32:35], v[24:31], v[218:225], v[32:35], v202, v202 op_sel_hi:[0,0,0]
	s_setprio 0
	s_barrier
	s_add_i32 s57, s57, 2
	s_add_u32 s16, s16, 0x100
	s_addc_u32 s17, s17, 0
	s_add_u32 s55, s55, 0x100
	s_addc_u32 s56, s56, 0
	s_cmp_gt_u32 s57, 41
	s_cbranch_scc0 .LBB0_2516
	s_nop 15
	s_nop 15
	s_nop 15
	s_nop 15
	s_nop 15
	s_and_b64 vcc, exec, s[10:11]
	s_cbranch_vccz .LBB0_2519
	s_barrier
